# GEMM K-loops: per-phase s_setprio flips inverted (priority 1 in the load/ds_read segments, 0 in the MFMA clusters) - strategy 7.4 A/B
# baseline (speedup 1.0000x reference)
; #define STAGE(bufoff, gbase) STAGE_(bufoff, gbase, voffA)
; #define STAGEB(bufoff, gbase) STAGE_(bufoff, gbase, voffB)
; #define LDA(dst, b, h) do { _Pragma("unroll") for (int m = 0; m < 4; ++m) _Pragma("unroll") for (int k = 0; k < 2; ++k) dst[m][k] = *LDSP(const bf16x8, lds + SA(b, h) + aoff + m * 2048 + k * 1024); } while (0)
; #define LDB(dst, b, h) do { _Pragma("unroll") for (int n = 0; n < 2; ++n) _Pragma("unroll") for (int k = 0; k < 2; ++k) dst[n][k] = *LDSP(const bf16x8, lds + SB(b, h) + boff + n * 2048 + k * 1024); } while (0)
; #define MMA(ai, bj, AT, BT) do { __builtin_amdgcn_s_setprio(1); \
;     _Pragma("unroll") for (int m = 0; m < 4; ++m) _Pragma("unroll") for (int n = 0; n < 2; ++n) _Pragma("unroll") for (int k = 0; k < 2; ++k) \
;       acc[ai][bj][m][n] = __builtin_amdgcn_mfma_f32_16x16x32_bf16(BT[n][k], AT[m][k], acc[ai][bj][m][n], 0, 0, 0); \
;     __builtin_amdgcn_s_setprio(0); } while (0)
; #define WAIT_V(n) asm volatile("s_waitcnt vmcnt(" #n ")" ::: "memory")
; #define WAIT_L(n) asm volatile("s_waitcnt lgkmcnt(" #n ")" ::: "memory")
; #define BAR __builtin_amdgcn_s_barrier()
; #define SCHED __builtin_amdgcn_sched_barrier(0)
; #define WAIT_V(n) asm volatile("s_waitcnt vmcnt(" #n ")" ::: "memory")
; #define BAR do { __builtin_amdgcn_sched_barrier(0); __builtin_amdgcn_s_barrier(); asm volatile("" ::: "memory"); __builtin_amdgcn_sched_barrier(0); } while (0)
; template <bool SP2, bool ALIGN_EPI, bool DUAL, class Epi> DI void gemm_phase2(const bf16_t* A, const bf16_t* Bt, const bf16_t* A2, const bf16_t* Bt2, int M, int N, int K, const Epi& E, lds_t* lds) {
;     ...
;     for (int t = 0; t < nt; t += 2) {
;       const bool last = (t == nt - 2);
;       const char* a1 = cA + (size_t)(t + 1) * kstep;
;       const char* a2 = last ? nA : cA + (size_t)(t + 2) * kstep; const char* b2 = last ? nB : cB + (size_t)(t + 2) * kstep;
;       const char* a3 = a2 + kstep; const char* b3 = b2 + kstep;
;       if constexpr (SP2) {
;         LDB(B0, 0, 0); LDB(B1, 0, 1); SCHED; LDA(At, 0, 0); STAGE(SA(1, 1), a1 + hstep);
;         WAIT_V(8); WAIT_L(0); BAR; MMA(0, 0, At, B0); MMA(0, 1, At, B1); BAR; SCHED;
;         LDA(At, 0, 1); STAGEB(SB(0, 0), b2); STAGEB(SB(0, 1), b2 + bstep); STAGE(SA(0, 0), a2);
;         WAIT_V(8); WAIT_L(0); BAR; MMA(1, 0, At, B0); MMA(1, 1, At, B1); BAR; SCHED;
.LBB0_157:
	ds_read_b128 v[144:147], v161
	ds_read_b128 v[148:151], v161 offset:1024
	ds_read_b128 v[166:169], v161 offset:2048
	ds_read_b128 v[170:173], v161 offset:3072
	ds_read_b128 v[174:177], v162
	ds_read_b128 v[178:181], v162 offset:1024
	ds_read_b128 v[182:185], v162 offset:2048
	ds_read_b128 v[186:189], v162 offset:3072
	s_add_u32 s22, s8, 0xfffc0080
	s_addc_u32 s23, s9, -1
	s_cmp_eq_u32 s21, 12
	s_cselect_b32 s91, s0, s23
	s_cselect_b32 s90, s1, s22
	s_cselect_b32 s89, s11, s20
	s_cselect_b32 s88, s18, s19
	v_lshl_add_u64 v[152:153], s[8:9], 0, v[140:141]
	s_add_i32 m0, s3, 0xc000
	ds_read_b128 v[190:193], v163
	ds_read_b128 v[194:197], v163 offset:1024
	ds_read_b128 v[198:201], v163 offset:2048
	ds_read_b128 v[202:205], v163 offset:3072
	ds_read_b128 v[206:209], v163 offset:4096
	ds_read_b128 v[214:217], v163 offset:5120
	ds_read_b128 v[218:221], v163 offset:6144
	ds_read_b128 v[222:225], v163 offset:7168
	global_load_lds_dwordx4 v[152:153], off
	v_lshl_add_u64 v[152:153], s[8:9], 0, v[142:143]
	s_add_i32 m0, s3, 0xe000
	s_nop 0
	global_load_lds_dwordx4 v[152:153], off
	s_waitcnt vmcnt(8)
	s_waitcnt lgkmcnt(0)
	s_barrier
	s_setprio 0
	s_waitcnt lgkmcnt(0)
	v_mfma_f32_16x16x32_bf16 v[124:127], v[144:147], v[190:193], v[124:127]
	v_mfma_f32_16x16x32_bf16 v[120:123], v[166:169], v[190:193], v[120:123]
	v_mfma_f32_16x16x32_bf16 v[108:111], v[144:147], v[198:201], v[108:111]
	v_mfma_f32_16x16x32_bf16 v[104:107], v[166:169], v[198:201], v[104:107]
	v_mfma_f32_16x16x32_bf16 v[92:95], v[144:147], v[206:209], v[92:95]
	v_mfma_f32_16x16x32_bf16 v[88:91], v[166:169], v[206:209], v[88:91]
	v_mfma_f32_16x16x32_bf16 v[76:79], v[144:147], v[218:221], v[76:79]
	v_mfma_f32_16x16x32_bf16 v[72:75], v[166:169], v[218:221], v[72:75]
	v_mfma_f32_16x16x32_bf16 v[124:127], v[148:151], v[194:197], v[124:127]
	v_mfma_f32_16x16x32_bf16 v[120:123], v[170:173], v[194:197], v[120:123]
	v_mfma_f32_16x16x32_bf16 v[108:111], v[148:151], v[202:205], v[108:111]
	v_mfma_f32_16x16x32_bf16 v[104:107], v[170:173], v[202:205], v[104:107]
	v_mfma_f32_16x16x32_bf16 v[92:95], v[148:151], v[214:217], v[92:95]
	v_mfma_f32_16x16x32_bf16 v[88:91], v[170:173], v[214:217], v[88:91]
	v_mfma_f32_16x16x32_bf16 v[76:79], v[148:151], v[222:225], v[76:79]
	v_mfma_f32_16x16x32_bf16 v[72:75], v[170:173], v[222:225], v[72:75]
	s_setprio 1
	s_setprio 0
	v_mfma_f32_16x16x32_bf16 v[116:119], v[174:177], v[190:193], v[116:119]
	v_mfma_f32_16x16x32_bf16 v[112:115], v[182:185], v[190:193], v[112:115]
	v_mfma_f32_16x16x32_bf16 v[100:103], v[174:177], v[198:201], v[100:103]
	v_mfma_f32_16x16x32_bf16 v[96:99], v[182:185], v[198:201], v[96:99]
	v_mfma_f32_16x16x32_bf16 v[84:87], v[174:177], v[206:209], v[84:87]
	v_mfma_f32_16x16x32_bf16 v[80:83], v[182:185], v[206:209], v[80:83]
	v_mfma_f32_16x16x32_bf16 v[68:71], v[174:177], v[218:221], v[68:71]
	v_mfma_f32_16x16x32_bf16 v[64:67], v[182:185], v[218:221], v[64:67]
	v_mfma_f32_16x16x32_bf16 v[116:119], v[178:181], v[194:197], v[116:119]
	v_mfma_f32_16x16x32_bf16 v[112:115], v[186:189], v[194:197], v[112:115]
	v_mfma_f32_16x16x32_bf16 v[100:103], v[178:181], v[202:205], v[100:103]
	v_mfma_f32_16x16x32_bf16 v[96:99], v[186:189], v[202:205], v[96:99]
	v_mfma_f32_16x16x32_bf16 v[84:87], v[178:181], v[214:217], v[84:87]
	v_mfma_f32_16x16x32_bf16 v[80:83], v[186:189], v[214:217], v[80:83]
	v_mfma_f32_16x16x32_bf16 v[68:71], v[178:181], v[222:225], v[68:71]
	v_mfma_f32_16x16x32_bf16 v[64:67], v[186:189], v[222:225], v[64:67]
	s_setprio 1
	s_barrier
	s_add_i32 s22, s12, s2
	v_lshl_add_u64 v[152:153], s[88:89], 0, v[130:131]
	s_mov_b32 m0, s22
	ds_read_b128 v[190:193], v163 offset:16384
	ds_read_b128 v[194:197], v163 offset:17408
	ds_read_b128 v[198:201], v163 offset:18432
	ds_read_b128 v[202:205], v163 offset:19456
	ds_read_b128 v[206:209], v163 offset:20480
	ds_read_b128 v[214:217], v163 offset:21504
	ds_read_b128 v[218:221], v163 offset:22528
	ds_read_b128 v[222:225], v163 offset:23552
	global_load_lds_dwordx4 v[152:153], off
	s_add_i32 m0, s22, 0x2000
	s_add_u32 s22, s88, 0x10000
	v_lshl_add_u64 v[210:211], s[88:89], 0, v[134:135]
	s_addc_u32 s23, s89, 0
	s_add_i32 s33, s13, s2
	global_load_lds_dwordx4 v[210:211], off
	v_lshl_add_u64 v[226:227], s[22:23], 0, v[130:131]
	s_mov_b32 m0, s33
	v_lshl_add_u64 v[228:229], s[90:91], 0, v[132:133]
	global_load_lds_dwordx4 v[226:227], off
	v_lshl_add_u64 v[226:227], s[22:23], 0, v[134:135]
	s_add_i32 m0, s33, 0x2000
	s_nop 0
	global_load_lds_dwordx4 v[226:227], off
	v_lshl_add_u64 v[226:227], s[90:91], 0, v[128:129]
	s_mov_b32 m0, s3
	s_nop 0
	global_load_lds_dwordx4 v[226:227], off
	s_mov_b32 m0, s14
	s_nop 0
	global_load_lds_dwordx4 v[228:229], off
	s_waitcnt vmcnt(8)
	s_waitcnt lgkmcnt(0)
	s_barrier
; #define STAGE(bufoff, gbase) STAGE_(bufoff, gbase, voffA)
; #define LDA(dst, b, h) do { _Pragma("unroll") for (int m = 0; m < 4; ++m) _Pragma("unroll") for (int k = 0; k < 2; ++k) dst[m][k] = *LDSP(const bf16x8, lds + SA(b, h) + aoff + m * 2048 + k * 1024); } while (0)
; #define LDB(dst, b, h) do { _Pragma("unroll") for (int n = 0; n < 2; ++n) _Pragma("unroll") for (int k = 0; k < 2; ++k) dst[n][k] = *LDSP(const bf16x8, lds + SB(b, h) + boff + n * 2048 + k * 1024); } while (0)
; #define MMA(ai, bj, AT, BT) do { __builtin_amdgcn_s_setprio(1); \
;     _Pragma("unroll") for (int m = 0; m < 4; ++m) _Pragma("unroll") for (int n = 0; n < 2; ++n) _Pragma("unroll") for (int k = 0; k < 2; ++k) \
;       acc[ai][bj][m][n] = __builtin_amdgcn_mfma_f32_16x16x32_bf16(BT[n][k], AT[m][k], acc[ai][bj][m][n], 0, 0, 0); \
;     __builtin_amdgcn_s_setprio(0); } while (0)
; #define WAIT_V(n) asm volatile("s_waitcnt vmcnt(" #n ")" ::: "memory")
; #define WAIT_L(n) asm volatile("s_waitcnt lgkmcnt(" #n ")" ::: "memory")
; #define BAR __builtin_amdgcn_s_barrier()
; #define SCHED __builtin_amdgcn_sched_barrier(0)
; #define WAIT_V(n) asm volatile("s_waitcnt vmcnt(" #n ")" ::: "memory")
; #define BAR do { __builtin_amdgcn_sched_barrier(0); __builtin_amdgcn_s_barrier(); asm volatile("" ::: "memory"); __builtin_amdgcn_sched_barrier(0); } while (0)
; template <bool SP2, bool ALIGN_EPI, bool DUAL, class Epi> DI void gemm_phase2(const bf16_t* A, const bf16_t* Bt, const bf16_t* A2, const bf16_t* Bt2, int M, int N, int K, const Epi& E, lds_t* lds) {
;     ...
;         WAIT_V(8); WAIT_L(0); BAR; MMA(1, 0, At, B0); MMA(1, 1, At, B1); BAR; SCHED;
;         LDB(B0, 1, 0); LDB(B1, 1, 1); SCHED; LDA(At, 1, 0); STAGE(SA(0, 1), a2 + hstep);
;         WAIT_V(8); WAIT_L(0); BAR; MMA(0, 0, At, B0); MMA(0, 1, At, B1); BAR; SCHED;
	s_setprio 0
	s_waitcnt lgkmcnt(0)
	v_mfma_f32_16x16x32_bf16 v[60:63], v[144:147], v[190:193], v[60:63]
	v_mfma_f32_16x16x32_bf16 v[56:59], v[166:169], v[190:193], v[56:59]
	v_mfma_f32_16x16x32_bf16 v[44:47], v[144:147], v[198:201], v[44:47]
	v_mfma_f32_16x16x32_bf16 v[40:43], v[166:169], v[198:201], v[40:43]
	v_mfma_f32_16x16x32_bf16 v[28:31], v[144:147], v[206:209], v[28:31]
	v_mfma_f32_16x16x32_bf16 v[24:27], v[166:169], v[206:209], v[24:27]
	v_mfma_f32_16x16x32_bf16 v[12:15], v[144:147], v[218:221], v[12:15]
	v_mfma_f32_16x16x32_bf16 v[8:11], v[166:169], v[218:221], v[8:11]
	v_mfma_f32_16x16x32_bf16 v[60:63], v[148:151], v[194:197], v[60:63]
	v_mfma_f32_16x16x32_bf16 v[56:59], v[170:173], v[194:197], v[56:59]
	v_mfma_f32_16x16x32_bf16 v[44:47], v[148:151], v[202:205], v[44:47]
	v_mfma_f32_16x16x32_bf16 v[40:43], v[170:173], v[202:205], v[40:43]
	v_mfma_f32_16x16x32_bf16 v[28:31], v[148:151], v[214:217], v[28:31]
	v_mfma_f32_16x16x32_bf16 v[24:27], v[170:173], v[214:217], v[24:27]
	v_mfma_f32_16x16x32_bf16 v[12:15], v[148:151], v[222:225], v[12:15]
	v_mfma_f32_16x16x32_bf16 v[8:11], v[170:173], v[222:225], v[8:11]
	s_setprio 1
	s_setprio 0
	v_mfma_f32_16x16x32_bf16 v[52:55], v[174:177], v[190:193], v[52:55]
	v_mfma_f32_16x16x32_bf16 v[48:51], v[182:185], v[190:193], v[48:51]
	v_mfma_f32_16x16x32_bf16 v[36:39], v[174:177], v[198:201], v[36:39]
	v_mfma_f32_16x16x32_bf16 v[32:35], v[182:185], v[198:201], v[32:35]
	v_mfma_f32_16x16x32_bf16 v[20:23], v[174:177], v[206:209], v[20:23]
	v_mfma_f32_16x16x32_bf16 v[16:19], v[182:185], v[206:209], v[16:19]
	v_mfma_f32_16x16x32_bf16 v[4:7], v[174:177], v[218:221], v[4:7]
	v_mfma_f32_16x16x32_bf16 v[0:3], v[182:185], v[218:221], v[0:3]
	v_mfma_f32_16x16x32_bf16 v[52:55], v[178:181], v[194:197], v[52:55]
	v_mfma_f32_16x16x32_bf16 v[48:51], v[186:189], v[194:197], v[48:51]
	v_mfma_f32_16x16x32_bf16 v[36:39], v[178:181], v[202:205], v[36:39]
	v_mfma_f32_16x16x32_bf16 v[32:35], v[186:189], v[202:205], v[32:35]
	v_mfma_f32_16x16x32_bf16 v[20:23], v[178:181], v[214:217], v[20:23]
	v_mfma_f32_16x16x32_bf16 v[16:19], v[186:189], v[214:217], v[16:19]
	v_mfma_f32_16x16x32_bf16 v[4:7], v[178:181], v[222:225], v[4:7]
	v_mfma_f32_16x16x32_bf16 v[0:3], v[186:189], v[222:225], v[0:3]
	s_setprio 1
	s_barrier
	s_add_i32 s33, 0, 0x18000
	s_add_i32 s34, 0, 0x1c000
	v_add_u32_e32 v170, s33, v157
	v_add_u32_e32 v186, s34, v157
	ds_read_b128 v[144:147], v170
	ds_read_b128 v[148:151], v170 offset:1024
	ds_read_b128 v[166:169], v170 offset:2048
	ds_read_b128 v[170:173], v170 offset:3072
	ds_read_b128 v[174:177], v186
	ds_read_b128 v[178:181], v186 offset:1024
	ds_read_b128 v[182:185], v186 offset:2048
	ds_read_b128 v[186:189], v186 offset:3072
	s_add_u32 s22, s90, 0x40000
	s_addc_u32 s23, s91, 0
	s_mov_b32 m0, s15
	v_lshl_add_u64 v[230:231], s[22:23], 0, v[128:129]
	ds_read_b128 v[190:193], v163 offset:32768
	ds_read_b128 v[194:197], v163 offset:33792
	ds_read_b128 v[198:201], v163 offset:34816
	ds_read_b128 v[202:205], v163 offset:35840
	ds_read_b128 v[206:209], v163 offset:36864
	ds_read_b128 v[214:217], v163 offset:37888
	ds_read_b128 v[218:221], v163 offset:38912
	ds_read_b128 v[222:225], v163 offset:39936
	global_load_lds_dwordx4 v[230:231], off
	v_lshl_add_u64 v[230:231], s[22:23], 0, v[132:133]
	s_mov_b32 m0, s35
	s_nop 0
	global_load_lds_dwordx4 v[230:231], off
	s_waitcnt vmcnt(8)
	s_waitcnt lgkmcnt(0)
	s_barrier
	s_setprio 0
	s_waitcnt lgkmcnt(0)
	v_mfma_f32_16x16x32_bf16 v[124:127], v[144:147], v[190:193], v[124:127]
	v_mfma_f32_16x16x32_bf16 v[120:123], v[166:169], v[190:193], v[120:123]
	v_mfma_f32_16x16x32_bf16 v[108:111], v[144:147], v[198:201], v[108:111]
	v_mfma_f32_16x16x32_bf16 v[104:107], v[166:169], v[198:201], v[104:107]
	v_mfma_f32_16x16x32_bf16 v[92:95], v[144:147], v[206:209], v[92:95]
	v_mfma_f32_16x16x32_bf16 v[88:91], v[166:169], v[206:209], v[88:91]
	v_mfma_f32_16x16x32_bf16 v[76:79], v[144:147], v[218:221], v[76:79]
	v_mfma_f32_16x16x32_bf16 v[72:75], v[166:169], v[218:221], v[72:75]
	v_mfma_f32_16x16x32_bf16 v[124:127], v[148:151], v[194:197], v[124:127]
	v_mfma_f32_16x16x32_bf16 v[120:123], v[170:173], v[194:197], v[120:123]
	v_mfma_f32_16x16x32_bf16 v[108:111], v[148:151], v[202:205], v[108:111]
	v_mfma_f32_16x16x32_bf16 v[104:107], v[170:173], v[202:205], v[104:107]
	v_mfma_f32_16x16x32_bf16 v[92:95], v[148:151], v[214:217], v[92:95]
	v_mfma_f32_16x16x32_bf16 v[88:91], v[170:173], v[214:217], v[88:91]
	v_mfma_f32_16x16x32_bf16 v[76:79], v[148:151], v[222:225], v[76:79]
	v_mfma_f32_16x16x32_bf16 v[72:75], v[170:173], v[222:225], v[72:75]
	s_setprio 1
	s_setprio 0
	v_mfma_f32_16x16x32_bf16 v[116:119], v[174:177], v[190:193], v[116:119]
	v_mfma_f32_16x16x32_bf16 v[112:115], v[182:185], v[190:193], v[112:115]
	v_mfma_f32_16x16x32_bf16 v[100:103], v[174:177], v[198:201], v[100:103]
	v_mfma_f32_16x16x32_bf16 v[96:99], v[182:185], v[198:201], v[96:99]
	v_mfma_f32_16x16x32_bf16 v[84:87], v[174:177], v[206:209], v[84:87]
	v_mfma_f32_16x16x32_bf16 v[80:83], v[182:185], v[206:209], v[80:83]
	v_mfma_f32_16x16x32_bf16 v[68:71], v[174:177], v[218:221], v[68:71]
	v_mfma_f32_16x16x32_bf16 v[64:67], v[182:185], v[218:221], v[64:67]
	v_mfma_f32_16x16x32_bf16 v[116:119], v[178:181], v[194:197], v[116:119]
	v_mfma_f32_16x16x32_bf16 v[112:115], v[186:189], v[194:197], v[112:115]
	v_mfma_f32_16x16x32_bf16 v[100:103], v[178:181], v[202:205], v[100:103]
	v_mfma_f32_16x16x32_bf16 v[96:99], v[186:189], v[202:205], v[96:99]
	v_mfma_f32_16x16x32_bf16 v[84:87], v[178:181], v[214:217], v[84:87]
	v_mfma_f32_16x16x32_bf16 v[80:83], v[186:189], v[214:217], v[80:83]
	v_mfma_f32_16x16x32_bf16 v[68:71], v[178:181], v[222:225], v[68:71]
	v_mfma_f32_16x16x32_bf16 v[64:67], v[186:189], v[222:225], v[64:67]
	s_setprio 1
	s_barrier
; #define STAGE(bufoff, gbase) STAGE_(bufoff, gbase, voffA)
; #define STAGEB(bufoff, gbase) STAGE_(bufoff, gbase, voffB)
; #define LDA(dst, b, h) do { _Pragma("unroll") for (int m = 0; m < 4; ++m) _Pragma("unroll") for (int k = 0; k < 2; ++k) dst[m][k] = *LDSP(const bf16x8, lds + SA(b, h) + aoff + m * 2048 + k * 1024); } while (0)
; #define MMA(ai, bj, AT, BT) do { __builtin_amdgcn_s_setprio(1); \
;     _Pragma("unroll") for (int m = 0; m < 4; ++m) _Pragma("unroll") for (int n = 0; n < 2; ++n) _Pragma("unroll") for (int k = 0; k < 2; ++k) \
;       acc[ai][bj][m][n] = __builtin_amdgcn_mfma_f32_16x16x32_bf16(BT[n][k], AT[m][k], acc[ai][bj][m][n], 0, 0, 0); \
;     __builtin_amdgcn_s_setprio(0); } while (0)
; #define WAIT_V(n) asm volatile("s_waitcnt vmcnt(" #n ")" ::: "memory")
; #define WAIT_L(n) asm volatile("s_waitcnt lgkmcnt(" #n ")" ::: "memory")
; #define BAR __builtin_amdgcn_s_barrier()
; #define SCHED __builtin_amdgcn_sched_barrier(0)
; #define WAIT_V(n) asm volatile("s_waitcnt vmcnt(" #n ")" ::: "memory")
; #define BAR do { __builtin_amdgcn_sched_barrier(0); __builtin_amdgcn_s_barrier(); asm volatile("" ::: "memory"); __builtin_amdgcn_sched_barrier(0); } while (0)
; template <bool SP2, bool ALIGN_EPI, bool DUAL, class Epi> DI void gemm_phase2(const bf16_t* A, const bf16_t* Bt, const bf16_t* A2, const bf16_t* Bt2, int M, int N, int K, const Epi& E, lds_t* lds) {
;     ...
;     for (int t = 0; t < nt; t += 2) {
;       const bool last = (t == nt - 2);
;       const char* a1 = cA + (size_t)(t + 1) * kstep;
;       const char* a2 = last ? nA : cA + (size_t)(t + 2) * kstep; const char* b2 = last ? nB : cB + (size_t)(t + 2) * kstep;
;       const char* a3 = a2 + kstep; const char* b3 = b2 + kstep;
;     ...
;         LDA(At, 1, 1); STAGEB(SB(1, 0), b3); STAGEB(SB(1, 1), b3 + bstep); STAGE(SA(1, 0), a3);
;         WAIT_V(8); WAIT_L(0); BAR; MMA(1, 0, At, B0); MMA(1, 1, At, B1); BAR; SCHED;
	s_add_i32 s22, s33, s2
	v_lshl_add_u64 v[152:153], v[152:153], 0, s[58:59]
	s_mov_b32 m0, s22
	ds_read_b128 v[190:193], v163 offset:49152
	ds_read_b128 v[194:197], v163 offset:50176
	ds_read_b128 v[198:201], v163 offset:51200
	ds_read_b128 v[202:205], v163 offset:52224
	ds_read_b128 v[206:209], v163 offset:53248
	ds_read_b128 v[214:217], v163 offset:54272
	ds_read_b128 v[218:221], v163 offset:55296
	ds_read_b128 v[222:225], v163 offset:56320
	global_load_lds_dwordx4 v[152:153], off
	s_add_i32 m0, s22, 0x2000
	s_add_u32 s22, s88, 0x10080
	v_lshl_add_u64 v[152:153], v[210:211], 0, s[58:59]
	s_addc_u32 s23, s89, 0
	s_add_i32 s33, s34, s2
	global_load_lds_dwordx4 v[152:153], off
	v_lshl_add_u64 v[152:153], s[22:23], 0, v[130:131]
	s_mov_b32 m0, s33
	s_nop 0
	global_load_lds_dwordx4 v[152:153], off
	v_lshl_add_u64 v[152:153], s[22:23], 0, v[134:135]
	s_add_i32 m0, s33, 0x2000
	s_nop 0
	global_load_lds_dwordx4 v[152:153], off
	v_lshl_add_u64 v[152:153], v[226:227], 0, s[58:59]
	s_mov_b32 m0, s52
	s_nop 0
	global_load_lds_dwordx4 v[152:153], off
	v_lshl_add_u64 v[152:153], v[228:229], 0, s[58:59]
	s_mov_b32 m0, s53
	s_nop 0
	global_load_lds_dwordx4 v[152:153], off
	s_waitcnt vmcnt(8)
	s_waitcnt lgkmcnt(0)
	s_barrier
	s_setprio 0
	s_waitcnt lgkmcnt(0)
	v_mfma_f32_16x16x32_bf16 v[60:63], v[144:147], v[190:193], v[60:63]
	v_mfma_f32_16x16x32_bf16 v[56:59], v[166:169], v[190:193], v[56:59]
	v_mfma_f32_16x16x32_bf16 v[44:47], v[144:147], v[198:201], v[44:47]
	v_mfma_f32_16x16x32_bf16 v[40:43], v[166:169], v[198:201], v[40:43]
	v_mfma_f32_16x16x32_bf16 v[28:31], v[144:147], v[206:209], v[28:31]
	v_mfma_f32_16x16x32_bf16 v[24:27], v[166:169], v[206:209], v[24:27]
	v_mfma_f32_16x16x32_bf16 v[12:15], v[144:147], v[218:221], v[12:15]
	v_mfma_f32_16x16x32_bf16 v[8:11], v[166:169], v[218:221], v[8:11]
	v_mfma_f32_16x16x32_bf16 v[60:63], v[148:151], v[194:197], v[60:63]
	v_mfma_f32_16x16x32_bf16 v[56:59], v[170:173], v[194:197], v[56:59]
	v_mfma_f32_16x16x32_bf16 v[44:47], v[148:151], v[202:205], v[44:47]
	v_mfma_f32_16x16x32_bf16 v[40:43], v[170:173], v[202:205], v[40:43]
	v_mfma_f32_16x16x32_bf16 v[28:31], v[148:151], v[214:217], v[28:31]
	v_mfma_f32_16x16x32_bf16 v[24:27], v[170:173], v[214:217], v[24:27]
	v_mfma_f32_16x16x32_bf16 v[12:15], v[148:151], v[222:225], v[12:15]
	v_mfma_f32_16x16x32_bf16 v[8:11], v[170:173], v[222:225], v[8:11]
	s_setprio 1
	s_setprio 0
	v_mfma_f32_16x16x32_bf16 v[52:55], v[174:177], v[190:193], v[52:55]
	v_mfma_f32_16x16x32_bf16 v[48:51], v[182:185], v[190:193], v[48:51]
	v_mfma_f32_16x16x32_bf16 v[36:39], v[174:177], v[198:201], v[36:39]
	v_mfma_f32_16x16x32_bf16 v[32:35], v[182:185], v[198:201], v[32:35]
	v_mfma_f32_16x16x32_bf16 v[20:23], v[174:177], v[206:209], v[20:23]
	v_mfma_f32_16x16x32_bf16 v[16:19], v[182:185], v[206:209], v[16:19]
	v_mfma_f32_16x16x32_bf16 v[4:7], v[174:177], v[218:221], v[4:7]
	v_mfma_f32_16x16x32_bf16 v[0:3], v[182:185], v[218:221], v[0:3]
	v_mfma_f32_16x16x32_bf16 v[52:55], v[178:181], v[194:197], v[52:55]
	v_mfma_f32_16x16x32_bf16 v[48:51], v[186:189], v[194:197], v[48:51]
	v_mfma_f32_16x16x32_bf16 v[36:39], v[178:181], v[202:205], v[36:39]
	v_mfma_f32_16x16x32_bf16 v[32:35], v[186:189], v[202:205], v[32:35]
	v_mfma_f32_16x16x32_bf16 v[20:23], v[178:181], v[214:217], v[20:23]
	v_mfma_f32_16x16x32_bf16 v[16:19], v[186:189], v[214:217], v[16:19]
	v_mfma_f32_16x16x32_bf16 v[4:7], v[178:181], v[222:225], v[4:7]
	v_mfma_f32_16x16x32_bf16 v[0:3], v[186:189], v[222:225], v[0:3]
	s_setprio 1
	s_barrier
	s_add_i32 s21, s21, 2
	s_add_u32 s8, s8, 0x100
	s_addc_u32 s9, s9, 0
	s_add_u32 s19, s19, 0x100
	s_addc_u32 s20, s20, 0
	s_cmp_gt_u32 s21, 13
	s_cbranch_scc0 .LBB0_157
	s_and_b64 vcc, exec, s[60:61]
	s_cbranch_vccz .LBB0_160
	s_barrier

; #define STAGE(bufoff, gbase) STAGE_(bufoff, gbase, voffA)
; #define STAGEB(bufoff, gbase) STAGE_(bufoff, gbase, voffB)
; #define LDA(dst, b, h) do { _Pragma("unroll") for (int m = 0; m < 4; ++m) _Pragma("unroll") for (int k = 0; k < 2; ++k) dst[m][k] = *LDSP(const bf16x8, lds + SA(b, h) + aoff + m * 2048 + k * 1024); } while (0)
; #define LDB(dst, b, h) do { _Pragma("unroll") for (int n = 0; n < 2; ++n) _Pragma("unroll") for (int k = 0; k < 2; ++k) dst[n][k] = *LDSP(const bf16x8, lds + SB(b, h) + boff + n * 2048 + k * 1024); } while (0)
; #define MMA(ai, bj, AT, BT) do { __builtin_amdgcn_s_setprio(1); \
;     _Pragma("unroll") for (int m = 0; m < 4; ++m) _Pragma("unroll") for (int n = 0; n < 2; ++n) _Pragma("unroll") for (int k = 0; k < 2; ++k) \
;       acc[ai][bj][m][n] = __builtin_amdgcn_mfma_f32_16x16x32_bf16(BT[n][k], AT[m][k], acc[ai][bj][m][n], 0, 0, 0); \
;     __builtin_amdgcn_s_setprio(0); } while (0)
; #define WAIT_V(n) asm volatile("s_waitcnt vmcnt(" #n ")" ::: "memory")
; #define WAIT_L(n) asm volatile("s_waitcnt lgkmcnt(" #n ")" ::: "memory")
; #define BAR __builtin_amdgcn_s_barrier()
; #define SCHED __builtin_amdgcn_sched_barrier(0)
; #define WAIT_V(n) asm volatile("s_waitcnt vmcnt(" #n ")" ::: "memory")
; #define BAR do { __builtin_amdgcn_sched_barrier(0); __builtin_amdgcn_s_barrier(); asm volatile("" ::: "memory"); __builtin_amdgcn_sched_barrier(0); } while (0)
; template <bool SP2, bool ALIGN_EPI, bool DUAL, class Epi> DI void gemm_phase2(const bf16_t* A, const bf16_t* Bt, const bf16_t* A2, const bf16_t* Bt2, int M, int N, int K, const Epi& E, lds_t* lds) {
;     ...
;     for (int t = 0; t < nt; t += 2) {
;       const bool last = (t == nt - 2);
;       const char* a1 = cA + (size_t)(t + 1) * kstep;
;       const char* a2 = last ? nA : cA + (size_t)(t + 2) * kstep; const char* b2 = last ? nB : cB + (size_t)(t + 2) * kstep;
;       const char* a3 = a2 + kstep; const char* b3 = b2 + kstep;
;       if constexpr (SP2) {
;         LDB(B0, 0, 0); LDB(B1, 0, 1); SCHED; LDA(At, 0, 0); STAGE(SA(1, 1), a1 + hstep);
;         WAIT_V(8); WAIT_L(0); BAR; MMA(0, 0, At, B0); MMA(0, 1, At, B1); BAR; SCHED;
;         LDA(At, 0, 1); STAGEB(SB(0, 0), b2); STAGEB(SB(0, 1), b2 + bstep); STAGE(SA(0, 0), a2);
;         WAIT_V(8); WAIT_L(0); BAR; MMA(1, 0, At, B0); MMA(1, 1, At, B1); BAR; SCHED;
.LBB0_341:
	ds_read_b128 v[148:151], v145
	ds_read_b128 v[156:159], v145 offset:1024
	ds_read_b128 v[160:163], v145 offset:2048
	ds_read_b128 v[164:167], v145 offset:3072
	ds_read_b128 v[168:171], v146
	ds_read_b128 v[172:175], v146 offset:1024
	ds_read_b128 v[176:179], v146 offset:2048
	ds_read_b128 v[180:183], v146 offset:3072
	s_add_u32 s52, s68, 0xfffc0080
	s_addc_u32 s53, s69, -1
	s_cmp_eq_u32 s35, 12
	s_cselect_b32 s89, s0, s53
	s_cselect_b32 s88, s1, s52
	s_cselect_b32 s87, s11, s34
	s_cselect_b32 s86, s23, s33
	v_lshl_add_u64 v[152:153], s[68:69], 0, v[136:137]
	s_add_i32 m0, s3, 0xc000
	ds_read_b128 v[184:187], v147
	ds_read_b128 v[188:191], v147 offset:1024
	ds_read_b128 v[192:195], v147 offset:2048
	ds_read_b128 v[196:199], v147 offset:3072
	ds_read_b128 v[200:203], v147 offset:4096
	ds_read_b128 v[204:207], v147 offset:5120
	ds_read_b128 v[208:211], v147 offset:6144
	ds_read_b128 v[214:217], v147 offset:7168
	global_load_lds_dwordx4 v[152:153], off
	v_lshl_add_u64 v[152:153], s[68:69], 0, v[138:139]
	s_add_i32 m0, s3, 0xe000
	s_nop 0
	global_load_lds_dwordx4 v[152:153], off
	s_waitcnt vmcnt(8)
	s_waitcnt lgkmcnt(0)
	s_barrier
	s_setprio 0
	s_waitcnt lgkmcnt(0)
	v_mfma_f32_16x16x32_bf16 v[124:127], v[148:151], v[184:187], v[124:127]
	v_mfma_f32_16x16x32_bf16 v[120:123], v[160:163], v[184:187], v[120:123]
	v_mfma_f32_16x16x32_bf16 v[108:111], v[148:151], v[192:195], v[108:111]
	v_mfma_f32_16x16x32_bf16 v[104:107], v[160:163], v[192:195], v[104:107]
	v_mfma_f32_16x16x32_bf16 v[92:95], v[148:151], v[200:203], v[92:95]
	v_mfma_f32_16x16x32_bf16 v[88:91], v[160:163], v[200:203], v[88:91]
	v_mfma_f32_16x16x32_bf16 v[76:79], v[148:151], v[208:211], v[76:79]
	v_mfma_f32_16x16x32_bf16 v[72:75], v[160:163], v[208:211], v[72:75]
	v_mfma_f32_16x16x32_bf16 v[124:127], v[156:159], v[188:191], v[124:127]
	v_mfma_f32_16x16x32_bf16 v[120:123], v[164:167], v[188:191], v[120:123]
	v_mfma_f32_16x16x32_bf16 v[108:111], v[156:159], v[196:199], v[108:111]
	v_mfma_f32_16x16x32_bf16 v[104:107], v[164:167], v[196:199], v[104:107]
	v_mfma_f32_16x16x32_bf16 v[92:95], v[156:159], v[204:207], v[92:95]
	v_mfma_f32_16x16x32_bf16 v[88:91], v[164:167], v[204:207], v[88:91]
	v_mfma_f32_16x16x32_bf16 v[76:79], v[156:159], v[214:217], v[76:79]
	v_mfma_f32_16x16x32_bf16 v[72:75], v[164:167], v[214:217], v[72:75]
	s_setprio 1
	s_setprio 0
	v_mfma_f32_16x16x32_bf16 v[116:119], v[168:171], v[184:187], v[116:119]
	v_mfma_f32_16x16x32_bf16 v[112:115], v[176:179], v[184:187], v[112:115]
	v_mfma_f32_16x16x32_bf16 v[100:103], v[168:171], v[192:195], v[100:103]
	v_mfma_f32_16x16x32_bf16 v[96:99], v[176:179], v[192:195], v[96:99]
	v_mfma_f32_16x16x32_bf16 v[84:87], v[168:171], v[200:203], v[84:87]
	v_mfma_f32_16x16x32_bf16 v[80:83], v[176:179], v[200:203], v[80:83]
	v_mfma_f32_16x16x32_bf16 v[68:71], v[168:171], v[208:211], v[68:71]
	v_mfma_f32_16x16x32_bf16 v[64:67], v[176:179], v[208:211], v[64:67]
	v_mfma_f32_16x16x32_bf16 v[116:119], v[172:175], v[188:191], v[116:119]
	v_mfma_f32_16x16x32_bf16 v[112:115], v[180:183], v[188:191], v[112:115]
	v_mfma_f32_16x16x32_bf16 v[100:103], v[172:175], v[196:199], v[100:103]
	v_mfma_f32_16x16x32_bf16 v[96:99], v[180:183], v[196:199], v[96:99]
	v_mfma_f32_16x16x32_bf16 v[84:87], v[172:175], v[204:207], v[84:87]
	v_mfma_f32_16x16x32_bf16 v[80:83], v[180:183], v[204:207], v[80:83]
	v_mfma_f32_16x16x32_bf16 v[68:71], v[172:175], v[214:217], v[68:71]
	v_mfma_f32_16x16x32_bf16 v[64:67], v[180:183], v[214:217], v[64:67]
	s_setprio 1
	s_barrier
	s_add_i32 s52, s19, s2
	v_lshl_add_u64 v[152:153], s[86:87], 0, v[130:131]
	s_mov_b32 m0, s52
	ds_read_b128 v[184:187], v147 offset:16384
	ds_read_b128 v[188:191], v147 offset:17408
	ds_read_b128 v[192:195], v147 offset:18432
	ds_read_b128 v[196:199], v147 offset:19456
	ds_read_b128 v[200:203], v147 offset:20480
	ds_read_b128 v[204:207], v147 offset:21504
	ds_read_b128 v[208:211], v147 offset:22528
	ds_read_b128 v[214:217], v147 offset:23552
	global_load_lds_dwordx4 v[152:153], off
	s_add_i32 m0, s52, 0x2000
	s_add_u32 s52, s86, 0x10000
	v_lshl_add_u64 v[218:219], s[86:87], 0, v[134:135]
	s_addc_u32 s53, s87, 0
	s_add_i32 s61, s20, s2
	global_load_lds_dwordx4 v[218:219], off
	v_lshl_add_u64 v[220:221], s[52:53], 0, v[130:131]
	s_mov_b32 m0, s61
	v_lshl_add_u64 v[222:223], s[88:89], 0, v[132:133]
	global_load_lds_dwordx4 v[220:221], off
	v_lshl_add_u64 v[220:221], s[52:53], 0, v[134:135]
	s_add_i32 m0, s61, 0x2000
	s_nop 0
	global_load_lds_dwordx4 v[220:221], off
	v_lshl_add_u64 v[220:221], s[88:89], 0, v[128:129]
	s_mov_b32 m0, s3
	s_nop 0
	global_load_lds_dwordx4 v[220:221], off
	s_mov_b32 m0, s12
	s_nop 0
	global_load_lds_dwordx4 v[222:223], off
	s_waitcnt vmcnt(8)
	s_waitcnt lgkmcnt(0)
	s_barrier
; #define STAGE(bufoff, gbase) STAGE_(bufoff, gbase, voffA)
; #define LDA(dst, b, h) do { _Pragma("unroll") for (int m = 0; m < 4; ++m) _Pragma("unroll") for (int k = 0; k < 2; ++k) dst[m][k] = *LDSP(const bf16x8, lds + SA(b, h) + aoff + m * 2048 + k * 1024); } while (0)
; #define LDB(dst, b, h) do { _Pragma("unroll") for (int n = 0; n < 2; ++n) _Pragma("unroll") for (int k = 0; k < 2; ++k) dst[n][k] = *LDSP(const bf16x8, lds + SB(b, h) + boff + n * 2048 + k * 1024); } while (0)
; #define MMA(ai, bj, AT, BT) do { __builtin_amdgcn_s_setprio(1); \
;     _Pragma("unroll") for (int m = 0; m < 4; ++m) _Pragma("unroll") for (int n = 0; n < 2; ++n) _Pragma("unroll") for (int k = 0; k < 2; ++k) \
;       acc[ai][bj][m][n] = __builtin_amdgcn_mfma_f32_16x16x32_bf16(BT[n][k], AT[m][k], acc[ai][bj][m][n], 0, 0, 0); \
;     __builtin_amdgcn_s_setprio(0); } while (0)
; #define WAIT_V(n) asm volatile("s_waitcnt vmcnt(" #n ")" ::: "memory")
; #define WAIT_L(n) asm volatile("s_waitcnt lgkmcnt(" #n ")" ::: "memory")
; #define BAR __builtin_amdgcn_s_barrier()
; #define SCHED __builtin_amdgcn_sched_barrier(0)
; #define WAIT_V(n) asm volatile("s_waitcnt vmcnt(" #n ")" ::: "memory")
; #define BAR do { __builtin_amdgcn_sched_barrier(0); __builtin_amdgcn_s_barrier(); asm volatile("" ::: "memory"); __builtin_amdgcn_sched_barrier(0); } while (0)
; template <bool SP2, bool ALIGN_EPI, bool DUAL, class Epi> DI void gemm_phase2(const bf16_t* A, const bf16_t* Bt, const bf16_t* A2, const bf16_t* Bt2, int M, int N, int K, const Epi& E, lds_t* lds) {
;     ...
;         WAIT_V(8); WAIT_L(0); BAR; MMA(1, 0, At, B0); MMA(1, 1, At, B1); BAR; SCHED;
;         LDB(B0, 1, 0); LDB(B1, 1, 1); SCHED; LDA(At, 1, 0); STAGE(SA(0, 1), a2 + hstep);
;         WAIT_V(8); WAIT_L(0); BAR; MMA(0, 0, At, B0); MMA(0, 1, At, B1); BAR; SCHED;
	s_setprio 0
	s_waitcnt lgkmcnt(0)
	v_mfma_f32_16x16x32_bf16 v[60:63], v[148:151], v[184:187], v[60:63]
	v_mfma_f32_16x16x32_bf16 v[56:59], v[160:163], v[184:187], v[56:59]
	v_mfma_f32_16x16x32_bf16 v[44:47], v[148:151], v[192:195], v[44:47]
	v_mfma_f32_16x16x32_bf16 v[40:43], v[160:163], v[192:195], v[40:43]
	v_mfma_f32_16x16x32_bf16 v[28:31], v[148:151], v[200:203], v[28:31]
	v_mfma_f32_16x16x32_bf16 v[24:27], v[160:163], v[200:203], v[24:27]
	v_mfma_f32_16x16x32_bf16 v[12:15], v[148:151], v[208:211], v[12:15]
	v_mfma_f32_16x16x32_bf16 v[8:11], v[160:163], v[208:211], v[8:11]
	v_mfma_f32_16x16x32_bf16 v[60:63], v[156:159], v[188:191], v[60:63]
	v_mfma_f32_16x16x32_bf16 v[56:59], v[164:167], v[188:191], v[56:59]
	v_mfma_f32_16x16x32_bf16 v[44:47], v[156:159], v[196:199], v[44:47]
	v_mfma_f32_16x16x32_bf16 v[40:43], v[164:167], v[196:199], v[40:43]
	v_mfma_f32_16x16x32_bf16 v[28:31], v[156:159], v[204:207], v[28:31]
	v_mfma_f32_16x16x32_bf16 v[24:27], v[164:167], v[204:207], v[24:27]
	v_mfma_f32_16x16x32_bf16 v[12:15], v[156:159], v[214:217], v[12:15]
	v_mfma_f32_16x16x32_bf16 v[8:11], v[164:167], v[214:217], v[8:11]
	s_setprio 1
	s_setprio 0
	v_mfma_f32_16x16x32_bf16 v[52:55], v[168:171], v[184:187], v[52:55]
	v_mfma_f32_16x16x32_bf16 v[48:51], v[176:179], v[184:187], v[48:51]
	v_mfma_f32_16x16x32_bf16 v[36:39], v[168:171], v[192:195], v[36:39]
	v_mfma_f32_16x16x32_bf16 v[32:35], v[176:179], v[192:195], v[32:35]
	v_mfma_f32_16x16x32_bf16 v[20:23], v[168:171], v[200:203], v[20:23]
	v_mfma_f32_16x16x32_bf16 v[16:19], v[176:179], v[200:203], v[16:19]
	v_mfma_f32_16x16x32_bf16 v[4:7], v[168:171], v[208:211], v[4:7]
	v_mfma_f32_16x16x32_bf16 v[0:3], v[176:179], v[208:211], v[0:3]
	v_mfma_f32_16x16x32_bf16 v[52:55], v[172:175], v[188:191], v[52:55]
	v_mfma_f32_16x16x32_bf16 v[48:51], v[180:183], v[188:191], v[48:51]
	v_mfma_f32_16x16x32_bf16 v[36:39], v[172:175], v[196:199], v[36:39]
	v_mfma_f32_16x16x32_bf16 v[32:35], v[180:183], v[196:199], v[32:35]
	v_mfma_f32_16x16x32_bf16 v[20:23], v[172:175], v[204:207], v[20:23]
	v_mfma_f32_16x16x32_bf16 v[16:19], v[180:183], v[204:207], v[16:19]
	v_mfma_f32_16x16x32_bf16 v[4:7], v[172:175], v[214:217], v[4:7]
	v_mfma_f32_16x16x32_bf16 v[0:3], v[180:183], v[214:217], v[0:3]
	s_setprio 1
	s_barrier
	s_add_i32 s61, 0, 0x18000
	v_add_u32_e32 v155, s61, v140
	s_add_i32 s65, 0, 0x1c000
	ds_read_b128 v[148:151], v155
	ds_read_b128 v[156:159], v155 offset:1024
	ds_read_b128 v[160:163], v155 offset:2048
	ds_read_b128 v[164:167], v155 offset:3072
	v_add_u32_e32 v155, s65, v140
	ds_read_b128 v[168:171], v155
	ds_read_b128 v[172:175], v155 offset:1024
	ds_read_b128 v[176:179], v155 offset:2048
	ds_read_b128 v[180:183], v155 offset:3072
	s_add_u32 s52, s88, 0x40000
	s_addc_u32 s53, s89, 0
	s_mov_b32 m0, s13
	v_lshl_add_u64 v[224:225], s[52:53], 0, v[128:129]
	ds_read_b128 v[184:187], v147 offset:32768
	ds_read_b128 v[188:191], v147 offset:33792
	ds_read_b128 v[192:195], v147 offset:34816
	ds_read_b128 v[196:199], v147 offset:35840
	ds_read_b128 v[200:203], v147 offset:36864
	ds_read_b128 v[204:207], v147 offset:37888
	ds_read_b128 v[208:211], v147 offset:38912
	ds_read_b128 v[214:217], v147 offset:39936
	global_load_lds_dwordx4 v[224:225], off
	v_lshl_add_u64 v[224:225], s[52:53], 0, v[132:133]
	s_mov_b32 m0, s14
	s_nop 0
	global_load_lds_dwordx4 v[224:225], off
	s_waitcnt vmcnt(8)
	s_waitcnt lgkmcnt(0)
	s_barrier
	s_setprio 0
	s_waitcnt lgkmcnt(0)
	v_mfma_f32_16x16x32_bf16 v[124:127], v[148:151], v[184:187], v[124:127]
	v_mfma_f32_16x16x32_bf16 v[120:123], v[160:163], v[184:187], v[120:123]
	v_mfma_f32_16x16x32_bf16 v[108:111], v[148:151], v[192:195], v[108:111]
	v_mfma_f32_16x16x32_bf16 v[104:107], v[160:163], v[192:195], v[104:107]
	v_mfma_f32_16x16x32_bf16 v[92:95], v[148:151], v[200:203], v[92:95]
	v_mfma_f32_16x16x32_bf16 v[88:91], v[160:163], v[200:203], v[88:91]
	v_mfma_f32_16x16x32_bf16 v[76:79], v[148:151], v[208:211], v[76:79]
	v_mfma_f32_16x16x32_bf16 v[72:75], v[160:163], v[208:211], v[72:75]
	v_mfma_f32_16x16x32_bf16 v[124:127], v[156:159], v[188:191], v[124:127]
	v_mfma_f32_16x16x32_bf16 v[120:123], v[164:167], v[188:191], v[120:123]
	v_mfma_f32_16x16x32_bf16 v[108:111], v[156:159], v[196:199], v[108:111]
	v_mfma_f32_16x16x32_bf16 v[104:107], v[164:167], v[196:199], v[104:107]
	v_mfma_f32_16x16x32_bf16 v[92:95], v[156:159], v[204:207], v[92:95]
	v_mfma_f32_16x16x32_bf16 v[88:91], v[164:167], v[204:207], v[88:91]
	v_mfma_f32_16x16x32_bf16 v[76:79], v[156:159], v[214:217], v[76:79]
	v_mfma_f32_16x16x32_bf16 v[72:75], v[164:167], v[214:217], v[72:75]
	s_setprio 1
	s_setprio 0
	v_mfma_f32_16x16x32_bf16 v[116:119], v[168:171], v[184:187], v[116:119]
	v_mfma_f32_16x16x32_bf16 v[112:115], v[176:179], v[184:187], v[112:115]
	v_mfma_f32_16x16x32_bf16 v[100:103], v[168:171], v[192:195], v[100:103]
	v_mfma_f32_16x16x32_bf16 v[96:99], v[176:179], v[192:195], v[96:99]
	v_mfma_f32_16x16x32_bf16 v[84:87], v[168:171], v[200:203], v[84:87]
	v_mfma_f32_16x16x32_bf16 v[80:83], v[176:179], v[200:203], v[80:83]
	v_mfma_f32_16x16x32_bf16 v[68:71], v[168:171], v[208:211], v[68:71]
	v_mfma_f32_16x16x32_bf16 v[64:67], v[176:179], v[208:211], v[64:67]
	v_mfma_f32_16x16x32_bf16 v[116:119], v[172:175], v[188:191], v[116:119]
	v_mfma_f32_16x16x32_bf16 v[112:115], v[180:183], v[188:191], v[112:115]
	v_mfma_f32_16x16x32_bf16 v[100:103], v[172:175], v[196:199], v[100:103]
	v_mfma_f32_16x16x32_bf16 v[96:99], v[180:183], v[196:199], v[96:99]
	v_mfma_f32_16x16x32_bf16 v[84:87], v[172:175], v[204:207], v[84:87]
	v_mfma_f32_16x16x32_bf16 v[80:83], v[180:183], v[204:207], v[80:83]
	v_mfma_f32_16x16x32_bf16 v[68:71], v[172:175], v[214:217], v[68:71]
	v_mfma_f32_16x16x32_bf16 v[64:67], v[180:183], v[214:217], v[64:67]
	s_setprio 1
	s_barrier
; #define STAGE(bufoff, gbase) STAGE_(bufoff, gbase, voffA)
; #define STAGEB(bufoff, gbase) STAGE_(bufoff, gbase, voffB)
; #define LDA(dst, b, h) do { _Pragma("unroll") for (int m = 0; m < 4; ++m) _Pragma("unroll") for (int k = 0; k < 2; ++k) dst[m][k] = *LDSP(const bf16x8, lds + SA(b, h) + aoff + m * 2048 + k * 1024); } while (0)
; #define MMA(ai, bj, AT, BT) do { __builtin_amdgcn_s_setprio(1); \
;     _Pragma("unroll") for (int m = 0; m < 4; ++m) _Pragma("unroll") for (int n = 0; n < 2; ++n) _Pragma("unroll") for (int k = 0; k < 2; ++k) \
;       acc[ai][bj][m][n] = __builtin_amdgcn_mfma_f32_16x16x32_bf16(BT[n][k], AT[m][k], acc[ai][bj][m][n], 0, 0, 0); \
;     __builtin_amdgcn_s_setprio(0); } while (0)
; #define WAIT_V(n) asm volatile("s_waitcnt vmcnt(" #n ")" ::: "memory")
; #define WAIT_L(n) asm volatile("s_waitcnt lgkmcnt(" #n ")" ::: "memory")
; #define BAR __builtin_amdgcn_s_barrier()
; #define SCHED __builtin_amdgcn_sched_barrier(0)
; #define WAIT_V(n) asm volatile("s_waitcnt vmcnt(" #n ")" ::: "memory")
; #define BAR do { __builtin_amdgcn_sched_barrier(0); __builtin_amdgcn_s_barrier(); asm volatile("" ::: "memory"); __builtin_amdgcn_sched_barrier(0); } while (0)
; template <bool SP2, bool ALIGN_EPI, bool DUAL, class Epi> DI void gemm_phase2(const bf16_t* A, const bf16_t* Bt, const bf16_t* A2, const bf16_t* Bt2, int M, int N, int K, const Epi& E, lds_t* lds) {
;     ...
;     for (int t = 0; t < nt; t += 2) {
;       const bool last = (t == nt - 2);
;       const char* a1 = cA + (size_t)(t + 1) * kstep;
;       const char* a2 = last ? nA : cA + (size_t)(t + 2) * kstep; const char* b2 = last ? nB : cB + (size_t)(t + 2) * kstep;
;       const char* a3 = a2 + kstep; const char* b3 = b2 + kstep;
;     ...
;         LDA(At, 1, 1); STAGEB(SB(1, 0), b3); STAGEB(SB(1, 1), b3 + bstep); STAGE(SA(1, 0), a3);
;         WAIT_V(8); WAIT_L(0); BAR; MMA(1, 0, At, B0); MMA(1, 1, At, B1); BAR; SCHED;
	s_add_i32 s52, s61, s2
	v_lshl_add_u64 v[152:153], v[152:153], 0, s[8:9]
	s_mov_b32 m0, s52
	ds_read_b128 v[184:187], v147 offset:49152
	ds_read_b128 v[188:191], v147 offset:50176
	ds_read_b128 v[192:195], v147 offset:51200
	ds_read_b128 v[196:199], v147 offset:52224
	ds_read_b128 v[200:203], v147 offset:53248
	ds_read_b128 v[204:207], v147 offset:54272
	ds_read_b128 v[208:211], v147 offset:55296
	ds_read_b128 v[214:217], v147 offset:56320
	global_load_lds_dwordx4 v[152:153], off
	s_add_i32 m0, s52, 0x2000
	s_add_u32 s52, s86, 0x10080
	v_lshl_add_u64 v[152:153], v[218:219], 0, s[8:9]
	s_addc_u32 s53, s87, 0
	s_add_i32 s61, s65, s2
	global_load_lds_dwordx4 v[152:153], off
	v_lshl_add_u64 v[152:153], s[52:53], 0, v[130:131]
	s_mov_b32 m0, s61
	s_nop 0
	global_load_lds_dwordx4 v[152:153], off
	v_lshl_add_u64 v[152:153], s[52:53], 0, v[134:135]
	s_add_i32 m0, s61, 0x2000
	s_nop 0
	global_load_lds_dwordx4 v[152:153], off
	v_lshl_add_u64 v[152:153], v[220:221], 0, s[8:9]
	s_mov_b32 m0, s15
	s_nop 0
	global_load_lds_dwordx4 v[152:153], off
	v_lshl_add_u64 v[152:153], v[222:223], 0, s[8:9]
	s_mov_b32 m0, s18
	s_nop 0
	global_load_lds_dwordx4 v[152:153], off
	s_waitcnt vmcnt(8)
	s_waitcnt lgkmcnt(0)
	s_barrier
	s_setprio 0
	s_waitcnt lgkmcnt(0)
	v_mfma_f32_16x16x32_bf16 v[60:63], v[148:151], v[184:187], v[60:63]
	v_mfma_f32_16x16x32_bf16 v[56:59], v[160:163], v[184:187], v[56:59]
	v_mfma_f32_16x16x32_bf16 v[44:47], v[148:151], v[192:195], v[44:47]
	v_mfma_f32_16x16x32_bf16 v[40:43], v[160:163], v[192:195], v[40:43]
	v_mfma_f32_16x16x32_bf16 v[28:31], v[148:151], v[200:203], v[28:31]
	v_mfma_f32_16x16x32_bf16 v[24:27], v[160:163], v[200:203], v[24:27]
	v_mfma_f32_16x16x32_bf16 v[12:15], v[148:151], v[208:211], v[12:15]
	v_mfma_f32_16x16x32_bf16 v[8:11], v[160:163], v[208:211], v[8:11]
	v_mfma_f32_16x16x32_bf16 v[60:63], v[156:159], v[188:191], v[60:63]
	v_mfma_f32_16x16x32_bf16 v[56:59], v[164:167], v[188:191], v[56:59]
	v_mfma_f32_16x16x32_bf16 v[44:47], v[156:159], v[196:199], v[44:47]
	v_mfma_f32_16x16x32_bf16 v[40:43], v[164:167], v[196:199], v[40:43]
	v_mfma_f32_16x16x32_bf16 v[28:31], v[156:159], v[204:207], v[28:31]
	v_mfma_f32_16x16x32_bf16 v[24:27], v[164:167], v[204:207], v[24:27]
	v_mfma_f32_16x16x32_bf16 v[12:15], v[156:159], v[214:217], v[12:15]
	v_mfma_f32_16x16x32_bf16 v[8:11], v[164:167], v[214:217], v[8:11]
	s_setprio 1
	s_setprio 0
	v_mfma_f32_16x16x32_bf16 v[52:55], v[168:171], v[184:187], v[52:55]
	v_mfma_f32_16x16x32_bf16 v[48:51], v[176:179], v[184:187], v[48:51]
	v_mfma_f32_16x16x32_bf16 v[36:39], v[168:171], v[192:195], v[36:39]
	v_mfma_f32_16x16x32_bf16 v[32:35], v[176:179], v[192:195], v[32:35]
	v_mfma_f32_16x16x32_bf16 v[20:23], v[168:171], v[200:203], v[20:23]
	v_mfma_f32_16x16x32_bf16 v[16:19], v[176:179], v[200:203], v[16:19]
	v_mfma_f32_16x16x32_bf16 v[4:7], v[168:171], v[208:211], v[4:7]
	v_mfma_f32_16x16x32_bf16 v[0:3], v[176:179], v[208:211], v[0:3]
	v_mfma_f32_16x16x32_bf16 v[52:55], v[172:175], v[188:191], v[52:55]
	v_mfma_f32_16x16x32_bf16 v[48:51], v[180:183], v[188:191], v[48:51]
	v_mfma_f32_16x16x32_bf16 v[36:39], v[172:175], v[196:199], v[36:39]
	v_mfma_f32_16x16x32_bf16 v[32:35], v[180:183], v[196:199], v[32:35]
	v_mfma_f32_16x16x32_bf16 v[20:23], v[172:175], v[204:207], v[20:23]
	v_mfma_f32_16x16x32_bf16 v[16:19], v[180:183], v[204:207], v[16:19]
	v_mfma_f32_16x16x32_bf16 v[4:7], v[172:175], v[214:217], v[4:7]
	v_mfma_f32_16x16x32_bf16 v[0:3], v[180:183], v[214:217], v[0:3]
	s_setprio 1
	s_barrier
	s_add_i32 s35, s35, 2
	s_add_u32 s68, s68, 0x100
	s_addc_u32 s69, s69, 0
	s_add_u32 s33, s33, 0x100
	s_addc_u32 s34, s34, 0
	s_cmp_gt_u32 s35, 13
	s_cbranch_scc0 .LBB0_341
	s_and_b64 vcc, exec, s[54:55]
	s_cbranch_vccz .LBB0_344
	s_barrier

; #define STAGE(bufoff, gbase) STAGE_(bufoff, gbase, voffA)
; #define STAGEB(bufoff, gbase) STAGE_(bufoff, gbase, voffB)
; #define LDA(dst, b, h) do { _Pragma("unroll") for (int m = 0; m < 4; ++m) _Pragma("unroll") for (int k = 0; k < 2; ++k) dst[m][k] = *LDSP(const bf16x8, lds + SA(b, h) + aoff + m * 2048 + k * 1024); } while (0)
; #define LDB(dst, b, h) do { _Pragma("unroll") for (int n = 0; n < 2; ++n) _Pragma("unroll") for (int k = 0; k < 2; ++k) dst[n][k] = *LDSP(const bf16x8, lds + SB(b, h) + boff + n * 2048 + k * 1024); } while (0)
; #define MMA(ai, bj, AT, BT) do { __builtin_amdgcn_s_setprio(1); \
;     _Pragma("unroll") for (int m = 0; m < 4; ++m) _Pragma("unroll") for (int n = 0; n < 2; ++n) _Pragma("unroll") for (int k = 0; k < 2; ++k) \
;       acc[ai][bj][m][n] = __builtin_amdgcn_mfma_f32_16x16x32_bf16(BT[n][k], AT[m][k], acc[ai][bj][m][n], 0, 0, 0); \
;     __builtin_amdgcn_s_setprio(0); } while (0)
; #define WAIT_V(n) asm volatile("s_waitcnt vmcnt(" #n ")" ::: "memory")
; #define WAIT_L(n) asm volatile("s_waitcnt lgkmcnt(" #n ")" ::: "memory")
; #define BAR __builtin_amdgcn_s_barrier()
; #define SCHED __builtin_amdgcn_sched_barrier(0)
; #define WAIT_V(n) asm volatile("s_waitcnt vmcnt(" #n ")" ::: "memory")
; #define BAR do { __builtin_amdgcn_sched_barrier(0); __builtin_amdgcn_s_barrier(); asm volatile("" ::: "memory"); __builtin_amdgcn_sched_barrier(0); } while (0)
; template <bool SP2, bool ALIGN_EPI, bool DUAL, class Epi> DI void gemm_phase2(const bf16_t* A, const bf16_t* Bt, const bf16_t* A2, const bf16_t* Bt2, int M, int N, int K, const Epi& E, lds_t* lds) {
;     ...
;     for (int t = 0; t < nt; t += 2) {
;       const bool last = (t == nt - 2);
;       const char* a1 = cA + (size_t)(t + 1) * kstep;
;       const char* a2 = last ? nA : cA + (size_t)(t + 2) * kstep; const char* b2 = last ? nB : cB + (size_t)(t + 2) * kstep;
;       const char* a3 = a2 + kstep; const char* b3 = b2 + kstep;
;       if constexpr (SP2) {
;         LDB(B0, 0, 0); LDB(B1, 0, 1); SCHED; LDA(At, 0, 0); STAGE(SA(1, 1), a1 + hstep);
;         WAIT_V(8); WAIT_L(0); BAR; MMA(0, 0, At, B0); MMA(0, 1, At, B1); BAR; SCHED;
;         LDA(At, 0, 1); STAGEB(SB(0, 0), b2); STAGEB(SB(0, 1), b2 + bstep); STAGE(SA(0, 0), a2);
;         WAIT_V(8); WAIT_L(0); BAR; MMA(1, 0, At, B0); MMA(1, 1, At, B1); BAR; SCHED;
.LBB0_482:
	v_add_u32_e32 v151, s20, v141
	ds_read_b128 v[152:155], v151
	ds_read_b128 v[156:159], v151 offset:1024
	ds_read_b128 v[160:163], v151 offset:2048
	ds_read_b128 v[164:167], v151 offset:3072
	v_add_u32_e32 v151, s21, v141
	ds_read_b128 v[168:171], v151
	ds_read_b128 v[172:175], v151 offset:1024
	ds_read_b128 v[176:179], v151 offset:2048
	ds_read_b128 v[180:183], v151 offset:3072
	s_add_u32 s41, s60, 0xfffc0080
	s_addc_u32 s59, s61, -1
	s_cmp_eq_u32 s37, 12
	s_cselect_b32 s65, s2, s59
	s_cselect_b32 s64, s3, s41
	s_cselect_b32 s63, s0, s35
	s_cselect_b32 s62, s1, s34
	v_lshl_add_u64 v[220:221], s[60:61], 0, v[136:137]
	s_add_i32 m0, s9, 0xc000
	ds_read_b128 v[184:187], v149
	ds_read_b128 v[188:191], v149 offset:1024
	ds_read_b128 v[192:195], v149 offset:2048
	ds_read_b128 v[196:199], v149 offset:3072
	ds_read_b128 v[200:203], v149 offset:4096
	ds_read_b128 v[204:207], v149 offset:5120
	ds_read_b128 v[208:211], v149 offset:6144
	ds_read_b128 v[216:219], v149 offset:7168
	global_load_lds_dwordx4 v[220:221], off
	v_lshl_add_u64 v[220:221], s[60:61], 0, v[138:139]
	s_add_i32 m0, s9, 0xe000
	s_nop 0
	global_load_lds_dwordx4 v[220:221], off
	s_waitcnt vmcnt(8)
	s_waitcnt lgkmcnt(0)
	s_barrier
	s_setprio 0
	s_waitcnt lgkmcnt(0)
	v_mfma_f32_16x16x32_bf16 v[124:127], v[152:155], v[184:187], v[124:127]
	v_mfma_f32_16x16x32_bf16 v[120:123], v[160:163], v[184:187], v[120:123]
	v_mfma_f32_16x16x32_bf16 v[116:119], v[152:155], v[192:195], v[116:119]
	v_mfma_f32_16x16x32_bf16 v[112:115], v[160:163], v[192:195], v[112:115]
	v_mfma_f32_16x16x32_bf16 v[108:111], v[152:155], v[200:203], v[108:111]
	v_mfma_f32_16x16x32_bf16 v[104:107], v[160:163], v[200:203], v[104:107]
	v_mfma_f32_16x16x32_bf16 v[100:103], v[152:155], v[208:211], v[100:103]
	v_mfma_f32_16x16x32_bf16 v[96:99], v[160:163], v[208:211], v[96:99]
	v_mfma_f32_16x16x32_bf16 v[124:127], v[156:159], v[188:191], v[124:127]
	v_mfma_f32_16x16x32_bf16 v[120:123], v[164:167], v[188:191], v[120:123]
	v_mfma_f32_16x16x32_bf16 v[116:119], v[156:159], v[196:199], v[116:119]
	v_mfma_f32_16x16x32_bf16 v[112:115], v[164:167], v[196:199], v[112:115]
	v_mfma_f32_16x16x32_bf16 v[108:111], v[156:159], v[204:207], v[108:111]
	v_mfma_f32_16x16x32_bf16 v[104:107], v[164:167], v[204:207], v[104:107]
	v_mfma_f32_16x16x32_bf16 v[100:103], v[156:159], v[216:219], v[100:103]
	v_mfma_f32_16x16x32_bf16 v[96:99], v[164:167], v[216:219], v[96:99]
	s_setprio 1
	s_setprio 0
	v_mfma_f32_16x16x32_bf16 v[92:95], v[168:171], v[184:187], v[92:95]
	v_mfma_f32_16x16x32_bf16 v[88:91], v[176:179], v[184:187], v[88:91]
	v_mfma_f32_16x16x32_bf16 v[84:87], v[168:171], v[192:195], v[84:87]
	v_mfma_f32_16x16x32_bf16 v[80:83], v[176:179], v[192:195], v[80:83]
	v_mfma_f32_16x16x32_bf16 v[76:79], v[168:171], v[200:203], v[76:79]
	v_mfma_f32_16x16x32_bf16 v[72:75], v[176:179], v[200:203], v[72:75]
	v_mfma_f32_16x16x32_bf16 v[68:71], v[168:171], v[208:211], v[68:71]
	v_mfma_f32_16x16x32_bf16 v[64:67], v[176:179], v[208:211], v[64:67]
	v_mfma_f32_16x16x32_bf16 v[92:95], v[172:175], v[188:191], v[92:95]
	v_mfma_f32_16x16x32_bf16 v[88:91], v[180:183], v[188:191], v[88:91]
	v_mfma_f32_16x16x32_bf16 v[84:87], v[172:175], v[196:199], v[84:87]
	v_mfma_f32_16x16x32_bf16 v[80:83], v[180:183], v[196:199], v[80:83]
	v_mfma_f32_16x16x32_bf16 v[76:79], v[172:175], v[204:207], v[76:79]
	v_mfma_f32_16x16x32_bf16 v[72:75], v[180:183], v[204:207], v[72:75]
	v_mfma_f32_16x16x32_bf16 v[68:71], v[172:175], v[216:219], v[68:71]
	v_mfma_f32_16x16x32_bf16 v[64:67], v[180:183], v[216:219], v[64:67]
	s_setprio 1
	s_barrier
	s_add_i32 s41, s20, s8
	v_lshl_add_u64 v[220:221], s[62:63], 0, v[130:131]
	s_mov_b32 m0, s41
	ds_read_b128 v[184:187], v149 offset:16384
	ds_read_b128 v[188:191], v149 offset:17408
	ds_read_b128 v[192:195], v149 offset:18432
	ds_read_b128 v[196:199], v149 offset:19456
	ds_read_b128 v[200:203], v149 offset:20480
	ds_read_b128 v[204:207], v149 offset:21504
	ds_read_b128 v[208:211], v149 offset:22528
	ds_read_b128 v[216:219], v149 offset:23552
	global_load_lds_dwordx4 v[220:221], off
	s_add_i32 m0, s41, 0x2000
	s_add_u32 s66, s62, 0x10000
	v_lshl_add_u64 v[222:223], s[62:63], 0, v[134:135]
	s_addc_u32 s67, s63, 0
	s_add_i32 s41, s21, s8
	global_load_lds_dwordx4 v[222:223], off
	v_lshl_add_u64 v[224:225], s[66:67], 0, v[130:131]
	s_mov_b32 m0, s41
	v_lshl_add_u64 v[226:227], s[64:65], 0, v[132:133]
	global_load_lds_dwordx4 v[224:225], off
	v_lshl_add_u64 v[224:225], s[66:67], 0, v[134:135]
	s_add_i32 m0, s41, 0x2000
	s_nop 0
	global_load_lds_dwordx4 v[224:225], off
	v_lshl_add_u64 v[224:225], s[64:65], 0, v[128:129]
	s_mov_b32 m0, s9
	s_nop 0
	global_load_lds_dwordx4 v[224:225], off
	s_mov_b32 m0, s10
	s_nop 0
	global_load_lds_dwordx4 v[226:227], off
	s_waitcnt vmcnt(8)
	s_waitcnt lgkmcnt(0)
	s_barrier
; #define STAGE(bufoff, gbase) STAGE_(bufoff, gbase, voffA)
; #define LDA(dst, b, h) do { _Pragma("unroll") for (int m = 0; m < 4; ++m) _Pragma("unroll") for (int k = 0; k < 2; ++k) dst[m][k] = *LDSP(const bf16x8, lds + SA(b, h) + aoff + m * 2048 + k * 1024); } while (0)
; #define LDB(dst, b, h) do { _Pragma("unroll") for (int n = 0; n < 2; ++n) _Pragma("unroll") for (int k = 0; k < 2; ++k) dst[n][k] = *LDSP(const bf16x8, lds + SB(b, h) + boff + n * 2048 + k * 1024); } while (0)
; #define MMA(ai, bj, AT, BT) do { __builtin_amdgcn_s_setprio(1); \
;     _Pragma("unroll") for (int m = 0; m < 4; ++m) _Pragma("unroll") for (int n = 0; n < 2; ++n) _Pragma("unroll") for (int k = 0; k < 2; ++k) \
;       acc[ai][bj][m][n] = __builtin_amdgcn_mfma_f32_16x16x32_bf16(BT[n][k], AT[m][k], acc[ai][bj][m][n], 0, 0, 0); \
;     __builtin_amdgcn_s_setprio(0); } while (0)
; #define WAIT_V(n) asm volatile("s_waitcnt vmcnt(" #n ")" ::: "memory")
; #define WAIT_L(n) asm volatile("s_waitcnt lgkmcnt(" #n ")" ::: "memory")
; #define BAR __builtin_amdgcn_s_barrier()
; #define SCHED __builtin_amdgcn_sched_barrier(0)
; #define WAIT_V(n) asm volatile("s_waitcnt vmcnt(" #n ")" ::: "memory")
; #define BAR do { __builtin_amdgcn_sched_barrier(0); __builtin_amdgcn_s_barrier(); asm volatile("" ::: "memory"); __builtin_amdgcn_sched_barrier(0); } while (0)
; template <bool SP2, bool ALIGN_EPI, bool DUAL, class Epi> DI void gemm_phase2(const bf16_t* A, const bf16_t* Bt, const bf16_t* A2, const bf16_t* Bt2, int M, int N, int K, const Epi& E, lds_t* lds) {
;     ...
;         WAIT_V(8); WAIT_L(0); BAR; MMA(1, 0, At, B0); MMA(1, 1, At, B1); BAR; SCHED;
;         LDB(B0, 1, 0); LDB(B1, 1, 1); SCHED; LDA(At, 1, 0); STAGE(SA(0, 1), a2 + hstep);
;         WAIT_V(8); WAIT_L(0); BAR; MMA(0, 0, At, B0); MMA(0, 1, At, B1); BAR; SCHED;
	s_setprio 0
	s_waitcnt lgkmcnt(0)
	v_mfma_f32_16x16x32_bf16 v[60:63], v[152:155], v[184:187], v[60:63]
	v_mfma_f32_16x16x32_bf16 v[56:59], v[160:163], v[184:187], v[56:59]
	v_mfma_f32_16x16x32_bf16 v[52:55], v[152:155], v[192:195], v[52:55]
	v_mfma_f32_16x16x32_bf16 v[48:51], v[160:163], v[192:195], v[48:51]
	v_mfma_f32_16x16x32_bf16 v[44:47], v[152:155], v[200:203], v[44:47]
	v_mfma_f32_16x16x32_bf16 v[40:43], v[160:163], v[200:203], v[40:43]
	v_mfma_f32_16x16x32_bf16 v[36:39], v[152:155], v[208:211], v[36:39]
	v_mfma_f32_16x16x32_bf16 v[32:35], v[160:163], v[208:211], v[32:35]
	v_mfma_f32_16x16x32_bf16 v[60:63], v[156:159], v[188:191], v[60:63]
	v_mfma_f32_16x16x32_bf16 v[56:59], v[164:167], v[188:191], v[56:59]
	v_mfma_f32_16x16x32_bf16 v[52:55], v[156:159], v[196:199], v[52:55]
	v_mfma_f32_16x16x32_bf16 v[48:51], v[164:167], v[196:199], v[48:51]
	v_mfma_f32_16x16x32_bf16 v[44:47], v[156:159], v[204:207], v[44:47]
	v_mfma_f32_16x16x32_bf16 v[40:43], v[164:167], v[204:207], v[40:43]
	v_mfma_f32_16x16x32_bf16 v[36:39], v[156:159], v[216:219], v[36:39]
	v_mfma_f32_16x16x32_bf16 v[32:35], v[164:167], v[216:219], v[32:35]
	s_setprio 1
	s_setprio 0
	v_mfma_f32_16x16x32_bf16 v[28:31], v[168:171], v[184:187], v[28:31]
	v_mfma_f32_16x16x32_bf16 v[24:27], v[176:179], v[184:187], v[24:27]
	v_mfma_f32_16x16x32_bf16 v[20:23], v[168:171], v[192:195], v[20:23]
	v_mfma_f32_16x16x32_bf16 v[16:19], v[176:179], v[192:195], v[16:19]
	v_mfma_f32_16x16x32_bf16 v[12:15], v[168:171], v[200:203], v[12:15]
	v_mfma_f32_16x16x32_bf16 v[8:11], v[176:179], v[200:203], v[8:11]
	v_mfma_f32_16x16x32_bf16 v[4:7], v[168:171], v[208:211], v[4:7]
	v_mfma_f32_16x16x32_bf16 v[0:3], v[176:179], v[208:211], v[0:3]
	v_mfma_f32_16x16x32_bf16 v[28:31], v[172:175], v[188:191], v[28:31]
	v_mfma_f32_16x16x32_bf16 v[24:27], v[180:183], v[188:191], v[24:27]
	v_mfma_f32_16x16x32_bf16 v[20:23], v[172:175], v[196:199], v[20:23]
	v_mfma_f32_16x16x32_bf16 v[16:19], v[180:183], v[196:199], v[16:19]
	v_mfma_f32_16x16x32_bf16 v[12:15], v[172:175], v[204:207], v[12:15]
	v_mfma_f32_16x16x32_bf16 v[8:11], v[180:183], v[204:207], v[8:11]
	v_mfma_f32_16x16x32_bf16 v[4:7], v[172:175], v[216:219], v[4:7]
	v_mfma_f32_16x16x32_bf16 v[0:3], v[180:183], v[216:219], v[0:3]
	s_setprio 1
	s_barrier
	s_add_i32 s41, 0, 0x18000
	v_add_u32_e32 v151, s41, v141
	s_add_i32 s59, 0, 0x1c000
	ds_read_b128 v[152:155], v151
	ds_read_b128 v[156:159], v151 offset:1024
	ds_read_b128 v[160:163], v151 offset:2048
	ds_read_b128 v[164:167], v151 offset:3072
	v_add_u32_e32 v151, s59, v141
	ds_read_b128 v[168:171], v151
	ds_read_b128 v[172:175], v151 offset:1024
	ds_read_b128 v[176:179], v151 offset:2048
	ds_read_b128 v[180:183], v151 offset:3072
	s_add_u32 s64, s64, 0x40000
	s_addc_u32 s65, s65, 0
	s_mov_b32 m0, s11
	v_lshl_add_u64 v[228:229], s[64:65], 0, v[128:129]
	ds_read_b128 v[184:187], v149 offset:32768
	ds_read_b128 v[188:191], v149 offset:33792
	ds_read_b128 v[192:195], v149 offset:34816
	ds_read_b128 v[196:199], v149 offset:35840
	ds_read_b128 v[200:203], v149 offset:36864
	ds_read_b128 v[204:207], v149 offset:37888
	ds_read_b128 v[208:211], v149 offset:38912
	ds_read_b128 v[216:219], v149 offset:39936
	global_load_lds_dwordx4 v[228:229], off
	v_lshl_add_u64 v[228:229], s[64:65], 0, v[132:133]
	s_mov_b32 m0, s14
	s_nop 0
	global_load_lds_dwordx4 v[228:229], off
	s_waitcnt vmcnt(8)
	s_waitcnt lgkmcnt(0)
	s_barrier
	s_setprio 0
	s_waitcnt lgkmcnt(0)
	v_mfma_f32_16x16x32_bf16 v[124:127], v[152:155], v[184:187], v[124:127]
	v_mfma_f32_16x16x32_bf16 v[120:123], v[160:163], v[184:187], v[120:123]
	v_mfma_f32_16x16x32_bf16 v[116:119], v[152:155], v[192:195], v[116:119]
	v_mfma_f32_16x16x32_bf16 v[112:115], v[160:163], v[192:195], v[112:115]
	v_mfma_f32_16x16x32_bf16 v[108:111], v[152:155], v[200:203], v[108:111]
	v_mfma_f32_16x16x32_bf16 v[104:107], v[160:163], v[200:203], v[104:107]
	v_mfma_f32_16x16x32_bf16 v[100:103], v[152:155], v[208:211], v[100:103]
	v_mfma_f32_16x16x32_bf16 v[96:99], v[160:163], v[208:211], v[96:99]
	v_mfma_f32_16x16x32_bf16 v[124:127], v[156:159], v[188:191], v[124:127]
	v_mfma_f32_16x16x32_bf16 v[120:123], v[164:167], v[188:191], v[120:123]
	v_mfma_f32_16x16x32_bf16 v[116:119], v[156:159], v[196:199], v[116:119]
	v_mfma_f32_16x16x32_bf16 v[112:115], v[164:167], v[196:199], v[112:115]
	v_mfma_f32_16x16x32_bf16 v[108:111], v[156:159], v[204:207], v[108:111]
	v_mfma_f32_16x16x32_bf16 v[104:107], v[164:167], v[204:207], v[104:107]
	v_mfma_f32_16x16x32_bf16 v[100:103], v[156:159], v[216:219], v[100:103]
	v_mfma_f32_16x16x32_bf16 v[96:99], v[164:167], v[216:219], v[96:99]
	s_setprio 1
	s_setprio 0
	v_mfma_f32_16x16x32_bf16 v[92:95], v[168:171], v[184:187], v[92:95]
	v_mfma_f32_16x16x32_bf16 v[88:91], v[176:179], v[184:187], v[88:91]
	v_mfma_f32_16x16x32_bf16 v[84:87], v[168:171], v[192:195], v[84:87]
	v_mfma_f32_16x16x32_bf16 v[80:83], v[176:179], v[192:195], v[80:83]
	v_mfma_f32_16x16x32_bf16 v[76:79], v[168:171], v[200:203], v[76:79]
	v_mfma_f32_16x16x32_bf16 v[72:75], v[176:179], v[200:203], v[72:75]
	v_mfma_f32_16x16x32_bf16 v[68:71], v[168:171], v[208:211], v[68:71]
	v_mfma_f32_16x16x32_bf16 v[64:67], v[176:179], v[208:211], v[64:67]
	v_mfma_f32_16x16x32_bf16 v[92:95], v[172:175], v[188:191], v[92:95]
	v_mfma_f32_16x16x32_bf16 v[88:91], v[180:183], v[188:191], v[88:91]
	v_mfma_f32_16x16x32_bf16 v[84:87], v[172:175], v[196:199], v[84:87]
	v_mfma_f32_16x16x32_bf16 v[80:83], v[180:183], v[196:199], v[80:83]
	v_mfma_f32_16x16x32_bf16 v[76:79], v[172:175], v[204:207], v[76:79]
	v_mfma_f32_16x16x32_bf16 v[72:75], v[180:183], v[204:207], v[72:75]
	v_mfma_f32_16x16x32_bf16 v[68:71], v[172:175], v[216:219], v[68:71]
	v_mfma_f32_16x16x32_bf16 v[64:67], v[180:183], v[216:219], v[64:67]
	s_setprio 1
	s_barrier
; #define STAGE(bufoff, gbase) STAGE_(bufoff, gbase, voffA)
; #define STAGEB(bufoff, gbase) STAGE_(bufoff, gbase, voffB)
; #define LDA(dst, b, h) do { _Pragma("unroll") for (int m = 0; m < 4; ++m) _Pragma("unroll") for (int k = 0; k < 2; ++k) dst[m][k] = *LDSP(const bf16x8, lds + SA(b, h) + aoff + m * 2048 + k * 1024); } while (0)
; #define MMA(ai, bj, AT, BT) do { __builtin_amdgcn_s_setprio(1); \
;     _Pragma("unroll") for (int m = 0; m < 4; ++m) _Pragma("unroll") for (int n = 0; n < 2; ++n) _Pragma("unroll") for (int k = 0; k < 2; ++k) \
;       acc[ai][bj][m][n] = __builtin_amdgcn_mfma_f32_16x16x32_bf16(BT[n][k], AT[m][k], acc[ai][bj][m][n], 0, 0, 0); \
;     __builtin_amdgcn_s_setprio(0); } while (0)
; #define WAIT_V(n) asm volatile("s_waitcnt vmcnt(" #n ")" ::: "memory")
; #define WAIT_L(n) asm volatile("s_waitcnt lgkmcnt(" #n ")" ::: "memory")
; #define BAR __builtin_amdgcn_s_barrier()
; #define SCHED __builtin_amdgcn_sched_barrier(0)
; #define WAIT_V(n) asm volatile("s_waitcnt vmcnt(" #n ")" ::: "memory")
; #define BAR do { __builtin_amdgcn_sched_barrier(0); __builtin_amdgcn_s_barrier(); asm volatile("" ::: "memory"); __builtin_amdgcn_sched_barrier(0); } while (0)
; template <bool SP2, bool ALIGN_EPI, bool DUAL, class Epi> DI void gemm_phase2(const bf16_t* A, const bf16_t* Bt, const bf16_t* A2, const bf16_t* Bt2, int M, int N, int K, const Epi& E, lds_t* lds) {
;     ...
;     for (int t = 0; t < nt; t += 2) {
;       const bool last = (t == nt - 2);
;       const char* a1 = cA + (size_t)(t + 1) * kstep;
;       const char* a2 = last ? nA : cA + (size_t)(t + 2) * kstep; const char* b2 = last ? nB : cB + (size_t)(t + 2) * kstep;
;       const char* a3 = a2 + kstep; const char* b3 = b2 + kstep;
;     ...
;         LDA(At, 1, 1); STAGEB(SB(1, 0), b3); STAGEB(SB(1, 1), b3 + bstep); STAGE(SA(1, 0), a3);
;         WAIT_V(8); WAIT_L(0); BAR; MMA(1, 0, At, B0); MMA(1, 1, At, B1); BAR; SCHED;
	s_add_i32 s41, s41, s8
	v_lshl_add_u64 v[220:221], v[220:221], 0, s[30:31]
	s_mov_b32 m0, s41
	ds_read_b128 v[184:187], v149 offset:49152
	ds_read_b128 v[188:191], v149 offset:50176
	ds_read_b128 v[192:195], v149 offset:51200
	ds_read_b128 v[196:199], v149 offset:52224
	ds_read_b128 v[200:203], v149 offset:53248
	ds_read_b128 v[204:207], v149 offset:54272
	ds_read_b128 v[208:211], v149 offset:55296
	ds_read_b128 v[216:219], v149 offset:56320
	global_load_lds_dwordx4 v[220:221], off
	s_add_i32 m0, s41, 0x2000
	s_add_u32 s62, s62, 0x10080
	v_lshl_add_u64 v[220:221], v[222:223], 0, s[30:31]
	s_addc_u32 s63, s63, 0
	s_add_i32 s41, s59, s8
	global_load_lds_dwordx4 v[220:221], off
	v_lshl_add_u64 v[220:221], s[62:63], 0, v[130:131]
	s_mov_b32 m0, s41
	s_nop 0
	global_load_lds_dwordx4 v[220:221], off
	v_lshl_add_u64 v[220:221], s[62:63], 0, v[134:135]
	s_add_i32 m0, s41, 0x2000
	s_nop 0
	global_load_lds_dwordx4 v[220:221], off
	v_lshl_add_u64 v[220:221], v[224:225], 0, s[30:31]
	s_mov_b32 m0, s18
	s_nop 0
	global_load_lds_dwordx4 v[220:221], off
	v_lshl_add_u64 v[220:221], v[226:227], 0, s[30:31]
	s_mov_b32 m0, s19
	s_nop 0
	global_load_lds_dwordx4 v[220:221], off
	s_waitcnt vmcnt(8)
	s_waitcnt lgkmcnt(0)
	s_barrier
	s_setprio 0
	s_waitcnt lgkmcnt(0)
	v_mfma_f32_16x16x32_bf16 v[60:63], v[152:155], v[184:187], v[60:63]
	v_mfma_f32_16x16x32_bf16 v[56:59], v[160:163], v[184:187], v[56:59]
	v_mfma_f32_16x16x32_bf16 v[52:55], v[152:155], v[192:195], v[52:55]
	v_mfma_f32_16x16x32_bf16 v[48:51], v[160:163], v[192:195], v[48:51]
	v_mfma_f32_16x16x32_bf16 v[44:47], v[152:155], v[200:203], v[44:47]
	v_mfma_f32_16x16x32_bf16 v[40:43], v[160:163], v[200:203], v[40:43]
	v_mfma_f32_16x16x32_bf16 v[36:39], v[152:155], v[208:211], v[36:39]
	v_mfma_f32_16x16x32_bf16 v[32:35], v[160:163], v[208:211], v[32:35]
	v_mfma_f32_16x16x32_bf16 v[60:63], v[156:159], v[188:191], v[60:63]
	v_mfma_f32_16x16x32_bf16 v[56:59], v[164:167], v[188:191], v[56:59]
	v_mfma_f32_16x16x32_bf16 v[52:55], v[156:159], v[196:199], v[52:55]
	v_mfma_f32_16x16x32_bf16 v[48:51], v[164:167], v[196:199], v[48:51]
	v_mfma_f32_16x16x32_bf16 v[44:47], v[156:159], v[204:207], v[44:47]
	v_mfma_f32_16x16x32_bf16 v[40:43], v[164:167], v[204:207], v[40:43]
	v_mfma_f32_16x16x32_bf16 v[36:39], v[156:159], v[216:219], v[36:39]
	v_mfma_f32_16x16x32_bf16 v[32:35], v[164:167], v[216:219], v[32:35]
	s_setprio 1
	s_setprio 0
	v_mfma_f32_16x16x32_bf16 v[28:31], v[168:171], v[184:187], v[28:31]
	v_mfma_f32_16x16x32_bf16 v[24:27], v[176:179], v[184:187], v[24:27]
	v_mfma_f32_16x16x32_bf16 v[20:23], v[168:171], v[192:195], v[20:23]
	v_mfma_f32_16x16x32_bf16 v[16:19], v[176:179], v[192:195], v[16:19]
	v_mfma_f32_16x16x32_bf16 v[12:15], v[168:171], v[200:203], v[12:15]
	v_mfma_f32_16x16x32_bf16 v[8:11], v[176:179], v[200:203], v[8:11]
	v_mfma_f32_16x16x32_bf16 v[4:7], v[168:171], v[208:211], v[4:7]
	v_mfma_f32_16x16x32_bf16 v[0:3], v[176:179], v[208:211], v[0:3]
	v_mfma_f32_16x16x32_bf16 v[28:31], v[172:175], v[188:191], v[28:31]
	v_mfma_f32_16x16x32_bf16 v[24:27], v[180:183], v[188:191], v[24:27]
	v_mfma_f32_16x16x32_bf16 v[20:23], v[172:175], v[196:199], v[20:23]
	v_mfma_f32_16x16x32_bf16 v[16:19], v[180:183], v[196:199], v[16:19]
	v_mfma_f32_16x16x32_bf16 v[12:15], v[172:175], v[204:207], v[12:15]
	v_mfma_f32_16x16x32_bf16 v[8:11], v[180:183], v[204:207], v[8:11]
	v_mfma_f32_16x16x32_bf16 v[4:7], v[172:175], v[216:219], v[4:7]
	v_mfma_f32_16x16x32_bf16 v[0:3], v[180:183], v[216:219], v[0:3]
	s_setprio 1
	s_barrier
	s_add_i32 s37, s37, 2
	s_add_u32 s60, s60, 0x100
	s_addc_u32 s61, s61, 0
	s_add_u32 s34, s34, 0x100
	s_addc_u32 s35, s35, 0
	s_cmp_gt_u32 s37, 13
	s_cbranch_scc0 .LBB0_482
	s_and_b64 vcc, exec, s[38:39]
	s_cbranch_vccz .LBB0_485
	s_barrier

; #define STAGE(bufoff, gbase) STAGE_(bufoff, gbase, voffA)
; #define STAGEB(bufoff, gbase) STAGE_(bufoff, gbase, voffB)
; #define LDA(dst, b, h) do { _Pragma("unroll") for (int m = 0; m < 4; ++m) _Pragma("unroll") for (int k = 0; k < 2; ++k) dst[m][k] = *LDSP(const bf16x8, lds + SA(b, h) + aoff + m * 2048 + k * 1024); } while (0)
; #define LDB(dst, b, h) do { _Pragma("unroll") for (int n = 0; n < 2; ++n) _Pragma("unroll") for (int k = 0; k < 2; ++k) dst[n][k] = *LDSP(const bf16x8, lds + SB(b, h) + boff + n * 2048 + k * 1024); } while (0)
; #define MMA(ai, bj, AT, BT) do { __builtin_amdgcn_s_setprio(1); \
;     _Pragma("unroll") for (int m = 0; m < 4; ++m) _Pragma("unroll") for (int n = 0; n < 2; ++n) _Pragma("unroll") for (int k = 0; k < 2; ++k) \
;       acc[ai][bj][m][n] = __builtin_amdgcn_mfma_f32_16x16x32_bf16(BT[n][k], AT[m][k], acc[ai][bj][m][n], 0, 0, 0); \
;     __builtin_amdgcn_s_setprio(0); } while (0)
; #define WAIT_V(n) asm volatile("s_waitcnt vmcnt(" #n ")" ::: "memory")
; #define WAIT_L(n) asm volatile("s_waitcnt lgkmcnt(" #n ")" ::: "memory")
; #define BAR __builtin_amdgcn_s_barrier()
; #define SCHED __builtin_amdgcn_sched_barrier(0)
; #define WAIT_V(n) asm volatile("s_waitcnt vmcnt(" #n ")" ::: "memory")
; #define BAR do { __builtin_amdgcn_sched_barrier(0); __builtin_amdgcn_s_barrier(); asm volatile("" ::: "memory"); __builtin_amdgcn_sched_barrier(0); } while (0)
; template <bool SP2, bool ALIGN_EPI, bool DUAL, class Epi> DI void gemm_phase2(const bf16_t* A, const bf16_t* Bt, const bf16_t* A2, const bf16_t* Bt2, int M, int N, int K, const Epi& E, lds_t* lds) {
;     ...
;     for (int t = 0; t < nt; t += 2) {
;       const bool last = (t == nt - 2);
;       const char* a1 = cA + (size_t)(t + 1) * kstep;
;       const char* a2 = last ? nA : cA + (size_t)(t + 2) * kstep; const char* b2 = last ? nB : cB + (size_t)(t + 2) * kstep;
;       const char* a3 = a2 + kstep; const char* b3 = b2 + kstep;
;       if constexpr (SP2) {
;         LDB(B0, 0, 0); LDB(B1, 0, 1); SCHED; LDA(At, 0, 0); STAGE(SA(1, 1), a1 + hstep);
;         WAIT_V(8); WAIT_L(0); BAR; MMA(0, 0, At, B0); MMA(0, 1, At, B1); BAR; SCHED;
;         LDA(At, 0, 1); STAGEB(SB(0, 0), b2); STAGEB(SB(0, 1), b2 + bstep); STAGE(SA(0, 0), a2);
;         WAIT_V(8); WAIT_L(0); BAR; MMA(1, 0, At, B0); MMA(1, 1, At, B1); BAR; SCHED;
.LBB0_551:
	ds_read_b128 v[152:155], v148
	ds_read_b128 v[156:159], v148 offset:1024
	ds_read_b128 v[160:163], v148 offset:2048
	ds_read_b128 v[164:167], v148 offset:3072
	ds_read_b128 v[168:171], v149
	ds_read_b128 v[172:175], v149 offset:1024
	ds_read_b128 v[176:179], v149 offset:2048
	ds_read_b128 v[180:183], v149 offset:3072
	s_add_u32 s35, s60, 0xfffc0080
	s_addc_u32 s37, s61, -1
	s_cmp_eq_u32 s34, 12
	s_cselect_b32 s65, s0, s37
	s_cselect_b32 s64, s1, s35
	s_cselect_b32 s63, s21, s33
	s_cselect_b32 s62, s22, s23
	v_lshl_add_u64 v[140:141], s[60:61], 0, v[136:137]
	s_add_i32 m0, s3, 0xc000
	ds_read_b128 v[184:187], v150
	ds_read_b128 v[188:191], v150 offset:1024
	ds_read_b128 v[192:195], v150 offset:2048
	ds_read_b128 v[196:199], v150 offset:3072
	ds_read_b128 v[200:203], v150 offset:4096
	ds_read_b128 v[204:207], v150 offset:5120
	ds_read_b128 v[208:211], v150 offset:6144
	ds_read_b128 v[216:219], v150 offset:7168
	global_load_lds_dwordx4 v[140:141], off
	v_lshl_add_u64 v[140:141], s[60:61], 0, v[138:139]
	s_add_i32 m0, s3, 0xe000
	s_nop 0
	global_load_lds_dwordx4 v[140:141], off
	s_waitcnt vmcnt(8)
	s_waitcnt lgkmcnt(0)
	s_barrier
	s_setprio 0
	s_waitcnt lgkmcnt(0)
	v_mfma_f32_16x16x32_bf16 v[124:127], v[152:155], v[184:187], v[124:127]
	v_mfma_f32_16x16x32_bf16 v[120:123], v[160:163], v[184:187], v[120:123]
	v_mfma_f32_16x16x32_bf16 v[108:111], v[152:155], v[192:195], v[108:111]
	v_mfma_f32_16x16x32_bf16 v[104:107], v[160:163], v[192:195], v[104:107]
	v_mfma_f32_16x16x32_bf16 v[92:95], v[152:155], v[200:203], v[92:95]
	v_mfma_f32_16x16x32_bf16 v[88:91], v[160:163], v[200:203], v[88:91]
	v_mfma_f32_16x16x32_bf16 v[76:79], v[152:155], v[208:211], v[76:79]
	v_mfma_f32_16x16x32_bf16 v[72:75], v[160:163], v[208:211], v[72:75]
	v_mfma_f32_16x16x32_bf16 v[124:127], v[156:159], v[188:191], v[124:127]
	v_mfma_f32_16x16x32_bf16 v[120:123], v[164:167], v[188:191], v[120:123]
	v_mfma_f32_16x16x32_bf16 v[108:111], v[156:159], v[196:199], v[108:111]
	v_mfma_f32_16x16x32_bf16 v[104:107], v[164:167], v[196:199], v[104:107]
	v_mfma_f32_16x16x32_bf16 v[92:95], v[156:159], v[204:207], v[92:95]
	v_mfma_f32_16x16x32_bf16 v[88:91], v[164:167], v[204:207], v[88:91]
	v_mfma_f32_16x16x32_bf16 v[76:79], v[156:159], v[216:219], v[76:79]
	v_mfma_f32_16x16x32_bf16 v[72:75], v[164:167], v[216:219], v[72:75]
	s_setprio 1
	s_setprio 0
	v_mfma_f32_16x16x32_bf16 v[116:119], v[168:171], v[184:187], v[116:119]
	v_mfma_f32_16x16x32_bf16 v[112:115], v[176:179], v[184:187], v[112:115]
	v_mfma_f32_16x16x32_bf16 v[100:103], v[168:171], v[192:195], v[100:103]
	v_mfma_f32_16x16x32_bf16 v[96:99], v[176:179], v[192:195], v[96:99]
	v_mfma_f32_16x16x32_bf16 v[84:87], v[168:171], v[200:203], v[84:87]
	v_mfma_f32_16x16x32_bf16 v[80:83], v[176:179], v[200:203], v[80:83]
	v_mfma_f32_16x16x32_bf16 v[68:71], v[168:171], v[208:211], v[68:71]
	v_mfma_f32_16x16x32_bf16 v[64:67], v[176:179], v[208:211], v[64:67]
	v_mfma_f32_16x16x32_bf16 v[116:119], v[172:175], v[188:191], v[116:119]
	v_mfma_f32_16x16x32_bf16 v[112:115], v[180:183], v[188:191], v[112:115]
	v_mfma_f32_16x16x32_bf16 v[100:103], v[172:175], v[196:199], v[100:103]
	v_mfma_f32_16x16x32_bf16 v[96:99], v[180:183], v[196:199], v[96:99]
	v_mfma_f32_16x16x32_bf16 v[84:87], v[172:175], v[204:207], v[84:87]
	v_mfma_f32_16x16x32_bf16 v[80:83], v[180:183], v[204:207], v[80:83]
	v_mfma_f32_16x16x32_bf16 v[68:71], v[172:175], v[216:219], v[68:71]
	v_mfma_f32_16x16x32_bf16 v[64:67], v[180:183], v[216:219], v[64:67]
	s_setprio 1
	s_barrier
	s_add_i32 s35, s18, s2
	v_lshl_add_u64 v[140:141], s[62:63], 0, v[130:131]
	s_mov_b32 m0, s35
	ds_read_b128 v[184:187], v150 offset:16384
	ds_read_b128 v[188:191], v150 offset:17408
	ds_read_b128 v[192:195], v150 offset:18432
	ds_read_b128 v[196:199], v150 offset:19456
	ds_read_b128 v[200:203], v150 offset:20480
	ds_read_b128 v[204:207], v150 offset:21504
	ds_read_b128 v[208:211], v150 offset:22528
	ds_read_b128 v[216:219], v150 offset:23552
	global_load_lds_dwordx4 v[140:141], off
	s_add_i32 m0, s35, 0x2000
	s_add_u32 s66, s62, 0x10000
	v_lshl_add_u64 v[220:221], s[62:63], 0, v[134:135]
	s_addc_u32 s67, s63, 0
	s_add_i32 s35, s19, s2
	global_load_lds_dwordx4 v[220:221], off
	v_lshl_add_u64 v[222:223], s[66:67], 0, v[130:131]
	s_mov_b32 m0, s35
	v_lshl_add_u64 v[224:225], s[64:65], 0, v[132:133]
	global_load_lds_dwordx4 v[222:223], off
	v_lshl_add_u64 v[222:223], s[66:67], 0, v[134:135]
	s_add_i32 m0, s35, 0x2000
	s_nop 0
	global_load_lds_dwordx4 v[222:223], off
	v_lshl_add_u64 v[222:223], s[64:65], 0, v[128:129]
	s_mov_b32 m0, s3
	s_nop 0
	global_load_lds_dwordx4 v[222:223], off
	s_mov_b32 m0, s8
	s_nop 0
	global_load_lds_dwordx4 v[224:225], off
	s_waitcnt vmcnt(8)
	s_waitcnt lgkmcnt(0)
	s_barrier
; #define STAGE(bufoff, gbase) STAGE_(bufoff, gbase, voffA)
; #define LDA(dst, b, h) do { _Pragma("unroll") for (int m = 0; m < 4; ++m) _Pragma("unroll") for (int k = 0; k < 2; ++k) dst[m][k] = *LDSP(const bf16x8, lds + SA(b, h) + aoff + m * 2048 + k * 1024); } while (0)
; #define LDB(dst, b, h) do { _Pragma("unroll") for (int n = 0; n < 2; ++n) _Pragma("unroll") for (int k = 0; k < 2; ++k) dst[n][k] = *LDSP(const bf16x8, lds + SB(b, h) + boff + n * 2048 + k * 1024); } while (0)
; #define MMA(ai, bj, AT, BT) do { __builtin_amdgcn_s_setprio(1); \
;     _Pragma("unroll") for (int m = 0; m < 4; ++m) _Pragma("unroll") for (int n = 0; n < 2; ++n) _Pragma("unroll") for (int k = 0; k < 2; ++k) \
;       acc[ai][bj][m][n] = __builtin_amdgcn_mfma_f32_16x16x32_bf16(BT[n][k], AT[m][k], acc[ai][bj][m][n], 0, 0, 0); \
;     __builtin_amdgcn_s_setprio(0); } while (0)
; #define WAIT_V(n) asm volatile("s_waitcnt vmcnt(" #n ")" ::: "memory")
; #define WAIT_L(n) asm volatile("s_waitcnt lgkmcnt(" #n ")" ::: "memory")
; #define BAR __builtin_amdgcn_s_barrier()
; #define SCHED __builtin_amdgcn_sched_barrier(0)
; #define WAIT_V(n) asm volatile("s_waitcnt vmcnt(" #n ")" ::: "memory")
; #define BAR do { __builtin_amdgcn_sched_barrier(0); __builtin_amdgcn_s_barrier(); asm volatile("" ::: "memory"); __builtin_amdgcn_sched_barrier(0); } while (0)
; template <bool SP2, bool ALIGN_EPI, bool DUAL, class Epi> DI void gemm_phase2(const bf16_t* A, const bf16_t* Bt, const bf16_t* A2, const bf16_t* Bt2, int M, int N, int K, const Epi& E, lds_t* lds) {
;     ...
;         WAIT_V(8); WAIT_L(0); BAR; MMA(1, 0, At, B0); MMA(1, 1, At, B1); BAR; SCHED;
;         LDB(B0, 1, 0); LDB(B1, 1, 1); SCHED; LDA(At, 1, 0); STAGE(SA(0, 1), a2 + hstep);
;         WAIT_V(8); WAIT_L(0); BAR; MMA(0, 0, At, B0); MMA(0, 1, At, B1); BAR; SCHED;
	s_setprio 0
	s_waitcnt lgkmcnt(0)
	v_mfma_f32_16x16x32_bf16 v[60:63], v[152:155], v[184:187], v[60:63]
	v_mfma_f32_16x16x32_bf16 v[56:59], v[160:163], v[184:187], v[56:59]
	v_mfma_f32_16x16x32_bf16 v[44:47], v[152:155], v[192:195], v[44:47]
	v_mfma_f32_16x16x32_bf16 v[40:43], v[160:163], v[192:195], v[40:43]
	v_mfma_f32_16x16x32_bf16 v[28:31], v[152:155], v[200:203], v[28:31]
	v_mfma_f32_16x16x32_bf16 v[24:27], v[160:163], v[200:203], v[24:27]
	v_mfma_f32_16x16x32_bf16 v[12:15], v[152:155], v[208:211], v[12:15]
	v_mfma_f32_16x16x32_bf16 v[8:11], v[160:163], v[208:211], v[8:11]
	v_mfma_f32_16x16x32_bf16 v[60:63], v[156:159], v[188:191], v[60:63]
	v_mfma_f32_16x16x32_bf16 v[56:59], v[164:167], v[188:191], v[56:59]
	v_mfma_f32_16x16x32_bf16 v[44:47], v[156:159], v[196:199], v[44:47]
	v_mfma_f32_16x16x32_bf16 v[40:43], v[164:167], v[196:199], v[40:43]
	v_mfma_f32_16x16x32_bf16 v[28:31], v[156:159], v[204:207], v[28:31]
	v_mfma_f32_16x16x32_bf16 v[24:27], v[164:167], v[204:207], v[24:27]
	v_mfma_f32_16x16x32_bf16 v[12:15], v[156:159], v[216:219], v[12:15]
	v_mfma_f32_16x16x32_bf16 v[8:11], v[164:167], v[216:219], v[8:11]
	s_setprio 1
	s_setprio 0
	v_mfma_f32_16x16x32_bf16 v[52:55], v[168:171], v[184:187], v[52:55]
	v_mfma_f32_16x16x32_bf16 v[48:51], v[176:179], v[184:187], v[48:51]
	v_mfma_f32_16x16x32_bf16 v[36:39], v[168:171], v[192:195], v[36:39]
	v_mfma_f32_16x16x32_bf16 v[32:35], v[176:179], v[192:195], v[32:35]
	v_mfma_f32_16x16x32_bf16 v[20:23], v[168:171], v[200:203], v[20:23]
	v_mfma_f32_16x16x32_bf16 v[16:19], v[176:179], v[200:203], v[16:19]
	v_mfma_f32_16x16x32_bf16 v[4:7], v[168:171], v[208:211], v[4:7]
	v_mfma_f32_16x16x32_bf16 v[0:3], v[176:179], v[208:211], v[0:3]
	v_mfma_f32_16x16x32_bf16 v[52:55], v[172:175], v[188:191], v[52:55]
	v_mfma_f32_16x16x32_bf16 v[48:51], v[180:183], v[188:191], v[48:51]
	v_mfma_f32_16x16x32_bf16 v[36:39], v[172:175], v[196:199], v[36:39]
	v_mfma_f32_16x16x32_bf16 v[32:35], v[180:183], v[196:199], v[32:35]
	v_mfma_f32_16x16x32_bf16 v[20:23], v[172:175], v[204:207], v[20:23]
	v_mfma_f32_16x16x32_bf16 v[16:19], v[180:183], v[204:207], v[16:19]
	v_mfma_f32_16x16x32_bf16 v[4:7], v[172:175], v[216:219], v[4:7]
	v_mfma_f32_16x16x32_bf16 v[0:3], v[180:183], v[216:219], v[0:3]
	s_setprio 1
	s_barrier
	s_add_i32 s35, 0, 0x18000
	s_add_i32 s37, 0, 0x1c000
	v_add_u32_e32 v164, s35, v143
	v_add_u32_e32 v180, s37, v143
	ds_read_b128 v[152:155], v164
	ds_read_b128 v[156:159], v164 offset:1024
	ds_read_b128 v[160:163], v164 offset:2048
	ds_read_b128 v[164:167], v164 offset:3072
	ds_read_b128 v[168:171], v180
	ds_read_b128 v[172:175], v180 offset:1024
	ds_read_b128 v[176:179], v180 offset:2048
	ds_read_b128 v[180:183], v180 offset:3072
	s_add_u32 s64, s64, 0x40000
	s_addc_u32 s65, s65, 0
	s_mov_b32 m0, s9
	v_lshl_add_u64 v[226:227], s[64:65], 0, v[128:129]
	ds_read_b128 v[184:187], v150 offset:32768
	ds_read_b128 v[188:191], v150 offset:33792
	ds_read_b128 v[192:195], v150 offset:34816
	ds_read_b128 v[196:199], v150 offset:35840
	ds_read_b128 v[200:203], v150 offset:36864
	ds_read_b128 v[204:207], v150 offset:37888
	ds_read_b128 v[208:211], v150 offset:38912
	ds_read_b128 v[216:219], v150 offset:39936
	global_load_lds_dwordx4 v[226:227], off
	v_lshl_add_u64 v[226:227], s[64:65], 0, v[132:133]
	s_mov_b32 m0, s10
	s_nop 0
	global_load_lds_dwordx4 v[226:227], off
	s_waitcnt vmcnt(8)
	s_waitcnt lgkmcnt(0)
	s_barrier
	s_setprio 0
	s_waitcnt lgkmcnt(0)
	v_mfma_f32_16x16x32_bf16 v[124:127], v[152:155], v[184:187], v[124:127]
	v_mfma_f32_16x16x32_bf16 v[120:123], v[160:163], v[184:187], v[120:123]
	v_mfma_f32_16x16x32_bf16 v[108:111], v[152:155], v[192:195], v[108:111]
	v_mfma_f32_16x16x32_bf16 v[104:107], v[160:163], v[192:195], v[104:107]
	v_mfma_f32_16x16x32_bf16 v[92:95], v[152:155], v[200:203], v[92:95]
	v_mfma_f32_16x16x32_bf16 v[88:91], v[160:163], v[200:203], v[88:91]
	v_mfma_f32_16x16x32_bf16 v[76:79], v[152:155], v[208:211], v[76:79]
	v_mfma_f32_16x16x32_bf16 v[72:75], v[160:163], v[208:211], v[72:75]
	v_mfma_f32_16x16x32_bf16 v[124:127], v[156:159], v[188:191], v[124:127]
	v_mfma_f32_16x16x32_bf16 v[120:123], v[164:167], v[188:191], v[120:123]
	v_mfma_f32_16x16x32_bf16 v[108:111], v[156:159], v[196:199], v[108:111]
	v_mfma_f32_16x16x32_bf16 v[104:107], v[164:167], v[196:199], v[104:107]
	v_mfma_f32_16x16x32_bf16 v[92:95], v[156:159], v[204:207], v[92:95]
	v_mfma_f32_16x16x32_bf16 v[88:91], v[164:167], v[204:207], v[88:91]
	v_mfma_f32_16x16x32_bf16 v[76:79], v[156:159], v[216:219], v[76:79]
	v_mfma_f32_16x16x32_bf16 v[72:75], v[164:167], v[216:219], v[72:75]
	s_setprio 1
	s_setprio 0
	v_mfma_f32_16x16x32_bf16 v[116:119], v[168:171], v[184:187], v[116:119]
	v_mfma_f32_16x16x32_bf16 v[112:115], v[176:179], v[184:187], v[112:115]
	v_mfma_f32_16x16x32_bf16 v[100:103], v[168:171], v[192:195], v[100:103]
	v_mfma_f32_16x16x32_bf16 v[96:99], v[176:179], v[192:195], v[96:99]
	v_mfma_f32_16x16x32_bf16 v[84:87], v[168:171], v[200:203], v[84:87]
	v_mfma_f32_16x16x32_bf16 v[80:83], v[176:179], v[200:203], v[80:83]
	v_mfma_f32_16x16x32_bf16 v[68:71], v[168:171], v[208:211], v[68:71]
	v_mfma_f32_16x16x32_bf16 v[64:67], v[176:179], v[208:211], v[64:67]
	v_mfma_f32_16x16x32_bf16 v[116:119], v[172:175], v[188:191], v[116:119]
	v_mfma_f32_16x16x32_bf16 v[112:115], v[180:183], v[188:191], v[112:115]
	v_mfma_f32_16x16x32_bf16 v[100:103], v[172:175], v[196:199], v[100:103]
	v_mfma_f32_16x16x32_bf16 v[96:99], v[180:183], v[196:199], v[96:99]
	v_mfma_f32_16x16x32_bf16 v[84:87], v[172:175], v[204:207], v[84:87]
	v_mfma_f32_16x16x32_bf16 v[80:83], v[180:183], v[204:207], v[80:83]
	v_mfma_f32_16x16x32_bf16 v[68:71], v[172:175], v[216:219], v[68:71]
	v_mfma_f32_16x16x32_bf16 v[64:67], v[180:183], v[216:219], v[64:67]
	s_setprio 1
	s_barrier
; #define STAGE(bufoff, gbase) STAGE_(bufoff, gbase, voffA)
; #define STAGEB(bufoff, gbase) STAGE_(bufoff, gbase, voffB)
; #define LDA(dst, b, h) do { _Pragma("unroll") for (int m = 0; m < 4; ++m) _Pragma("unroll") for (int k = 0; k < 2; ++k) dst[m][k] = *LDSP(const bf16x8, lds + SA(b, h) + aoff + m * 2048 + k * 1024); } while (0)
; #define MMA(ai, bj, AT, BT) do { __builtin_amdgcn_s_setprio(1); \
;     _Pragma("unroll") for (int m = 0; m < 4; ++m) _Pragma("unroll") for (int n = 0; n < 2; ++n) _Pragma("unroll") for (int k = 0; k < 2; ++k) \
;       acc[ai][bj][m][n] = __builtin_amdgcn_mfma_f32_16x16x32_bf16(BT[n][k], AT[m][k], acc[ai][bj][m][n], 0, 0, 0); \
;     __builtin_amdgcn_s_setprio(0); } while (0)
; #define WAIT_V(n) asm volatile("s_waitcnt vmcnt(" #n ")" ::: "memory")
; #define WAIT_L(n) asm volatile("s_waitcnt lgkmcnt(" #n ")" ::: "memory")
; #define BAR __builtin_amdgcn_s_barrier()
; #define SCHED __builtin_amdgcn_sched_barrier(0)
; #define WAIT_V(n) asm volatile("s_waitcnt vmcnt(" #n ")" ::: "memory")
; #define BAR do { __builtin_amdgcn_sched_barrier(0); __builtin_amdgcn_s_barrier(); asm volatile("" ::: "memory"); __builtin_amdgcn_sched_barrier(0); } while (0)
; template <bool SP2, bool ALIGN_EPI, bool DUAL, class Epi> DI void gemm_phase2(const bf16_t* A, const bf16_t* Bt, const bf16_t* A2, const bf16_t* Bt2, int M, int N, int K, const Epi& E, lds_t* lds) {
;     ...
;     for (int t = 0; t < nt; t += 2) {
;       const bool last = (t == nt - 2);
;       const char* a1 = cA + (size_t)(t + 1) * kstep;
;       const char* a2 = last ? nA : cA + (size_t)(t + 2) * kstep; const char* b2 = last ? nB : cB + (size_t)(t + 2) * kstep;
;       const char* a3 = a2 + kstep; const char* b3 = b2 + kstep;
;     ...
;         LDA(At, 1, 1); STAGEB(SB(1, 0), b3); STAGEB(SB(1, 1), b3 + bstep); STAGE(SA(1, 0), a3);
;         WAIT_V(8); WAIT_L(0); BAR; MMA(1, 0, At, B0); MMA(1, 1, At, B1); BAR; SCHED;
	s_add_i32 s35, s35, s2
	v_lshl_add_u64 v[140:141], v[140:141], 0, s[30:31]
	s_mov_b32 m0, s35
	ds_read_b128 v[184:187], v150 offset:49152
	ds_read_b128 v[188:191], v150 offset:50176
	ds_read_b128 v[192:195], v150 offset:51200
	ds_read_b128 v[196:199], v150 offset:52224
	ds_read_b128 v[200:203], v150 offset:53248
	ds_read_b128 v[204:207], v150 offset:54272
	ds_read_b128 v[208:211], v150 offset:55296
	ds_read_b128 v[216:219], v150 offset:56320
	global_load_lds_dwordx4 v[140:141], off
	s_add_i32 m0, s35, 0x2000
	s_add_u32 s62, s62, 0x10080
	v_lshl_add_u64 v[140:141], v[220:221], 0, s[30:31]
	s_addc_u32 s63, s63, 0
	s_add_i32 s35, s37, s2
	global_load_lds_dwordx4 v[140:141], off
	v_lshl_add_u64 v[140:141], s[62:63], 0, v[130:131]
	s_mov_b32 m0, s35
	s_nop 0
	global_load_lds_dwordx4 v[140:141], off
	v_lshl_add_u64 v[140:141], s[62:63], 0, v[134:135]
	s_add_i32 m0, s35, 0x2000
	s_nop 0
	global_load_lds_dwordx4 v[140:141], off
	v_lshl_add_u64 v[140:141], v[222:223], 0, s[30:31]
	s_mov_b32 m0, s14
	s_nop 0
	global_load_lds_dwordx4 v[140:141], off
	v_lshl_add_u64 v[140:141], v[224:225], 0, s[30:31]
	s_mov_b32 m0, s15
	s_nop 0
	global_load_lds_dwordx4 v[140:141], off
	s_waitcnt vmcnt(8)
	s_waitcnt lgkmcnt(0)
	s_barrier
	s_setprio 0
	s_waitcnt lgkmcnt(0)
	v_mfma_f32_16x16x32_bf16 v[60:63], v[152:155], v[184:187], v[60:63]
	v_mfma_f32_16x16x32_bf16 v[56:59], v[160:163], v[184:187], v[56:59]
	v_mfma_f32_16x16x32_bf16 v[44:47], v[152:155], v[192:195], v[44:47]
	v_mfma_f32_16x16x32_bf16 v[40:43], v[160:163], v[192:195], v[40:43]
	v_mfma_f32_16x16x32_bf16 v[28:31], v[152:155], v[200:203], v[28:31]
	v_mfma_f32_16x16x32_bf16 v[24:27], v[160:163], v[200:203], v[24:27]
	v_mfma_f32_16x16x32_bf16 v[12:15], v[152:155], v[208:211], v[12:15]
	v_mfma_f32_16x16x32_bf16 v[8:11], v[160:163], v[208:211], v[8:11]
	v_mfma_f32_16x16x32_bf16 v[60:63], v[156:159], v[188:191], v[60:63]
	v_mfma_f32_16x16x32_bf16 v[56:59], v[164:167], v[188:191], v[56:59]
	v_mfma_f32_16x16x32_bf16 v[44:47], v[156:159], v[196:199], v[44:47]
	v_mfma_f32_16x16x32_bf16 v[40:43], v[164:167], v[196:199], v[40:43]
	v_mfma_f32_16x16x32_bf16 v[28:31], v[156:159], v[204:207], v[28:31]
	v_mfma_f32_16x16x32_bf16 v[24:27], v[164:167], v[204:207], v[24:27]
	v_mfma_f32_16x16x32_bf16 v[12:15], v[156:159], v[216:219], v[12:15]
	v_mfma_f32_16x16x32_bf16 v[8:11], v[164:167], v[216:219], v[8:11]
	s_setprio 1
	s_setprio 0
	v_mfma_f32_16x16x32_bf16 v[52:55], v[168:171], v[184:187], v[52:55]
	v_mfma_f32_16x16x32_bf16 v[48:51], v[176:179], v[184:187], v[48:51]
	v_mfma_f32_16x16x32_bf16 v[36:39], v[168:171], v[192:195], v[36:39]
	v_mfma_f32_16x16x32_bf16 v[32:35], v[176:179], v[192:195], v[32:35]
	v_mfma_f32_16x16x32_bf16 v[20:23], v[168:171], v[200:203], v[20:23]
	v_mfma_f32_16x16x32_bf16 v[16:19], v[176:179], v[200:203], v[16:19]
	v_mfma_f32_16x16x32_bf16 v[4:7], v[168:171], v[208:211], v[4:7]
	v_mfma_f32_16x16x32_bf16 v[0:3], v[176:179], v[208:211], v[0:3]
	v_mfma_f32_16x16x32_bf16 v[52:55], v[172:175], v[188:191], v[52:55]
	v_mfma_f32_16x16x32_bf16 v[48:51], v[180:183], v[188:191], v[48:51]
	v_mfma_f32_16x16x32_bf16 v[36:39], v[172:175], v[196:199], v[36:39]
	v_mfma_f32_16x16x32_bf16 v[32:35], v[180:183], v[196:199], v[32:35]
	v_mfma_f32_16x16x32_bf16 v[20:23], v[172:175], v[204:207], v[20:23]
	v_mfma_f32_16x16x32_bf16 v[16:19], v[180:183], v[204:207], v[16:19]
	v_mfma_f32_16x16x32_bf16 v[4:7], v[172:175], v[216:219], v[4:7]
	v_mfma_f32_16x16x32_bf16 v[0:3], v[180:183], v[216:219], v[0:3]
	s_setprio 1
	s_barrier
	s_add_i32 s34, s34, 2
	s_add_u32 s60, s60, 0x100
	s_addc_u32 s61, s61, 0
	s_add_u32 s23, s23, 0x100
	s_addc_u32 s33, s33, 0
	s_cmp_gt_u32 s34, 13
	s_cbranch_scc0 .LBB0_551
	s_and_b64 vcc, exec, s[38:39]
	s_cbranch_vccz .LBB0_554
	s_barrier

; #define STAGE(bufoff, gbase) STAGE_(bufoff, gbase, voffA)
; #define STAGEB(bufoff, gbase) STAGE_(bufoff, gbase, voffB)
; #define LDA(dst, b, h) do { _Pragma("unroll") for (int m = 0; m < 4; ++m) _Pragma("unroll") for (int k = 0; k < 2; ++k) dst[m][k] = *LDSP(const bf16x8, lds + SA(b, h) + aoff + m * 2048 + k * 1024); } while (0)
; #define LDB(dst, b, h) do { _Pragma("unroll") for (int n = 0; n < 2; ++n) _Pragma("unroll") for (int k = 0; k < 2; ++k) dst[n][k] = *LDSP(const bf16x8, lds + SB(b, h) + boff + n * 2048 + k * 1024); } while (0)
; #define MMA(ai, bj, AT, BT) do { __builtin_amdgcn_s_setprio(1); \
;     _Pragma("unroll") for (int m = 0; m < 4; ++m) _Pragma("unroll") for (int n = 0; n < 2; ++n) _Pragma("unroll") for (int k = 0; k < 2; ++k) \
;       acc[ai][bj][m][n] = __builtin_amdgcn_mfma_f32_16x16x32_bf16(BT[n][k], AT[m][k], acc[ai][bj][m][n], 0, 0, 0); \
;     __builtin_amdgcn_s_setprio(0); } while (0)
; #define WAIT_V(n) asm volatile("s_waitcnt vmcnt(" #n ")" ::: "memory")
; #define WAIT_L(n) asm volatile("s_waitcnt lgkmcnt(" #n ")" ::: "memory")
; #define BAR __builtin_amdgcn_s_barrier()
; #define SCHED __builtin_amdgcn_sched_barrier(0)
; #define WAIT_V(n) asm volatile("s_waitcnt vmcnt(" #n ")" ::: "memory")
; #define BAR do { __builtin_amdgcn_sched_barrier(0); __builtin_amdgcn_s_barrier(); asm volatile("" ::: "memory"); __builtin_amdgcn_sched_barrier(0); } while (0)
; template <bool SP2, bool ALIGN_EPI, bool DUAL, class Epi> DI void gemm_phase2(const bf16_t* A, const bf16_t* Bt, const bf16_t* A2, const bf16_t* Bt2, int M, int N, int K, const Epi& E, lds_t* lds) {
;     ...
;     for (int t = 0; t < nt; t += 2) {
;       const bool last = (t == nt - 2);
;       const char* a1 = cA + (size_t)(t + 1) * kstep;
;       const char* a2 = last ? nA : cA + (size_t)(t + 2) * kstep; const char* b2 = last ? nB : cB + (size_t)(t + 2) * kstep;
;       const char* a3 = a2 + kstep; const char* b3 = b2 + kstep;
;       if constexpr (SP2) {
;         LDB(B0, 0, 0); LDB(B1, 0, 1); SCHED; LDA(At, 0, 0); STAGE(SA(1, 1), a1 + hstep);
;         WAIT_V(8); WAIT_L(0); BAR; MMA(0, 0, At, B0); MMA(0, 1, At, B1); BAR; SCHED;
;         LDA(At, 0, 1); STAGEB(SB(0, 0), b2); STAGEB(SB(0, 1), b2 + bstep); STAGE(SA(0, 0), a2);
;         WAIT_V(8); WAIT_L(0); BAR; MMA(1, 0, At, B0); MMA(1, 1, At, B1); BAR; SCHED;
.LBB0_620:
	ds_read_b128 v[150:153], v146
	ds_read_b128 v[154:157], v146 offset:1024
	ds_read_b128 v[158:161], v146 offset:2048
	ds_read_b128 v[162:165], v146 offset:3072
	ds_read_b128 v[166:169], v147
	ds_read_b128 v[170:173], v147 offset:1024
	ds_read_b128 v[174:177], v147 offset:2048
	ds_read_b128 v[178:181], v147 offset:3072
	s_add_u32 s47, s52, 0xfffc0080
	s_addc_u32 s54, s53, -1
	s_cmp_eq_u32 s37, 12
	s_cselect_b32 s57, s1, s54
	s_cselect_b32 s56, s23, s47
	s_cselect_b32 s55, s29, s35
	s_cselect_b32 s54, s33, s34
	v_lshl_add_u64 v[210:211], s[52:53], 0, v[136:137]
	s_add_i32 m0, s3, 0xc000
	ds_read_b128 v[182:185], v148
	ds_read_b128 v[186:189], v148 offset:1024
	ds_read_b128 v[190:193], v148 offset:2048
	ds_read_b128 v[194:197], v148 offset:3072
	ds_read_b128 v[198:201], v148 offset:4096
	ds_read_b128 v[202:205], v148 offset:5120
	ds_read_b128 v[206:209], v148 offset:6144
	ds_read_b128 v[216:219], v148 offset:7168
	global_load_lds_dwordx4 v[210:211], off
	v_lshl_add_u64 v[210:211], s[52:53], 0, v[138:139]
	s_add_i32 m0, s3, 0xe000
	s_nop 0
	global_load_lds_dwordx4 v[210:211], off
	s_waitcnt vmcnt(8)
	s_waitcnt lgkmcnt(0)
	s_barrier
	s_setprio 0
	s_waitcnt lgkmcnt(0)
	v_mfma_f32_16x16x32_bf16 v[124:127], v[150:153], v[182:185], v[124:127]
	v_mfma_f32_16x16x32_bf16 v[120:123], v[158:161], v[182:185], v[120:123]
	v_mfma_f32_16x16x32_bf16 v[108:111], v[150:153], v[190:193], v[108:111]
	v_mfma_f32_16x16x32_bf16 v[104:107], v[158:161], v[190:193], v[104:107]
	v_mfma_f32_16x16x32_bf16 v[92:95], v[150:153], v[198:201], v[92:95]
	v_mfma_f32_16x16x32_bf16 v[88:91], v[158:161], v[198:201], v[88:91]
	v_mfma_f32_16x16x32_bf16 v[76:79], v[150:153], v[206:209], v[76:79]
	v_mfma_f32_16x16x32_bf16 v[72:75], v[158:161], v[206:209], v[72:75]
	v_mfma_f32_16x16x32_bf16 v[124:127], v[154:157], v[186:189], v[124:127]
	v_mfma_f32_16x16x32_bf16 v[120:123], v[162:165], v[186:189], v[120:123]
	v_mfma_f32_16x16x32_bf16 v[108:111], v[154:157], v[194:197], v[108:111]
	v_mfma_f32_16x16x32_bf16 v[104:107], v[162:165], v[194:197], v[104:107]
	v_mfma_f32_16x16x32_bf16 v[92:95], v[154:157], v[202:205], v[92:95]
	v_mfma_f32_16x16x32_bf16 v[88:91], v[162:165], v[202:205], v[88:91]
	v_mfma_f32_16x16x32_bf16 v[76:79], v[154:157], v[216:219], v[76:79]
	v_mfma_f32_16x16x32_bf16 v[72:75], v[162:165], v[216:219], v[72:75]
	s_setprio 1
	s_setprio 0
	v_mfma_f32_16x16x32_bf16 v[116:119], v[166:169], v[182:185], v[116:119]
	v_mfma_f32_16x16x32_bf16 v[112:115], v[174:177], v[182:185], v[112:115]
	v_mfma_f32_16x16x32_bf16 v[100:103], v[166:169], v[190:193], v[100:103]
	v_mfma_f32_16x16x32_bf16 v[96:99], v[174:177], v[190:193], v[96:99]
	v_mfma_f32_16x16x32_bf16 v[84:87], v[166:169], v[198:201], v[84:87]
	v_mfma_f32_16x16x32_bf16 v[80:83], v[174:177], v[198:201], v[80:83]
	v_mfma_f32_16x16x32_bf16 v[68:71], v[166:169], v[206:209], v[68:71]
	v_mfma_f32_16x16x32_bf16 v[64:67], v[174:177], v[206:209], v[64:67]
	v_mfma_f32_16x16x32_bf16 v[116:119], v[170:173], v[186:189], v[116:119]
	v_mfma_f32_16x16x32_bf16 v[112:115], v[178:181], v[186:189], v[112:115]
	v_mfma_f32_16x16x32_bf16 v[100:103], v[170:173], v[194:197], v[100:103]
	v_mfma_f32_16x16x32_bf16 v[96:99], v[178:181], v[194:197], v[96:99]
	v_mfma_f32_16x16x32_bf16 v[84:87], v[170:173], v[202:205], v[84:87]
	v_mfma_f32_16x16x32_bf16 v[80:83], v[178:181], v[202:205], v[80:83]
	v_mfma_f32_16x16x32_bf16 v[68:71], v[170:173], v[216:219], v[68:71]
	v_mfma_f32_16x16x32_bf16 v[64:67], v[178:181], v[216:219], v[64:67]
	s_setprio 1
	s_barrier
	s_add_i32 s47, s19, s2
	v_lshl_add_u64 v[210:211], s[54:55], 0, v[132:133]
	s_mov_b32 m0, s47
	ds_read_b128 v[182:185], v148 offset:16384
	ds_read_b128 v[186:189], v148 offset:17408
	ds_read_b128 v[190:193], v148 offset:18432
	ds_read_b128 v[194:197], v148 offset:19456
	ds_read_b128 v[198:201], v148 offset:20480
	ds_read_b128 v[202:205], v148 offset:21504
	ds_read_b128 v[206:209], v148 offset:22528
	ds_read_b128 v[216:219], v148 offset:23552
	global_load_lds_dwordx4 v[210:211], off
	s_add_i32 m0, s47, 0x2000
	s_add_u32 s58, s54, 0x10000
	v_lshl_add_u64 v[220:221], s[54:55], 0, v[128:129]
	s_addc_u32 s59, s55, 0
	s_add_i32 s47, s20, s2
	global_load_lds_dwordx4 v[220:221], off
	v_lshl_add_u64 v[222:223], s[58:59], 0, v[132:133]
	s_mov_b32 m0, s47
	v_lshl_add_u64 v[224:225], s[56:57], 0, v[130:131]
	global_load_lds_dwordx4 v[222:223], off
	v_lshl_add_u64 v[222:223], s[58:59], 0, v[128:129]
	s_add_i32 m0, s47, 0x2000
	s_nop 0
	global_load_lds_dwordx4 v[222:223], off
	v_lshl_add_u64 v[222:223], s[56:57], 0, v[134:135]
	s_mov_b32 m0, s3
	s_nop 0
	global_load_lds_dwordx4 v[222:223], off
	s_mov_b32 m0, s8
	s_nop 0
	global_load_lds_dwordx4 v[224:225], off
	s_waitcnt vmcnt(8)
	s_waitcnt lgkmcnt(0)
	s_barrier
; #define STAGE(bufoff, gbase) STAGE_(bufoff, gbase, voffA)
; #define LDA(dst, b, h) do { _Pragma("unroll") for (int m = 0; m < 4; ++m) _Pragma("unroll") for (int k = 0; k < 2; ++k) dst[m][k] = *LDSP(const bf16x8, lds + SA(b, h) + aoff + m * 2048 + k * 1024); } while (0)
; #define LDB(dst, b, h) do { _Pragma("unroll") for (int n = 0; n < 2; ++n) _Pragma("unroll") for (int k = 0; k < 2; ++k) dst[n][k] = *LDSP(const bf16x8, lds + SB(b, h) + boff + n * 2048 + k * 1024); } while (0)
; #define MMA(ai, bj, AT, BT) do { __builtin_amdgcn_s_setprio(1); \
;     _Pragma("unroll") for (int m = 0; m < 4; ++m) _Pragma("unroll") for (int n = 0; n < 2; ++n) _Pragma("unroll") for (int k = 0; k < 2; ++k) \
;       acc[ai][bj][m][n] = __builtin_amdgcn_mfma_f32_16x16x32_bf16(BT[n][k], AT[m][k], acc[ai][bj][m][n], 0, 0, 0); \
;     __builtin_amdgcn_s_setprio(0); } while (0)
; #define WAIT_V(n) asm volatile("s_waitcnt vmcnt(" #n ")" ::: "memory")
; #define WAIT_L(n) asm volatile("s_waitcnt lgkmcnt(" #n ")" ::: "memory")
; #define BAR __builtin_amdgcn_s_barrier()
; #define SCHED __builtin_amdgcn_sched_barrier(0)
; #define WAIT_V(n) asm volatile("s_waitcnt vmcnt(" #n ")" ::: "memory")
; #define BAR do { __builtin_amdgcn_sched_barrier(0); __builtin_amdgcn_s_barrier(); asm volatile("" ::: "memory"); __builtin_amdgcn_sched_barrier(0); } while (0)
; template <bool SP2, bool ALIGN_EPI, bool DUAL, class Epi> DI void gemm_phase2(const bf16_t* A, const bf16_t* Bt, const bf16_t* A2, const bf16_t* Bt2, int M, int N, int K, const Epi& E, lds_t* lds) {
;     ...
;         WAIT_V(8); WAIT_L(0); BAR; MMA(1, 0, At, B0); MMA(1, 1, At, B1); BAR; SCHED;
;         LDB(B0, 1, 0); LDB(B1, 1, 1); SCHED; LDA(At, 1, 0); STAGE(SA(0, 1), a2 + hstep);
;         WAIT_V(8); WAIT_L(0); BAR; MMA(0, 0, At, B0); MMA(0, 1, At, B1); BAR; SCHED;
	s_setprio 0
	s_waitcnt lgkmcnt(0)
	v_mfma_f32_16x16x32_bf16 v[60:63], v[150:153], v[182:185], v[60:63]
	v_mfma_f32_16x16x32_bf16 v[56:59], v[158:161], v[182:185], v[56:59]
	v_mfma_f32_16x16x32_bf16 v[44:47], v[150:153], v[190:193], v[44:47]
	v_mfma_f32_16x16x32_bf16 v[40:43], v[158:161], v[190:193], v[40:43]
	v_mfma_f32_16x16x32_bf16 v[28:31], v[150:153], v[198:201], v[28:31]
	v_mfma_f32_16x16x32_bf16 v[24:27], v[158:161], v[198:201], v[24:27]
	v_mfma_f32_16x16x32_bf16 v[12:15], v[150:153], v[206:209], v[12:15]
	v_mfma_f32_16x16x32_bf16 v[8:11], v[158:161], v[206:209], v[8:11]
	v_mfma_f32_16x16x32_bf16 v[60:63], v[154:157], v[186:189], v[60:63]
	v_mfma_f32_16x16x32_bf16 v[56:59], v[162:165], v[186:189], v[56:59]
	v_mfma_f32_16x16x32_bf16 v[44:47], v[154:157], v[194:197], v[44:47]
	v_mfma_f32_16x16x32_bf16 v[40:43], v[162:165], v[194:197], v[40:43]
	v_mfma_f32_16x16x32_bf16 v[28:31], v[154:157], v[202:205], v[28:31]
	v_mfma_f32_16x16x32_bf16 v[24:27], v[162:165], v[202:205], v[24:27]
	v_mfma_f32_16x16x32_bf16 v[12:15], v[154:157], v[216:219], v[12:15]
	v_mfma_f32_16x16x32_bf16 v[8:11], v[162:165], v[216:219], v[8:11]
	s_setprio 1
	s_setprio 0
	v_mfma_f32_16x16x32_bf16 v[52:55], v[166:169], v[182:185], v[52:55]
	v_mfma_f32_16x16x32_bf16 v[48:51], v[174:177], v[182:185], v[48:51]
	v_mfma_f32_16x16x32_bf16 v[36:39], v[166:169], v[190:193], v[36:39]
	v_mfma_f32_16x16x32_bf16 v[32:35], v[174:177], v[190:193], v[32:35]
	v_mfma_f32_16x16x32_bf16 v[20:23], v[166:169], v[198:201], v[20:23]
	v_mfma_f32_16x16x32_bf16 v[16:19], v[174:177], v[198:201], v[16:19]
	v_mfma_f32_16x16x32_bf16 v[4:7], v[166:169], v[206:209], v[4:7]
	v_mfma_f32_16x16x32_bf16 v[0:3], v[174:177], v[206:209], v[0:3]
	v_mfma_f32_16x16x32_bf16 v[52:55], v[170:173], v[186:189], v[52:55]
	v_mfma_f32_16x16x32_bf16 v[48:51], v[178:181], v[186:189], v[48:51]
	v_mfma_f32_16x16x32_bf16 v[36:39], v[170:173], v[194:197], v[36:39]
	v_mfma_f32_16x16x32_bf16 v[32:35], v[178:181], v[194:197], v[32:35]
	v_mfma_f32_16x16x32_bf16 v[20:23], v[170:173], v[202:205], v[20:23]
	v_mfma_f32_16x16x32_bf16 v[16:19], v[178:181], v[202:205], v[16:19]
	v_mfma_f32_16x16x32_bf16 v[4:7], v[170:173], v[216:219], v[4:7]
	v_mfma_f32_16x16x32_bf16 v[0:3], v[178:181], v[216:219], v[0:3]
	s_setprio 1
	s_barrier
	s_add_i32 s47, 0, 0x18000
	s_add_i32 s58, 0, 0x1c000
	v_add_u32_e32 v162, s47, v141
	v_add_u32_e32 v178, s58, v141
	ds_read_b128 v[150:153], v162
	ds_read_b128 v[154:157], v162 offset:1024
	ds_read_b128 v[158:161], v162 offset:2048
	ds_read_b128 v[162:165], v162 offset:3072
	ds_read_b128 v[166:169], v178
	ds_read_b128 v[170:173], v178 offset:1024
	ds_read_b128 v[174:177], v178 offset:2048
	ds_read_b128 v[178:181], v178 offset:3072
	s_add_u32 s56, s56, 0x40000
	s_addc_u32 s57, s57, 0
	s_mov_b32 m0, s9
	v_lshl_add_u64 v[226:227], s[56:57], 0, v[134:135]
	ds_read_b128 v[182:185], v148 offset:32768
	ds_read_b128 v[186:189], v148 offset:33792
	ds_read_b128 v[190:193], v148 offset:34816
	ds_read_b128 v[194:197], v148 offset:35840
	ds_read_b128 v[198:201], v148 offset:36864
	ds_read_b128 v[202:205], v148 offset:37888
	ds_read_b128 v[206:209], v148 offset:38912
	ds_read_b128 v[216:219], v148 offset:39936
	global_load_lds_dwordx4 v[226:227], off
	v_lshl_add_u64 v[226:227], s[56:57], 0, v[130:131]
	s_mov_b32 m0, s10
	s_nop 0
	global_load_lds_dwordx4 v[226:227], off
	s_waitcnt vmcnt(8)
	s_waitcnt lgkmcnt(0)
	s_barrier
	s_setprio 0
	s_waitcnt lgkmcnt(0)
	v_mfma_f32_16x16x32_bf16 v[124:127], v[150:153], v[182:185], v[124:127]
	v_mfma_f32_16x16x32_bf16 v[120:123], v[158:161], v[182:185], v[120:123]
	v_mfma_f32_16x16x32_bf16 v[108:111], v[150:153], v[190:193], v[108:111]
	v_mfma_f32_16x16x32_bf16 v[104:107], v[158:161], v[190:193], v[104:107]
	v_mfma_f32_16x16x32_bf16 v[92:95], v[150:153], v[198:201], v[92:95]
	v_mfma_f32_16x16x32_bf16 v[88:91], v[158:161], v[198:201], v[88:91]
	v_mfma_f32_16x16x32_bf16 v[76:79], v[150:153], v[206:209], v[76:79]
	v_mfma_f32_16x16x32_bf16 v[72:75], v[158:161], v[206:209], v[72:75]
	v_mfma_f32_16x16x32_bf16 v[124:127], v[154:157], v[186:189], v[124:127]
	v_mfma_f32_16x16x32_bf16 v[120:123], v[162:165], v[186:189], v[120:123]
	v_mfma_f32_16x16x32_bf16 v[108:111], v[154:157], v[194:197], v[108:111]
	v_mfma_f32_16x16x32_bf16 v[104:107], v[162:165], v[194:197], v[104:107]
	v_mfma_f32_16x16x32_bf16 v[92:95], v[154:157], v[202:205], v[92:95]
	v_mfma_f32_16x16x32_bf16 v[88:91], v[162:165], v[202:205], v[88:91]
	v_mfma_f32_16x16x32_bf16 v[76:79], v[154:157], v[216:219], v[76:79]
	v_mfma_f32_16x16x32_bf16 v[72:75], v[162:165], v[216:219], v[72:75]
	s_setprio 1
	s_setprio 0
	v_mfma_f32_16x16x32_bf16 v[116:119], v[166:169], v[182:185], v[116:119]
	v_mfma_f32_16x16x32_bf16 v[112:115], v[174:177], v[182:185], v[112:115]
	v_mfma_f32_16x16x32_bf16 v[100:103], v[166:169], v[190:193], v[100:103]
	v_mfma_f32_16x16x32_bf16 v[96:99], v[174:177], v[190:193], v[96:99]
	v_mfma_f32_16x16x32_bf16 v[84:87], v[166:169], v[198:201], v[84:87]
	v_mfma_f32_16x16x32_bf16 v[80:83], v[174:177], v[198:201], v[80:83]
	v_mfma_f32_16x16x32_bf16 v[68:71], v[166:169], v[206:209], v[68:71]
	v_mfma_f32_16x16x32_bf16 v[64:67], v[174:177], v[206:209], v[64:67]
	v_mfma_f32_16x16x32_bf16 v[116:119], v[170:173], v[186:189], v[116:119]
	v_mfma_f32_16x16x32_bf16 v[112:115], v[178:181], v[186:189], v[112:115]
	v_mfma_f32_16x16x32_bf16 v[100:103], v[170:173], v[194:197], v[100:103]
	v_mfma_f32_16x16x32_bf16 v[96:99], v[178:181], v[194:197], v[96:99]
	v_mfma_f32_16x16x32_bf16 v[84:87], v[170:173], v[202:205], v[84:87]
	v_mfma_f32_16x16x32_bf16 v[80:83], v[178:181], v[202:205], v[80:83]
	v_mfma_f32_16x16x32_bf16 v[68:71], v[170:173], v[216:219], v[68:71]
	v_mfma_f32_16x16x32_bf16 v[64:67], v[178:181], v[216:219], v[64:67]
	s_setprio 1
	s_barrier
; #define STAGE(bufoff, gbase) STAGE_(bufoff, gbase, voffA)
; #define STAGEB(bufoff, gbase) STAGE_(bufoff, gbase, voffB)
; #define LDA(dst, b, h) do { _Pragma("unroll") for (int m = 0; m < 4; ++m) _Pragma("unroll") for (int k = 0; k < 2; ++k) dst[m][k] = *LDSP(const bf16x8, lds + SA(b, h) + aoff + m * 2048 + k * 1024); } while (0)
; #define MMA(ai, bj, AT, BT) do { __builtin_amdgcn_s_setprio(1); \
;     _Pragma("unroll") for (int m = 0; m < 4; ++m) _Pragma("unroll") for (int n = 0; n < 2; ++n) _Pragma("unroll") for (int k = 0; k < 2; ++k) \
;       acc[ai][bj][m][n] = __builtin_amdgcn_mfma_f32_16x16x32_bf16(BT[n][k], AT[m][k], acc[ai][bj][m][n], 0, 0, 0); \
;     __builtin_amdgcn_s_setprio(0); } while (0)
; #define WAIT_V(n) asm volatile("s_waitcnt vmcnt(" #n ")" ::: "memory")
; #define WAIT_L(n) asm volatile("s_waitcnt lgkmcnt(" #n ")" ::: "memory")
; #define BAR __builtin_amdgcn_s_barrier()
; #define SCHED __builtin_amdgcn_sched_barrier(0)
; #define WAIT_V(n) asm volatile("s_waitcnt vmcnt(" #n ")" ::: "memory")
; #define BAR do { __builtin_amdgcn_sched_barrier(0); __builtin_amdgcn_s_barrier(); asm volatile("" ::: "memory"); __builtin_amdgcn_sched_barrier(0); } while (0)
; template <bool SP2, bool ALIGN_EPI, bool DUAL, class Epi> DI void gemm_phase2(const bf16_t* A, const bf16_t* Bt, const bf16_t* A2, const bf16_t* Bt2, int M, int N, int K, const Epi& E, lds_t* lds) {
;     ...
;     for (int t = 0; t < nt; t += 2) {
;       const bool last = (t == nt - 2);
;       const char* a1 = cA + (size_t)(t + 1) * kstep;
;       const char* a2 = last ? nA : cA + (size_t)(t + 2) * kstep; const char* b2 = last ? nB : cB + (size_t)(t + 2) * kstep;
;       const char* a3 = a2 + kstep; const char* b3 = b2 + kstep;
;     ...
;         LDA(At, 1, 1); STAGEB(SB(1, 0), b3); STAGEB(SB(1, 1), b3 + bstep); STAGE(SA(1, 0), a3);
;         WAIT_V(8); WAIT_L(0); BAR; MMA(1, 0, At, B0); MMA(1, 1, At, B1); BAR; SCHED;
	s_add_i32 s47, s47, s2
	v_lshl_add_u64 v[210:211], v[210:211], 0, s[16:17]
	s_mov_b32 m0, s47
	ds_read_b128 v[182:185], v148 offset:49152
	ds_read_b128 v[186:189], v148 offset:50176
	ds_read_b128 v[190:193], v148 offset:51200
	ds_read_b128 v[194:197], v148 offset:52224
	ds_read_b128 v[198:201], v148 offset:53248
	ds_read_b128 v[202:205], v148 offset:54272
	ds_read_b128 v[206:209], v148 offset:55296
	ds_read_b128 v[216:219], v148 offset:56320
	global_load_lds_dwordx4 v[210:211], off
	s_add_i32 m0, s47, 0x2000
	s_add_u32 s54, s54, 0x10080
	v_lshl_add_u64 v[210:211], v[220:221], 0, s[16:17]
	s_addc_u32 s55, s55, 0
	s_add_i32 s47, s58, s2
	global_load_lds_dwordx4 v[210:211], off
	v_lshl_add_u64 v[210:211], s[54:55], 0, v[132:133]
	s_mov_b32 m0, s47
	s_nop 0
	global_load_lds_dwordx4 v[210:211], off
	v_lshl_add_u64 v[210:211], s[54:55], 0, v[128:129]
	s_add_i32 m0, s47, 0x2000
	s_nop 0
	global_load_lds_dwordx4 v[210:211], off
	v_lshl_add_u64 v[210:211], v[222:223], 0, s[16:17]
	s_mov_b32 m0, s15
	s_nop 0
	global_load_lds_dwordx4 v[210:211], off
	v_lshl_add_u64 v[210:211], v[224:225], 0, s[16:17]
	s_mov_b32 m0, s18
	s_nop 0
	global_load_lds_dwordx4 v[210:211], off
	s_waitcnt vmcnt(8)
	s_waitcnt lgkmcnt(0)
	s_barrier
	s_setprio 0
	s_waitcnt lgkmcnt(0)
	v_mfma_f32_16x16x32_bf16 v[60:63], v[150:153], v[182:185], v[60:63]
	v_mfma_f32_16x16x32_bf16 v[56:59], v[158:161], v[182:185], v[56:59]
	v_mfma_f32_16x16x32_bf16 v[44:47], v[150:153], v[190:193], v[44:47]
	v_mfma_f32_16x16x32_bf16 v[40:43], v[158:161], v[190:193], v[40:43]
	v_mfma_f32_16x16x32_bf16 v[28:31], v[150:153], v[198:201], v[28:31]
	v_mfma_f32_16x16x32_bf16 v[24:27], v[158:161], v[198:201], v[24:27]
	v_mfma_f32_16x16x32_bf16 v[12:15], v[150:153], v[206:209], v[12:15]
	v_mfma_f32_16x16x32_bf16 v[8:11], v[158:161], v[206:209], v[8:11]
	v_mfma_f32_16x16x32_bf16 v[60:63], v[154:157], v[186:189], v[60:63]
	v_mfma_f32_16x16x32_bf16 v[56:59], v[162:165], v[186:189], v[56:59]
	v_mfma_f32_16x16x32_bf16 v[44:47], v[154:157], v[194:197], v[44:47]
	v_mfma_f32_16x16x32_bf16 v[40:43], v[162:165], v[194:197], v[40:43]
	v_mfma_f32_16x16x32_bf16 v[28:31], v[154:157], v[202:205], v[28:31]
	v_mfma_f32_16x16x32_bf16 v[24:27], v[162:165], v[202:205], v[24:27]
	v_mfma_f32_16x16x32_bf16 v[12:15], v[154:157], v[216:219], v[12:15]
	v_mfma_f32_16x16x32_bf16 v[8:11], v[162:165], v[216:219], v[8:11]
	s_setprio 1
	s_setprio 0
	v_mfma_f32_16x16x32_bf16 v[52:55], v[166:169], v[182:185], v[52:55]
	v_mfma_f32_16x16x32_bf16 v[48:51], v[174:177], v[182:185], v[48:51]
	v_mfma_f32_16x16x32_bf16 v[36:39], v[166:169], v[190:193], v[36:39]
	v_mfma_f32_16x16x32_bf16 v[32:35], v[174:177], v[190:193], v[32:35]
	v_mfma_f32_16x16x32_bf16 v[20:23], v[166:169], v[198:201], v[20:23]
	v_mfma_f32_16x16x32_bf16 v[16:19], v[174:177], v[198:201], v[16:19]
	v_mfma_f32_16x16x32_bf16 v[4:7], v[166:169], v[206:209], v[4:7]
	v_mfma_f32_16x16x32_bf16 v[0:3], v[174:177], v[206:209], v[0:3]
	v_mfma_f32_16x16x32_bf16 v[52:55], v[170:173], v[186:189], v[52:55]
	v_mfma_f32_16x16x32_bf16 v[48:51], v[178:181], v[186:189], v[48:51]
	v_mfma_f32_16x16x32_bf16 v[36:39], v[170:173], v[194:197], v[36:39]
	v_mfma_f32_16x16x32_bf16 v[32:35], v[178:181], v[194:197], v[32:35]
	v_mfma_f32_16x16x32_bf16 v[20:23], v[170:173], v[202:205], v[20:23]
	v_mfma_f32_16x16x32_bf16 v[16:19], v[178:181], v[202:205], v[16:19]
	v_mfma_f32_16x16x32_bf16 v[4:7], v[170:173], v[216:219], v[4:7]
	v_mfma_f32_16x16x32_bf16 v[0:3], v[178:181], v[216:219], v[0:3]
	s_setprio 1
	s_barrier
	s_add_i32 s37, s37, 2
	s_add_u32 s52, s52, 0x100
	s_addc_u32 s53, s53, 0
	s_add_u32 s34, s34, 0x100
	s_addc_u32 s35, s35, 0
	s_cmp_gt_u32 s37, 13
	s_cbranch_scc0 .LBB0_620
	s_and_b64 vcc, exec, s[30:31]
	s_cbranch_vccz .LBB0_623
	s_barrier

; #define STAGE(bufoff, gbase) STAGE_(bufoff, gbase, voffA)
; #define STAGEB(bufoff, gbase) STAGE_(bufoff, gbase, voffB)
; #define LDA(dst, b, h) do { _Pragma("unroll") for (int m = 0; m < 4; ++m) _Pragma("unroll") for (int k = 0; k < 2; ++k) dst[m][k] = *LDSP(const bf16x8, lds + SA(b, h) + aoff + m * 2048 + k * 1024); } while (0)
; #define LDB(dst, b, h) do { _Pragma("unroll") for (int n = 0; n < 2; ++n) _Pragma("unroll") for (int k = 0; k < 2; ++k) dst[n][k] = *LDSP(const bf16x8, lds + SB(b, h) + boff + n * 2048 + k * 1024); } while (0)
; #define MMA(ai, bj, AT, BT) do { __builtin_amdgcn_s_setprio(1); \
;     _Pragma("unroll") for (int m = 0; m < 4; ++m) _Pragma("unroll") for (int n = 0; n < 2; ++n) _Pragma("unroll") for (int k = 0; k < 2; ++k) \
;       acc[ai][bj][m][n] = __builtin_amdgcn_mfma_f32_16x16x32_bf16(BT[n][k], AT[m][k], acc[ai][bj][m][n], 0, 0, 0); \
;     __builtin_amdgcn_s_setprio(0); } while (0)
; #define WAIT_V(n) asm volatile("s_waitcnt vmcnt(" #n ")" ::: "memory")
; #define WAIT_L(n) asm volatile("s_waitcnt lgkmcnt(" #n ")" ::: "memory")
; #define BAR __builtin_amdgcn_s_barrier()
; #define SCHED __builtin_amdgcn_sched_barrier(0)
; #define WAIT_V(n) asm volatile("s_waitcnt vmcnt(" #n ")" ::: "memory")
; #define BAR do { __builtin_amdgcn_sched_barrier(0); __builtin_amdgcn_s_barrier(); asm volatile("" ::: "memory"); __builtin_amdgcn_sched_barrier(0); } while (0)
; template <bool SP2, bool ALIGN_EPI, bool DUAL, class Epi> DI void gemm_phase2(const bf16_t* A, const bf16_t* Bt, const bf16_t* A2, const bf16_t* Bt2, int M, int N, int K, const Epi& E, lds_t* lds) {
;     ...
;     for (int t = 0; t < nt; t += 2) {
;       const bool last = (t == nt - 2);
;       const char* a1 = cA + (size_t)(t + 1) * kstep;
;       const char* a2 = last ? nA : cA + (size_t)(t + 2) * kstep; const char* b2 = last ? nB : cB + (size_t)(t + 2) * kstep;
;       const char* a3 = a2 + kstep; const char* b3 = b2 + kstep;
;       if constexpr (SP2) {
;         LDB(B0, 0, 0); LDB(B1, 0, 1); SCHED; LDA(At, 0, 0); STAGE(SA(1, 1), a1 + hstep);
;         WAIT_V(8); WAIT_L(0); BAR; MMA(0, 0, At, B0); MMA(0, 1, At, B1); BAR; SCHED;
;         LDA(At, 0, 1); STAGEB(SB(0, 0), b2); STAGEB(SB(0, 1), b2 + bstep); STAGE(SA(0, 0), a2);
;         WAIT_V(8); WAIT_L(0); BAR; MMA(1, 0, At, B0); MMA(1, 1, At, B1); BAR; SCHED;
.LBB0_691:
	ds_read_b128 v[152:155], v148
	ds_read_b128 v[156:159], v148 offset:1024
	ds_read_b128 v[160:163], v148 offset:2048
	ds_read_b128 v[164:167], v148 offset:3072
	ds_read_b128 v[168:171], v149
	ds_read_b128 v[172:175], v149 offset:1024
	ds_read_b128 v[176:179], v149 offset:2048
	ds_read_b128 v[180:183], v149 offset:3072
	s_add_u32 s34, s52, 0xfffc0080
	s_addc_u32 s35, s53, -1
	s_cmp_eq_u32 s33, 12
	s_cselect_b32 s57, s0, s35
	s_cselect_b32 s56, s1, s34
	s_cselect_b32 s55, s21, s31
	s_cselect_b32 s54, s22, s23
	v_lshl_add_u64 v[140:141], s[52:53], 0, v[136:137]
	s_add_i32 m0, s3, 0xc000
	ds_read_b128 v[184:187], v150
	ds_read_b128 v[188:191], v150 offset:1024
	ds_read_b128 v[192:195], v150 offset:2048
	ds_read_b128 v[196:199], v150 offset:3072
	ds_read_b128 v[200:203], v150 offset:4096
	ds_read_b128 v[204:207], v150 offset:5120
	ds_read_b128 v[208:211], v150 offset:6144
	ds_read_b128 v[216:219], v150 offset:7168
	global_load_lds_dwordx4 v[140:141], off
	v_lshl_add_u64 v[140:141], s[52:53], 0, v[138:139]
	s_add_i32 m0, s3, 0xe000
	s_nop 0
	global_load_lds_dwordx4 v[140:141], off
	s_waitcnt vmcnt(8)
	s_waitcnt lgkmcnt(0)
	s_barrier
	s_setprio 0
	s_waitcnt lgkmcnt(0)
	v_mfma_f32_16x16x32_bf16 v[124:127], v[152:155], v[184:187], v[124:127]
	v_mfma_f32_16x16x32_bf16 v[120:123], v[160:163], v[184:187], v[120:123]
	v_mfma_f32_16x16x32_bf16 v[108:111], v[152:155], v[192:195], v[108:111]
	v_mfma_f32_16x16x32_bf16 v[104:107], v[160:163], v[192:195], v[104:107]
	v_mfma_f32_16x16x32_bf16 v[92:95], v[152:155], v[200:203], v[92:95]
	v_mfma_f32_16x16x32_bf16 v[88:91], v[160:163], v[200:203], v[88:91]
	v_mfma_f32_16x16x32_bf16 v[76:79], v[152:155], v[208:211], v[76:79]
	v_mfma_f32_16x16x32_bf16 v[72:75], v[160:163], v[208:211], v[72:75]
	v_mfma_f32_16x16x32_bf16 v[124:127], v[156:159], v[188:191], v[124:127]
	v_mfma_f32_16x16x32_bf16 v[120:123], v[164:167], v[188:191], v[120:123]
	v_mfma_f32_16x16x32_bf16 v[108:111], v[156:159], v[196:199], v[108:111]
	v_mfma_f32_16x16x32_bf16 v[104:107], v[164:167], v[196:199], v[104:107]
	v_mfma_f32_16x16x32_bf16 v[92:95], v[156:159], v[204:207], v[92:95]
	v_mfma_f32_16x16x32_bf16 v[88:91], v[164:167], v[204:207], v[88:91]
	v_mfma_f32_16x16x32_bf16 v[76:79], v[156:159], v[216:219], v[76:79]
	v_mfma_f32_16x16x32_bf16 v[72:75], v[164:167], v[216:219], v[72:75]
	s_setprio 1
	s_setprio 0
	v_mfma_f32_16x16x32_bf16 v[116:119], v[168:171], v[184:187], v[116:119]
	v_mfma_f32_16x16x32_bf16 v[112:115], v[176:179], v[184:187], v[112:115]
	v_mfma_f32_16x16x32_bf16 v[100:103], v[168:171], v[192:195], v[100:103]
	v_mfma_f32_16x16x32_bf16 v[96:99], v[176:179], v[192:195], v[96:99]
	v_mfma_f32_16x16x32_bf16 v[84:87], v[168:171], v[200:203], v[84:87]
	v_mfma_f32_16x16x32_bf16 v[80:83], v[176:179], v[200:203], v[80:83]
	v_mfma_f32_16x16x32_bf16 v[68:71], v[168:171], v[208:211], v[68:71]
	v_mfma_f32_16x16x32_bf16 v[64:67], v[176:179], v[208:211], v[64:67]
	v_mfma_f32_16x16x32_bf16 v[116:119], v[172:175], v[188:191], v[116:119]
	v_mfma_f32_16x16x32_bf16 v[112:115], v[180:183], v[188:191], v[112:115]
	v_mfma_f32_16x16x32_bf16 v[100:103], v[172:175], v[196:199], v[100:103]
	v_mfma_f32_16x16x32_bf16 v[96:99], v[180:183], v[196:199], v[96:99]
	v_mfma_f32_16x16x32_bf16 v[84:87], v[172:175], v[204:207], v[84:87]
	v_mfma_f32_16x16x32_bf16 v[80:83], v[180:183], v[204:207], v[80:83]
	v_mfma_f32_16x16x32_bf16 v[68:71], v[172:175], v[216:219], v[68:71]
	v_mfma_f32_16x16x32_bf16 v[64:67], v[180:183], v[216:219], v[64:67]
	s_setprio 1
	s_barrier
	s_add_i32 s34, s18, s2
	v_lshl_add_u64 v[140:141], s[54:55], 0, v[130:131]
	s_mov_b32 m0, s34
	ds_read_b128 v[184:187], v150 offset:16384
	ds_read_b128 v[188:191], v150 offset:17408
	ds_read_b128 v[192:195], v150 offset:18432
	ds_read_b128 v[196:199], v150 offset:19456
	ds_read_b128 v[200:203], v150 offset:20480
	ds_read_b128 v[204:207], v150 offset:21504
	ds_read_b128 v[208:211], v150 offset:22528
	ds_read_b128 v[216:219], v150 offset:23552
	global_load_lds_dwordx4 v[140:141], off
	s_add_i32 m0, s34, 0x2000
	s_add_u32 s34, s54, 0x10000
	v_lshl_add_u64 v[220:221], s[54:55], 0, v[134:135]
	s_addc_u32 s35, s55, 0
	s_add_i32 s41, s19, s2
	global_load_lds_dwordx4 v[220:221], off
	v_lshl_add_u64 v[222:223], s[34:35], 0, v[130:131]
	s_mov_b32 m0, s41
	v_lshl_add_u64 v[224:225], s[56:57], 0, v[132:133]
	global_load_lds_dwordx4 v[222:223], off
	v_lshl_add_u64 v[222:223], s[34:35], 0, v[134:135]
	s_add_i32 m0, s41, 0x2000
	s_nop 0
	global_load_lds_dwordx4 v[222:223], off
	v_lshl_add_u64 v[222:223], s[56:57], 0, v[128:129]
	s_mov_b32 m0, s3
	s_nop 0
	global_load_lds_dwordx4 v[222:223], off
	s_mov_b32 m0, s8
	s_nop 0
	global_load_lds_dwordx4 v[224:225], off
	s_waitcnt vmcnt(8)
	s_waitcnt lgkmcnt(0)
	s_barrier
; #define STAGE(bufoff, gbase) STAGE_(bufoff, gbase, voffA)
; #define LDA(dst, b, h) do { _Pragma("unroll") for (int m = 0; m < 4; ++m) _Pragma("unroll") for (int k = 0; k < 2; ++k) dst[m][k] = *LDSP(const bf16x8, lds + SA(b, h) + aoff + m * 2048 + k * 1024); } while (0)
; #define LDB(dst, b, h) do { _Pragma("unroll") for (int n = 0; n < 2; ++n) _Pragma("unroll") for (int k = 0; k < 2; ++k) dst[n][k] = *LDSP(const bf16x8, lds + SB(b, h) + boff + n * 2048 + k * 1024); } while (0)
; #define MMA(ai, bj, AT, BT) do { __builtin_amdgcn_s_setprio(1); \
;     _Pragma("unroll") for (int m = 0; m < 4; ++m) _Pragma("unroll") for (int n = 0; n < 2; ++n) _Pragma("unroll") for (int k = 0; k < 2; ++k) \
;       acc[ai][bj][m][n] = __builtin_amdgcn_mfma_f32_16x16x32_bf16(BT[n][k], AT[m][k], acc[ai][bj][m][n], 0, 0, 0); \
;     __builtin_amdgcn_s_setprio(0); } while (0)
; #define WAIT_V(n) asm volatile("s_waitcnt vmcnt(" #n ")" ::: "memory")
; #define WAIT_L(n) asm volatile("s_waitcnt lgkmcnt(" #n ")" ::: "memory")
; #define BAR __builtin_amdgcn_s_barrier()
; #define SCHED __builtin_amdgcn_sched_barrier(0)
; #define WAIT_V(n) asm volatile("s_waitcnt vmcnt(" #n ")" ::: "memory")
; #define BAR do { __builtin_amdgcn_sched_barrier(0); __builtin_amdgcn_s_barrier(); asm volatile("" ::: "memory"); __builtin_amdgcn_sched_barrier(0); } while (0)
; template <bool SP2, bool ALIGN_EPI, bool DUAL, class Epi> DI void gemm_phase2(const bf16_t* A, const bf16_t* Bt, const bf16_t* A2, const bf16_t* Bt2, int M, int N, int K, const Epi& E, lds_t* lds) {
;     ...
;         WAIT_V(8); WAIT_L(0); BAR; MMA(1, 0, At, B0); MMA(1, 1, At, B1); BAR; SCHED;
;         LDB(B0, 1, 0); LDB(B1, 1, 1); SCHED; LDA(At, 1, 0); STAGE(SA(0, 1), a2 + hstep);
;         WAIT_V(8); WAIT_L(0); BAR; MMA(0, 0, At, B0); MMA(0, 1, At, B1); BAR; SCHED;
	s_setprio 0
	s_waitcnt lgkmcnt(0)
	v_mfma_f32_16x16x32_bf16 v[60:63], v[152:155], v[184:187], v[60:63]
	v_mfma_f32_16x16x32_bf16 v[56:59], v[160:163], v[184:187], v[56:59]
	v_mfma_f32_16x16x32_bf16 v[44:47], v[152:155], v[192:195], v[44:47]
	v_mfma_f32_16x16x32_bf16 v[40:43], v[160:163], v[192:195], v[40:43]
	v_mfma_f32_16x16x32_bf16 v[28:31], v[152:155], v[200:203], v[28:31]
	v_mfma_f32_16x16x32_bf16 v[24:27], v[160:163], v[200:203], v[24:27]
	v_mfma_f32_16x16x32_bf16 v[12:15], v[152:155], v[208:211], v[12:15]
	v_mfma_f32_16x16x32_bf16 v[8:11], v[160:163], v[208:211], v[8:11]
	v_mfma_f32_16x16x32_bf16 v[60:63], v[156:159], v[188:191], v[60:63]
	v_mfma_f32_16x16x32_bf16 v[56:59], v[164:167], v[188:191], v[56:59]
	v_mfma_f32_16x16x32_bf16 v[44:47], v[156:159], v[196:199], v[44:47]
	v_mfma_f32_16x16x32_bf16 v[40:43], v[164:167], v[196:199], v[40:43]
	v_mfma_f32_16x16x32_bf16 v[28:31], v[156:159], v[204:207], v[28:31]
	v_mfma_f32_16x16x32_bf16 v[24:27], v[164:167], v[204:207], v[24:27]
	v_mfma_f32_16x16x32_bf16 v[12:15], v[156:159], v[216:219], v[12:15]
	v_mfma_f32_16x16x32_bf16 v[8:11], v[164:167], v[216:219], v[8:11]
	s_setprio 1
	s_setprio 0
	v_mfma_f32_16x16x32_bf16 v[52:55], v[168:171], v[184:187], v[52:55]
	v_mfma_f32_16x16x32_bf16 v[48:51], v[176:179], v[184:187], v[48:51]
	v_mfma_f32_16x16x32_bf16 v[36:39], v[168:171], v[192:195], v[36:39]
	v_mfma_f32_16x16x32_bf16 v[32:35], v[176:179], v[192:195], v[32:35]
	v_mfma_f32_16x16x32_bf16 v[20:23], v[168:171], v[200:203], v[20:23]
	v_mfma_f32_16x16x32_bf16 v[16:19], v[176:179], v[200:203], v[16:19]
	v_mfma_f32_16x16x32_bf16 v[4:7], v[168:171], v[208:211], v[4:7]
	v_mfma_f32_16x16x32_bf16 v[0:3], v[176:179], v[208:211], v[0:3]
	v_mfma_f32_16x16x32_bf16 v[52:55], v[172:175], v[188:191], v[52:55]
	v_mfma_f32_16x16x32_bf16 v[48:51], v[180:183], v[188:191], v[48:51]
	v_mfma_f32_16x16x32_bf16 v[36:39], v[172:175], v[196:199], v[36:39]
	v_mfma_f32_16x16x32_bf16 v[32:35], v[180:183], v[196:199], v[32:35]
	v_mfma_f32_16x16x32_bf16 v[20:23], v[172:175], v[204:207], v[20:23]
	v_mfma_f32_16x16x32_bf16 v[16:19], v[180:183], v[204:207], v[16:19]
	v_mfma_f32_16x16x32_bf16 v[4:7], v[172:175], v[216:219], v[4:7]
	v_mfma_f32_16x16x32_bf16 v[0:3], v[180:183], v[216:219], v[0:3]
	s_setprio 1
	s_barrier
	s_add_i32 s41, 0, 0x18000
	s_add_i32 s49, 0, 0x1c000
	v_add_u32_e32 v164, s41, v143
	v_add_u32_e32 v180, s49, v143
	ds_read_b128 v[152:155], v164
	ds_read_b128 v[156:159], v164 offset:1024
	ds_read_b128 v[160:163], v164 offset:2048
	ds_read_b128 v[164:167], v164 offset:3072
	ds_read_b128 v[168:171], v180
	ds_read_b128 v[172:175], v180 offset:1024
	ds_read_b128 v[176:179], v180 offset:2048
	ds_read_b128 v[180:183], v180 offset:3072
	s_add_u32 s34, s56, 0x40000
	s_addc_u32 s35, s57, 0
	s_mov_b32 m0, s9
	v_lshl_add_u64 v[226:227], s[34:35], 0, v[128:129]
	ds_read_b128 v[184:187], v150 offset:32768
	ds_read_b128 v[188:191], v150 offset:33792
	ds_read_b128 v[192:195], v150 offset:34816
	ds_read_b128 v[196:199], v150 offset:35840
	ds_read_b128 v[200:203], v150 offset:36864
	ds_read_b128 v[204:207], v150 offset:37888
	ds_read_b128 v[208:211], v150 offset:38912
	ds_read_b128 v[216:219], v150 offset:39936
	global_load_lds_dwordx4 v[226:227], off
	v_lshl_add_u64 v[226:227], s[34:35], 0, v[132:133]
	s_mov_b32 m0, s10
	s_nop 0
	global_load_lds_dwordx4 v[226:227], off
	s_waitcnt vmcnt(8)
	s_waitcnt lgkmcnt(0)
	s_barrier
	s_setprio 0
	s_waitcnt lgkmcnt(0)
	v_mfma_f32_16x16x32_bf16 v[124:127], v[152:155], v[184:187], v[124:127]
	v_mfma_f32_16x16x32_bf16 v[120:123], v[160:163], v[184:187], v[120:123]
	v_mfma_f32_16x16x32_bf16 v[108:111], v[152:155], v[192:195], v[108:111]
	v_mfma_f32_16x16x32_bf16 v[104:107], v[160:163], v[192:195], v[104:107]
	v_mfma_f32_16x16x32_bf16 v[92:95], v[152:155], v[200:203], v[92:95]
	v_mfma_f32_16x16x32_bf16 v[88:91], v[160:163], v[200:203], v[88:91]
	v_mfma_f32_16x16x32_bf16 v[76:79], v[152:155], v[208:211], v[76:79]
	v_mfma_f32_16x16x32_bf16 v[72:75], v[160:163], v[208:211], v[72:75]
	v_mfma_f32_16x16x32_bf16 v[124:127], v[156:159], v[188:191], v[124:127]
	v_mfma_f32_16x16x32_bf16 v[120:123], v[164:167], v[188:191], v[120:123]
	v_mfma_f32_16x16x32_bf16 v[108:111], v[156:159], v[196:199], v[108:111]
	v_mfma_f32_16x16x32_bf16 v[104:107], v[164:167], v[196:199], v[104:107]
	v_mfma_f32_16x16x32_bf16 v[92:95], v[156:159], v[204:207], v[92:95]
	v_mfma_f32_16x16x32_bf16 v[88:91], v[164:167], v[204:207], v[88:91]
	v_mfma_f32_16x16x32_bf16 v[76:79], v[156:159], v[216:219], v[76:79]
	v_mfma_f32_16x16x32_bf16 v[72:75], v[164:167], v[216:219], v[72:75]
	s_setprio 1
	s_setprio 0
	v_mfma_f32_16x16x32_bf16 v[116:119], v[168:171], v[184:187], v[116:119]
	v_mfma_f32_16x16x32_bf16 v[112:115], v[176:179], v[184:187], v[112:115]
	v_mfma_f32_16x16x32_bf16 v[100:103], v[168:171], v[192:195], v[100:103]
	v_mfma_f32_16x16x32_bf16 v[96:99], v[176:179], v[192:195], v[96:99]
	v_mfma_f32_16x16x32_bf16 v[84:87], v[168:171], v[200:203], v[84:87]
	v_mfma_f32_16x16x32_bf16 v[80:83], v[176:179], v[200:203], v[80:83]
	v_mfma_f32_16x16x32_bf16 v[68:71], v[168:171], v[208:211], v[68:71]
	v_mfma_f32_16x16x32_bf16 v[64:67], v[176:179], v[208:211], v[64:67]
	v_mfma_f32_16x16x32_bf16 v[116:119], v[172:175], v[188:191], v[116:119]
	v_mfma_f32_16x16x32_bf16 v[112:115], v[180:183], v[188:191], v[112:115]
	v_mfma_f32_16x16x32_bf16 v[100:103], v[172:175], v[196:199], v[100:103]
	v_mfma_f32_16x16x32_bf16 v[96:99], v[180:183], v[196:199], v[96:99]
	v_mfma_f32_16x16x32_bf16 v[84:87], v[172:175], v[204:207], v[84:87]
	v_mfma_f32_16x16x32_bf16 v[80:83], v[180:183], v[204:207], v[80:83]
	v_mfma_f32_16x16x32_bf16 v[68:71], v[172:175], v[216:219], v[68:71]
	v_mfma_f32_16x16x32_bf16 v[64:67], v[180:183], v[216:219], v[64:67]
	s_setprio 1
	s_barrier
; #define STAGE(bufoff, gbase) STAGE_(bufoff, gbase, voffA)
; #define STAGEB(bufoff, gbase) STAGE_(bufoff, gbase, voffB)
; #define LDA(dst, b, h) do { _Pragma("unroll") for (int m = 0; m < 4; ++m) _Pragma("unroll") for (int k = 0; k < 2; ++k) dst[m][k] = *LDSP(const bf16x8, lds + SA(b, h) + aoff + m * 2048 + k * 1024); } while (0)
; #define MMA(ai, bj, AT, BT) do { __builtin_amdgcn_s_setprio(1); \
;     _Pragma("unroll") for (int m = 0; m < 4; ++m) _Pragma("unroll") for (int n = 0; n < 2; ++n) _Pragma("unroll") for (int k = 0; k < 2; ++k) \
;       acc[ai][bj][m][n] = __builtin_amdgcn_mfma_f32_16x16x32_bf16(BT[n][k], AT[m][k], acc[ai][bj][m][n], 0, 0, 0); \
;     __builtin_amdgcn_s_setprio(0); } while (0)
; #define WAIT_V(n) asm volatile("s_waitcnt vmcnt(" #n ")" ::: "memory")
; #define WAIT_L(n) asm volatile("s_waitcnt lgkmcnt(" #n ")" ::: "memory")
; #define BAR __builtin_amdgcn_s_barrier()
; #define SCHED __builtin_amdgcn_sched_barrier(0)
; #define WAIT_V(n) asm volatile("s_waitcnt vmcnt(" #n ")" ::: "memory")
; #define BAR do { __builtin_amdgcn_sched_barrier(0); __builtin_amdgcn_s_barrier(); asm volatile("" ::: "memory"); __builtin_amdgcn_sched_barrier(0); } while (0)
; template <bool SP2, bool ALIGN_EPI, bool DUAL, class Epi> DI void gemm_phase2(const bf16_t* A, const bf16_t* Bt, const bf16_t* A2, const bf16_t* Bt2, int M, int N, int K, const Epi& E, lds_t* lds) {
;     ...
;     for (int t = 0; t < nt; t += 2) {
;       const bool last = (t == nt - 2);
;       const char* a1 = cA + (size_t)(t + 1) * kstep;
;       const char* a2 = last ? nA : cA + (size_t)(t + 2) * kstep; const char* b2 = last ? nB : cB + (size_t)(t + 2) * kstep;
;       const char* a3 = a2 + kstep; const char* b3 = b2 + kstep;
;     ...
;         LDA(At, 1, 1); STAGEB(SB(1, 0), b3); STAGEB(SB(1, 1), b3 + bstep); STAGE(SA(1, 0), a3);
;         WAIT_V(8); WAIT_L(0); BAR; MMA(1, 0, At, B0); MMA(1, 1, At, B1); BAR; SCHED;
	s_add_i32 s34, s41, s2
	v_lshl_add_u64 v[140:141], v[140:141], 0, s[28:29]
	s_mov_b32 m0, s34
	ds_read_b128 v[184:187], v150 offset:49152
	ds_read_b128 v[188:191], v150 offset:50176
	ds_read_b128 v[192:195], v150 offset:51200
	ds_read_b128 v[196:199], v150 offset:52224
	ds_read_b128 v[200:203], v150 offset:53248
	ds_read_b128 v[204:207], v150 offset:54272
	ds_read_b128 v[208:211], v150 offset:55296
	ds_read_b128 v[216:219], v150 offset:56320
	global_load_lds_dwordx4 v[140:141], off
	s_add_i32 m0, s34, 0x2000
	s_add_u32 s34, s54, 0x10080
	v_lshl_add_u64 v[140:141], v[220:221], 0, s[28:29]
	s_addc_u32 s35, s55, 0
	s_add_i32 s41, s49, s2
	global_load_lds_dwordx4 v[140:141], off
	v_lshl_add_u64 v[140:141], s[34:35], 0, v[130:131]
	s_mov_b32 m0, s41
	s_nop 0
	global_load_lds_dwordx4 v[140:141], off
	v_lshl_add_u64 v[140:141], s[34:35], 0, v[134:135]
	s_add_i32 m0, s41, 0x2000
	s_nop 0
	global_load_lds_dwordx4 v[140:141], off
	v_lshl_add_u64 v[140:141], v[222:223], 0, s[28:29]
	s_mov_b32 m0, s14
	s_nop 0
	global_load_lds_dwordx4 v[140:141], off
	v_lshl_add_u64 v[140:141], v[224:225], 0, s[28:29]
	s_mov_b32 m0, s15
	s_nop 0
	global_load_lds_dwordx4 v[140:141], off
	s_waitcnt vmcnt(8)
	s_waitcnt lgkmcnt(0)
	s_barrier
	s_setprio 0
	s_waitcnt lgkmcnt(0)
	v_mfma_f32_16x16x32_bf16 v[60:63], v[152:155], v[184:187], v[60:63]
	v_mfma_f32_16x16x32_bf16 v[56:59], v[160:163], v[184:187], v[56:59]
	v_mfma_f32_16x16x32_bf16 v[44:47], v[152:155], v[192:195], v[44:47]
	v_mfma_f32_16x16x32_bf16 v[40:43], v[160:163], v[192:195], v[40:43]
	v_mfma_f32_16x16x32_bf16 v[28:31], v[152:155], v[200:203], v[28:31]
	v_mfma_f32_16x16x32_bf16 v[24:27], v[160:163], v[200:203], v[24:27]
	v_mfma_f32_16x16x32_bf16 v[12:15], v[152:155], v[208:211], v[12:15]
	v_mfma_f32_16x16x32_bf16 v[8:11], v[160:163], v[208:211], v[8:11]
	v_mfma_f32_16x16x32_bf16 v[60:63], v[156:159], v[188:191], v[60:63]
	v_mfma_f32_16x16x32_bf16 v[56:59], v[164:167], v[188:191], v[56:59]
	v_mfma_f32_16x16x32_bf16 v[44:47], v[156:159], v[196:199], v[44:47]
	v_mfma_f32_16x16x32_bf16 v[40:43], v[164:167], v[196:199], v[40:43]
	v_mfma_f32_16x16x32_bf16 v[28:31], v[156:159], v[204:207], v[28:31]
	v_mfma_f32_16x16x32_bf16 v[24:27], v[164:167], v[204:207], v[24:27]
	v_mfma_f32_16x16x32_bf16 v[12:15], v[156:159], v[216:219], v[12:15]
	v_mfma_f32_16x16x32_bf16 v[8:11], v[164:167], v[216:219], v[8:11]
	s_setprio 1
	s_setprio 0
	v_mfma_f32_16x16x32_bf16 v[52:55], v[168:171], v[184:187], v[52:55]
	v_mfma_f32_16x16x32_bf16 v[48:51], v[176:179], v[184:187], v[48:51]
	v_mfma_f32_16x16x32_bf16 v[36:39], v[168:171], v[192:195], v[36:39]
	v_mfma_f32_16x16x32_bf16 v[32:35], v[176:179], v[192:195], v[32:35]
	v_mfma_f32_16x16x32_bf16 v[20:23], v[168:171], v[200:203], v[20:23]
	v_mfma_f32_16x16x32_bf16 v[16:19], v[176:179], v[200:203], v[16:19]
	v_mfma_f32_16x16x32_bf16 v[4:7], v[168:171], v[208:211], v[4:7]
	v_mfma_f32_16x16x32_bf16 v[0:3], v[176:179], v[208:211], v[0:3]
	v_mfma_f32_16x16x32_bf16 v[52:55], v[172:175], v[188:191], v[52:55]
	v_mfma_f32_16x16x32_bf16 v[48:51], v[180:183], v[188:191], v[48:51]
	v_mfma_f32_16x16x32_bf16 v[36:39], v[172:175], v[196:199], v[36:39]
	v_mfma_f32_16x16x32_bf16 v[32:35], v[180:183], v[196:199], v[32:35]
	v_mfma_f32_16x16x32_bf16 v[20:23], v[172:175], v[204:207], v[20:23]
	v_mfma_f32_16x16x32_bf16 v[16:19], v[180:183], v[204:207], v[16:19]
	v_mfma_f32_16x16x32_bf16 v[4:7], v[172:175], v[216:219], v[4:7]
	v_mfma_f32_16x16x32_bf16 v[0:3], v[180:183], v[216:219], v[0:3]
	s_setprio 1
	s_barrier
	s_add_i32 s33, s33, 2
	s_add_u32 s52, s52, 0x100
	s_addc_u32 s53, s53, 0
	s_add_u32 s23, s23, 0x100
	s_addc_u32 s31, s31, 0
	s_cmp_gt_u32 s33, 13
	s_cbranch_scc0 .LBB0_691
	s_and_b64 vcc, exec, s[36:37]
	s_cbranch_vccz .LBB0_694
	s_barrier

; #define STAGE(bufoff, gbase) STAGE_(bufoff, gbase, voffA)
; #define STAGEB(bufoff, gbase) STAGE_(bufoff, gbase, voffB)
; #define LDA(dst, b, h) do { _Pragma("unroll") for (int m = 0; m < 4; ++m) _Pragma("unroll") for (int k = 0; k < 2; ++k) dst[m][k] = *LDSP(const bf16x8, lds + SA(b, h) + aoff + m * 2048 + k * 1024); } while (0)
; #define LDB(dst, b, h) do { _Pragma("unroll") for (int n = 0; n < 2; ++n) _Pragma("unroll") for (int k = 0; k < 2; ++k) dst[n][k] = *LDSP(const bf16x8, lds + SB(b, h) + boff + n * 2048 + k * 1024); } while (0)
; #define MMA(ai, bj, AT, BT) do { __builtin_amdgcn_s_setprio(1); \
;     _Pragma("unroll") for (int m = 0; m < 4; ++m) _Pragma("unroll") for (int n = 0; n < 2; ++n) _Pragma("unroll") for (int k = 0; k < 2; ++k) \
;       acc[ai][bj][m][n] = __builtin_amdgcn_mfma_f32_16x16x32_bf16(BT[n][k], AT[m][k], acc[ai][bj][m][n], 0, 0, 0); \
;     __builtin_amdgcn_s_setprio(0); } while (0)
; #define WAIT_V(n) asm volatile("s_waitcnt vmcnt(" #n ")" ::: "memory")
; #define WAIT_L(n) asm volatile("s_waitcnt lgkmcnt(" #n ")" ::: "memory")
; #define BAR __builtin_amdgcn_s_barrier()
; #define SCHED __builtin_amdgcn_sched_barrier(0)
; #define WAIT_V(n) asm volatile("s_waitcnt vmcnt(" #n ")" ::: "memory")
; #define BAR do { __builtin_amdgcn_sched_barrier(0); __builtin_amdgcn_s_barrier(); asm volatile("" ::: "memory"); __builtin_amdgcn_sched_barrier(0); } while (0)
; template <bool SP2, bool ALIGN_EPI, bool DUAL, class Epi> DI void gemm_phase2(const bf16_t* A, const bf16_t* Bt, const bf16_t* A2, const bf16_t* Bt2, int M, int N, int K, const Epi& E, lds_t* lds) {
;     ...
;     for (int t = 0; t < nt; t += 2) {
;       const bool last = (t == nt - 2);
;       const char* a1 = cA + (size_t)(t + 1) * kstep;
;       const char* a2 = last ? nA : cA + (size_t)(t + 2) * kstep; const char* b2 = last ? nB : cB + (size_t)(t + 2) * kstep;
;       const char* a3 = a2 + kstep; const char* b3 = b2 + kstep;
;       if constexpr (SP2) {
;         LDB(B0, 0, 0); LDB(B1, 0, 1); SCHED; LDA(At, 0, 0); STAGE(SA(1, 1), a1 + hstep);
;         WAIT_V(8); WAIT_L(0); BAR; MMA(0, 0, At, B0); MMA(0, 1, At, B1); BAR; SCHED;
;         LDA(At, 0, 1); STAGEB(SB(0, 0), b2); STAGEB(SB(0, 1), b2 + bstep); STAGE(SA(0, 0), a2);
;         WAIT_V(8); WAIT_L(0); BAR; MMA(1, 0, At, B0); MMA(1, 1, At, B1); BAR; SCHED;
.LBB0_760:
	ds_read_b128 v[150:153], v146
	ds_read_b128 v[154:157], v146 offset:1024
	ds_read_b128 v[158:161], v146 offset:2048
	ds_read_b128 v[162:165], v146 offset:3072
	ds_read_b128 v[166:169], v147
	ds_read_b128 v[170:173], v147 offset:1024
	ds_read_b128 v[174:177], v147 offset:2048
	ds_read_b128 v[178:181], v147 offset:3072
	s_add_u32 s46, s44, 0xfffc0080
	s_addc_u32 s47, s45, -1
	s_cmp_eq_u32 s50, 12
	s_cselect_b32 s49, s0, s47
	s_cselect_b32 s48, s27, s46
	s_cselect_b32 s47, s31, s43
	s_cselect_b32 s46, s34, s35
	v_lshl_add_u64 v[210:211], s[44:45], 0, v[136:137]
	s_add_i32 m0, s3, 0xc000
	ds_read_b128 v[182:185], v148
	ds_read_b128 v[186:189], v148 offset:1024
	ds_read_b128 v[190:193], v148 offset:2048
	ds_read_b128 v[194:197], v148 offset:3072
	ds_read_b128 v[198:201], v148 offset:4096
	ds_read_b128 v[202:205], v148 offset:5120
	ds_read_b128 v[206:209], v148 offset:6144
	ds_read_b128 v[216:219], v148 offset:7168
	global_load_lds_dwordx4 v[210:211], off
	v_lshl_add_u64 v[210:211], s[44:45], 0, v[138:139]
	s_add_i32 m0, s3, 0xe000
	s_nop 0
	global_load_lds_dwordx4 v[210:211], off
	s_waitcnt vmcnt(8)
	s_waitcnt lgkmcnt(0)
	s_barrier
	s_setprio 0
	s_waitcnt lgkmcnt(0)
	v_mfma_f32_16x16x32_bf16 v[124:127], v[150:153], v[182:185], v[124:127]
	v_mfma_f32_16x16x32_bf16 v[120:123], v[158:161], v[182:185], v[120:123]
	v_mfma_f32_16x16x32_bf16 v[108:111], v[150:153], v[190:193], v[108:111]
	v_mfma_f32_16x16x32_bf16 v[104:107], v[158:161], v[190:193], v[104:107]
	v_mfma_f32_16x16x32_bf16 v[92:95], v[150:153], v[198:201], v[92:95]
	v_mfma_f32_16x16x32_bf16 v[88:91], v[158:161], v[198:201], v[88:91]
	v_mfma_f32_16x16x32_bf16 v[76:79], v[150:153], v[206:209], v[76:79]
	v_mfma_f32_16x16x32_bf16 v[72:75], v[158:161], v[206:209], v[72:75]
	v_mfma_f32_16x16x32_bf16 v[124:127], v[154:157], v[186:189], v[124:127]
	v_mfma_f32_16x16x32_bf16 v[120:123], v[162:165], v[186:189], v[120:123]
	v_mfma_f32_16x16x32_bf16 v[108:111], v[154:157], v[194:197], v[108:111]
	v_mfma_f32_16x16x32_bf16 v[104:107], v[162:165], v[194:197], v[104:107]
	v_mfma_f32_16x16x32_bf16 v[92:95], v[154:157], v[202:205], v[92:95]
	v_mfma_f32_16x16x32_bf16 v[88:91], v[162:165], v[202:205], v[88:91]
	v_mfma_f32_16x16x32_bf16 v[76:79], v[154:157], v[216:219], v[76:79]
	v_mfma_f32_16x16x32_bf16 v[72:75], v[162:165], v[216:219], v[72:75]
	s_setprio 1
	s_setprio 0
	v_mfma_f32_16x16x32_bf16 v[116:119], v[166:169], v[182:185], v[116:119]
	v_mfma_f32_16x16x32_bf16 v[112:115], v[174:177], v[182:185], v[112:115]
	v_mfma_f32_16x16x32_bf16 v[100:103], v[166:169], v[190:193], v[100:103]
	v_mfma_f32_16x16x32_bf16 v[96:99], v[174:177], v[190:193], v[96:99]
	v_mfma_f32_16x16x32_bf16 v[84:87], v[166:169], v[198:201], v[84:87]
	v_mfma_f32_16x16x32_bf16 v[80:83], v[174:177], v[198:201], v[80:83]
	v_mfma_f32_16x16x32_bf16 v[68:71], v[166:169], v[206:209], v[68:71]
	v_mfma_f32_16x16x32_bf16 v[64:67], v[174:177], v[206:209], v[64:67]
	v_mfma_f32_16x16x32_bf16 v[116:119], v[170:173], v[186:189], v[116:119]
	v_mfma_f32_16x16x32_bf16 v[112:115], v[178:181], v[186:189], v[112:115]
	v_mfma_f32_16x16x32_bf16 v[100:103], v[170:173], v[194:197], v[100:103]
	v_mfma_f32_16x16x32_bf16 v[96:99], v[178:181], v[194:197], v[96:99]
	v_mfma_f32_16x16x32_bf16 v[84:87], v[170:173], v[202:205], v[84:87]
	v_mfma_f32_16x16x32_bf16 v[80:83], v[178:181], v[202:205], v[80:83]
	v_mfma_f32_16x16x32_bf16 v[68:71], v[170:173], v[216:219], v[68:71]
	v_mfma_f32_16x16x32_bf16 v[64:67], v[178:181], v[216:219], v[64:67]
	s_setprio 1
	s_barrier
	s_add_i32 s51, s19, s2
	v_lshl_add_u64 v[210:211], s[46:47], 0, v[132:133]
	s_mov_b32 m0, s51
	ds_read_b128 v[182:185], v148 offset:16384
	ds_read_b128 v[186:189], v148 offset:17408
	ds_read_b128 v[190:193], v148 offset:18432
	ds_read_b128 v[194:197], v148 offset:19456
	ds_read_b128 v[198:201], v148 offset:20480
	ds_read_b128 v[202:205], v148 offset:21504
	ds_read_b128 v[206:209], v148 offset:22528
	ds_read_b128 v[216:219], v148 offset:23552
	global_load_lds_dwordx4 v[210:211], off
	s_add_i32 m0, s51, 0x2000
	s_add_u32 s52, s46, 0x10000
	v_lshl_add_u64 v[220:221], s[46:47], 0, v[128:129]
	s_addc_u32 s53, s47, 0
	s_add_i32 s51, s20, s2
	global_load_lds_dwordx4 v[220:221], off
	v_lshl_add_u64 v[222:223], s[52:53], 0, v[132:133]
	s_mov_b32 m0, s51
	v_lshl_add_u64 v[224:225], s[48:49], 0, v[130:131]
	global_load_lds_dwordx4 v[222:223], off
	v_lshl_add_u64 v[222:223], s[52:53], 0, v[128:129]
	s_add_i32 m0, s51, 0x2000
	s_nop 0
	global_load_lds_dwordx4 v[222:223], off
	v_lshl_add_u64 v[222:223], s[48:49], 0, v[134:135]
	s_mov_b32 m0, s3
	s_nop 0
	global_load_lds_dwordx4 v[222:223], off
	s_mov_b32 m0, s8
	s_nop 0
	global_load_lds_dwordx4 v[224:225], off
	s_waitcnt vmcnt(8)
	s_waitcnt lgkmcnt(0)
	s_barrier
; #define STAGE(bufoff, gbase) STAGE_(bufoff, gbase, voffA)
; #define LDA(dst, b, h) do { _Pragma("unroll") for (int m = 0; m < 4; ++m) _Pragma("unroll") for (int k = 0; k < 2; ++k) dst[m][k] = *LDSP(const bf16x8, lds + SA(b, h) + aoff + m * 2048 + k * 1024); } while (0)
; #define LDB(dst, b, h) do { _Pragma("unroll") for (int n = 0; n < 2; ++n) _Pragma("unroll") for (int k = 0; k < 2; ++k) dst[n][k] = *LDSP(const bf16x8, lds + SB(b, h) + boff + n * 2048 + k * 1024); } while (0)
; #define MMA(ai, bj, AT, BT) do { __builtin_amdgcn_s_setprio(1); \
;     _Pragma("unroll") for (int m = 0; m < 4; ++m) _Pragma("unroll") for (int n = 0; n < 2; ++n) _Pragma("unroll") for (int k = 0; k < 2; ++k) \
;       acc[ai][bj][m][n] = __builtin_amdgcn_mfma_f32_16x16x32_bf16(BT[n][k], AT[m][k], acc[ai][bj][m][n], 0, 0, 0); \
;     __builtin_amdgcn_s_setprio(0); } while (0)
; #define WAIT_V(n) asm volatile("s_waitcnt vmcnt(" #n ")" ::: "memory")
; #define WAIT_L(n) asm volatile("s_waitcnt lgkmcnt(" #n ")" ::: "memory")
; #define BAR __builtin_amdgcn_s_barrier()
; #define SCHED __builtin_amdgcn_sched_barrier(0)
; #define WAIT_V(n) asm volatile("s_waitcnt vmcnt(" #n ")" ::: "memory")
; #define BAR do { __builtin_amdgcn_sched_barrier(0); __builtin_amdgcn_s_barrier(); asm volatile("" ::: "memory"); __builtin_amdgcn_sched_barrier(0); } while (0)
; template <bool SP2, bool ALIGN_EPI, bool DUAL, class Epi> DI void gemm_phase2(const bf16_t* A, const bf16_t* Bt, const bf16_t* A2, const bf16_t* Bt2, int M, int N, int K, const Epi& E, lds_t* lds) {
;     ...
;         WAIT_V(8); WAIT_L(0); BAR; MMA(1, 0, At, B0); MMA(1, 1, At, B1); BAR; SCHED;
;         LDB(B0, 1, 0); LDB(B1, 1, 1); SCHED; LDA(At, 1, 0); STAGE(SA(0, 1), a2 + hstep);
;         WAIT_V(8); WAIT_L(0); BAR; MMA(0, 0, At, B0); MMA(0, 1, At, B1); BAR; SCHED;
	s_setprio 0
	s_waitcnt lgkmcnt(0)
	v_mfma_f32_16x16x32_bf16 v[60:63], v[150:153], v[182:185], v[60:63]
	v_mfma_f32_16x16x32_bf16 v[56:59], v[158:161], v[182:185], v[56:59]
	v_mfma_f32_16x16x32_bf16 v[44:47], v[150:153], v[190:193], v[44:47]
	v_mfma_f32_16x16x32_bf16 v[40:43], v[158:161], v[190:193], v[40:43]
	v_mfma_f32_16x16x32_bf16 v[28:31], v[150:153], v[198:201], v[28:31]
	v_mfma_f32_16x16x32_bf16 v[24:27], v[158:161], v[198:201], v[24:27]
	v_mfma_f32_16x16x32_bf16 v[12:15], v[150:153], v[206:209], v[12:15]
	v_mfma_f32_16x16x32_bf16 v[8:11], v[158:161], v[206:209], v[8:11]
	v_mfma_f32_16x16x32_bf16 v[60:63], v[154:157], v[186:189], v[60:63]
	v_mfma_f32_16x16x32_bf16 v[56:59], v[162:165], v[186:189], v[56:59]
	v_mfma_f32_16x16x32_bf16 v[44:47], v[154:157], v[194:197], v[44:47]
	v_mfma_f32_16x16x32_bf16 v[40:43], v[162:165], v[194:197], v[40:43]
	v_mfma_f32_16x16x32_bf16 v[28:31], v[154:157], v[202:205], v[28:31]
	v_mfma_f32_16x16x32_bf16 v[24:27], v[162:165], v[202:205], v[24:27]
	v_mfma_f32_16x16x32_bf16 v[12:15], v[154:157], v[216:219], v[12:15]
	v_mfma_f32_16x16x32_bf16 v[8:11], v[162:165], v[216:219], v[8:11]
	s_setprio 1
	s_setprio 0
	v_mfma_f32_16x16x32_bf16 v[52:55], v[166:169], v[182:185], v[52:55]
	v_mfma_f32_16x16x32_bf16 v[48:51], v[174:177], v[182:185], v[48:51]
	v_mfma_f32_16x16x32_bf16 v[36:39], v[166:169], v[190:193], v[36:39]
	v_mfma_f32_16x16x32_bf16 v[32:35], v[174:177], v[190:193], v[32:35]
	v_mfma_f32_16x16x32_bf16 v[20:23], v[166:169], v[198:201], v[20:23]
	v_mfma_f32_16x16x32_bf16 v[16:19], v[174:177], v[198:201], v[16:19]
	v_mfma_f32_16x16x32_bf16 v[4:7], v[166:169], v[206:209], v[4:7]
	v_mfma_f32_16x16x32_bf16 v[0:3], v[174:177], v[206:209], v[0:3]
	v_mfma_f32_16x16x32_bf16 v[52:55], v[170:173], v[186:189], v[52:55]
	v_mfma_f32_16x16x32_bf16 v[48:51], v[178:181], v[186:189], v[48:51]
	v_mfma_f32_16x16x32_bf16 v[36:39], v[170:173], v[194:197], v[36:39]
	v_mfma_f32_16x16x32_bf16 v[32:35], v[178:181], v[194:197], v[32:35]
	v_mfma_f32_16x16x32_bf16 v[20:23], v[170:173], v[202:205], v[20:23]
	v_mfma_f32_16x16x32_bf16 v[16:19], v[178:181], v[202:205], v[16:19]
	v_mfma_f32_16x16x32_bf16 v[4:7], v[170:173], v[216:219], v[4:7]
	v_mfma_f32_16x16x32_bf16 v[0:3], v[178:181], v[216:219], v[0:3]
	s_setprio 1
	s_barrier
	s_add_i32 s51, 0, 0x18000
	s_add_i32 s52, 0, 0x1c000
	v_add_u32_e32 v162, s51, v141
	v_add_u32_e32 v178, s52, v141
	ds_read_b128 v[150:153], v162
	ds_read_b128 v[154:157], v162 offset:1024
	ds_read_b128 v[158:161], v162 offset:2048
	ds_read_b128 v[162:165], v162 offset:3072
	ds_read_b128 v[166:169], v178
	ds_read_b128 v[170:173], v178 offset:1024
	ds_read_b128 v[174:177], v178 offset:2048
	ds_read_b128 v[178:181], v178 offset:3072
	s_add_u32 s48, s48, 0x40000
	s_addc_u32 s49, s49, 0
	s_mov_b32 m0, s9
	v_lshl_add_u64 v[226:227], s[48:49], 0, v[134:135]
	ds_read_b128 v[182:185], v148 offset:32768
	ds_read_b128 v[186:189], v148 offset:33792
	ds_read_b128 v[190:193], v148 offset:34816
	ds_read_b128 v[194:197], v148 offset:35840
	ds_read_b128 v[198:201], v148 offset:36864
	ds_read_b128 v[202:205], v148 offset:37888
	ds_read_b128 v[206:209], v148 offset:38912
	ds_read_b128 v[216:219], v148 offset:39936
	global_load_lds_dwordx4 v[226:227], off
	v_lshl_add_u64 v[226:227], s[48:49], 0, v[130:131]
	s_mov_b32 m0, s10
	s_nop 0
	global_load_lds_dwordx4 v[226:227], off
	s_waitcnt vmcnt(8)
	s_waitcnt lgkmcnt(0)
	s_barrier
	s_setprio 0
	s_waitcnt lgkmcnt(0)
	v_mfma_f32_16x16x32_bf16 v[124:127], v[150:153], v[182:185], v[124:127]
	v_mfma_f32_16x16x32_bf16 v[120:123], v[158:161], v[182:185], v[120:123]
	v_mfma_f32_16x16x32_bf16 v[108:111], v[150:153], v[190:193], v[108:111]
	v_mfma_f32_16x16x32_bf16 v[104:107], v[158:161], v[190:193], v[104:107]
	v_mfma_f32_16x16x32_bf16 v[92:95], v[150:153], v[198:201], v[92:95]
	v_mfma_f32_16x16x32_bf16 v[88:91], v[158:161], v[198:201], v[88:91]
	v_mfma_f32_16x16x32_bf16 v[76:79], v[150:153], v[206:209], v[76:79]
	v_mfma_f32_16x16x32_bf16 v[72:75], v[158:161], v[206:209], v[72:75]
	v_mfma_f32_16x16x32_bf16 v[124:127], v[154:157], v[186:189], v[124:127]
	v_mfma_f32_16x16x32_bf16 v[120:123], v[162:165], v[186:189], v[120:123]
	v_mfma_f32_16x16x32_bf16 v[108:111], v[154:157], v[194:197], v[108:111]
	v_mfma_f32_16x16x32_bf16 v[104:107], v[162:165], v[194:197], v[104:107]
	v_mfma_f32_16x16x32_bf16 v[92:95], v[154:157], v[202:205], v[92:95]
	v_mfma_f32_16x16x32_bf16 v[88:91], v[162:165], v[202:205], v[88:91]
	v_mfma_f32_16x16x32_bf16 v[76:79], v[154:157], v[216:219], v[76:79]
	v_mfma_f32_16x16x32_bf16 v[72:75], v[162:165], v[216:219], v[72:75]
	s_setprio 1
	s_setprio 0
	v_mfma_f32_16x16x32_bf16 v[116:119], v[166:169], v[182:185], v[116:119]
	v_mfma_f32_16x16x32_bf16 v[112:115], v[174:177], v[182:185], v[112:115]
	v_mfma_f32_16x16x32_bf16 v[100:103], v[166:169], v[190:193], v[100:103]
	v_mfma_f32_16x16x32_bf16 v[96:99], v[174:177], v[190:193], v[96:99]
	v_mfma_f32_16x16x32_bf16 v[84:87], v[166:169], v[198:201], v[84:87]
	v_mfma_f32_16x16x32_bf16 v[80:83], v[174:177], v[198:201], v[80:83]
	v_mfma_f32_16x16x32_bf16 v[68:71], v[166:169], v[206:209], v[68:71]
	v_mfma_f32_16x16x32_bf16 v[64:67], v[174:177], v[206:209], v[64:67]
	v_mfma_f32_16x16x32_bf16 v[116:119], v[170:173], v[186:189], v[116:119]
	v_mfma_f32_16x16x32_bf16 v[112:115], v[178:181], v[186:189], v[112:115]
	v_mfma_f32_16x16x32_bf16 v[100:103], v[170:173], v[194:197], v[100:103]
	v_mfma_f32_16x16x32_bf16 v[96:99], v[178:181], v[194:197], v[96:99]
	v_mfma_f32_16x16x32_bf16 v[84:87], v[170:173], v[202:205], v[84:87]
	v_mfma_f32_16x16x32_bf16 v[80:83], v[178:181], v[202:205], v[80:83]
	v_mfma_f32_16x16x32_bf16 v[68:71], v[170:173], v[216:219], v[68:71]
	v_mfma_f32_16x16x32_bf16 v[64:67], v[178:181], v[216:219], v[64:67]
	s_setprio 1
	s_barrier
; #define STAGE(bufoff, gbase) STAGE_(bufoff, gbase, voffA)
; #define STAGEB(bufoff, gbase) STAGE_(bufoff, gbase, voffB)
; #define LDA(dst, b, h) do { _Pragma("unroll") for (int m = 0; m < 4; ++m) _Pragma("unroll") for (int k = 0; k < 2; ++k) dst[m][k] = *LDSP(const bf16x8, lds + SA(b, h) + aoff + m * 2048 + k * 1024); } while (0)
; #define MMA(ai, bj, AT, BT) do { __builtin_amdgcn_s_setprio(1); \
;     _Pragma("unroll") for (int m = 0; m < 4; ++m) _Pragma("unroll") for (int n = 0; n < 2; ++n) _Pragma("unroll") for (int k = 0; k < 2; ++k) \
;       acc[ai][bj][m][n] = __builtin_amdgcn_mfma_f32_16x16x32_bf16(BT[n][k], AT[m][k], acc[ai][bj][m][n], 0, 0, 0); \
;     __builtin_amdgcn_s_setprio(0); } while (0)
; #define WAIT_V(n) asm volatile("s_waitcnt vmcnt(" #n ")" ::: "memory")
; #define WAIT_L(n) asm volatile("s_waitcnt lgkmcnt(" #n ")" ::: "memory")
; #define BAR __builtin_amdgcn_s_barrier()
; #define SCHED __builtin_amdgcn_sched_barrier(0)
; #define WAIT_V(n) asm volatile("s_waitcnt vmcnt(" #n ")" ::: "memory")
; #define BAR do { __builtin_amdgcn_sched_barrier(0); __builtin_amdgcn_s_barrier(); asm volatile("" ::: "memory"); __builtin_amdgcn_sched_barrier(0); } while (0)
; template <bool SP2, bool ALIGN_EPI, bool DUAL, class Epi> DI void gemm_phase2(const bf16_t* A, const bf16_t* Bt, const bf16_t* A2, const bf16_t* Bt2, int M, int N, int K, const Epi& E, lds_t* lds) {
;     ...
;     for (int t = 0; t < nt; t += 2) {
;       const bool last = (t == nt - 2);
;       const char* a1 = cA + (size_t)(t + 1) * kstep;
;       const char* a2 = last ? nA : cA + (size_t)(t + 2) * kstep; const char* b2 = last ? nB : cB + (size_t)(t + 2) * kstep;
;       const char* a3 = a2 + kstep; const char* b3 = b2 + kstep;
;     ...
;         LDA(At, 1, 1); STAGEB(SB(1, 0), b3); STAGEB(SB(1, 1), b3 + bstep); STAGE(SA(1, 0), a3);
;         WAIT_V(8); WAIT_L(0); BAR; MMA(1, 0, At, B0); MMA(1, 1, At, B1); BAR; SCHED;
	s_add_i32 s48, s51, s2
	v_lshl_add_u64 v[210:211], v[210:211], 0, s[22:23]
	s_mov_b32 m0, s48
	ds_read_b128 v[182:185], v148 offset:49152
	ds_read_b128 v[186:189], v148 offset:50176
	ds_read_b128 v[190:193], v148 offset:51200
	ds_read_b128 v[194:197], v148 offset:52224
	ds_read_b128 v[198:201], v148 offset:53248
	ds_read_b128 v[202:205], v148 offset:54272
	ds_read_b128 v[206:209], v148 offset:55296
	ds_read_b128 v[216:219], v148 offset:56320
	global_load_lds_dwordx4 v[210:211], off
	s_add_i32 m0, s48, 0x2000
	s_add_u32 s46, s46, 0x10080
	v_lshl_add_u64 v[210:211], v[220:221], 0, s[22:23]
	s_addc_u32 s47, s47, 0
	s_add_i32 s48, s52, s2
	global_load_lds_dwordx4 v[210:211], off
	v_lshl_add_u64 v[210:211], s[46:47], 0, v[132:133]
	s_mov_b32 m0, s48
	s_nop 0
	global_load_lds_dwordx4 v[210:211], off
	v_lshl_add_u64 v[210:211], s[46:47], 0, v[128:129]
	s_add_i32 m0, s48, 0x2000
	s_nop 0
	global_load_lds_dwordx4 v[210:211], off
	v_lshl_add_u64 v[210:211], v[222:223], 0, s[22:23]
	s_mov_b32 m0, s15
	s_nop 0
	global_load_lds_dwordx4 v[210:211], off
	v_lshl_add_u64 v[210:211], v[224:225], 0, s[22:23]
	s_mov_b32 m0, s18
	s_nop 0
	global_load_lds_dwordx4 v[210:211], off
	s_waitcnt vmcnt(8)
	s_waitcnt lgkmcnt(0)
	s_barrier
	s_setprio 0
	s_waitcnt lgkmcnt(0)
	v_mfma_f32_16x16x32_bf16 v[60:63], v[150:153], v[182:185], v[60:63]
	v_mfma_f32_16x16x32_bf16 v[56:59], v[158:161], v[182:185], v[56:59]
	v_mfma_f32_16x16x32_bf16 v[44:47], v[150:153], v[190:193], v[44:47]
	v_mfma_f32_16x16x32_bf16 v[40:43], v[158:161], v[190:193], v[40:43]
	v_mfma_f32_16x16x32_bf16 v[28:31], v[150:153], v[198:201], v[28:31]
	v_mfma_f32_16x16x32_bf16 v[24:27], v[158:161], v[198:201], v[24:27]
	v_mfma_f32_16x16x32_bf16 v[12:15], v[150:153], v[206:209], v[12:15]
	v_mfma_f32_16x16x32_bf16 v[8:11], v[158:161], v[206:209], v[8:11]
	v_mfma_f32_16x16x32_bf16 v[60:63], v[154:157], v[186:189], v[60:63]
	v_mfma_f32_16x16x32_bf16 v[56:59], v[162:165], v[186:189], v[56:59]
	v_mfma_f32_16x16x32_bf16 v[44:47], v[154:157], v[194:197], v[44:47]
	v_mfma_f32_16x16x32_bf16 v[40:43], v[162:165], v[194:197], v[40:43]
	v_mfma_f32_16x16x32_bf16 v[28:31], v[154:157], v[202:205], v[28:31]
	v_mfma_f32_16x16x32_bf16 v[24:27], v[162:165], v[202:205], v[24:27]
	v_mfma_f32_16x16x32_bf16 v[12:15], v[154:157], v[216:219], v[12:15]
	v_mfma_f32_16x16x32_bf16 v[8:11], v[162:165], v[216:219], v[8:11]
	s_setprio 1
	s_setprio 0
	v_mfma_f32_16x16x32_bf16 v[52:55], v[166:169], v[182:185], v[52:55]
	v_mfma_f32_16x16x32_bf16 v[48:51], v[174:177], v[182:185], v[48:51]
	v_mfma_f32_16x16x32_bf16 v[36:39], v[166:169], v[190:193], v[36:39]
	v_mfma_f32_16x16x32_bf16 v[32:35], v[174:177], v[190:193], v[32:35]
	v_mfma_f32_16x16x32_bf16 v[20:23], v[166:169], v[198:201], v[20:23]
	v_mfma_f32_16x16x32_bf16 v[16:19], v[174:177], v[198:201], v[16:19]
	v_mfma_f32_16x16x32_bf16 v[4:7], v[166:169], v[206:209], v[4:7]
	v_mfma_f32_16x16x32_bf16 v[0:3], v[174:177], v[206:209], v[0:3]
	v_mfma_f32_16x16x32_bf16 v[52:55], v[170:173], v[186:189], v[52:55]
	v_mfma_f32_16x16x32_bf16 v[48:51], v[178:181], v[186:189], v[48:51]
	v_mfma_f32_16x16x32_bf16 v[36:39], v[170:173], v[194:197], v[36:39]
	v_mfma_f32_16x16x32_bf16 v[32:35], v[178:181], v[194:197], v[32:35]
	v_mfma_f32_16x16x32_bf16 v[20:23], v[170:173], v[202:205], v[20:23]
	v_mfma_f32_16x16x32_bf16 v[16:19], v[178:181], v[202:205], v[16:19]
	v_mfma_f32_16x16x32_bf16 v[4:7], v[170:173], v[216:219], v[4:7]
	v_mfma_f32_16x16x32_bf16 v[0:3], v[178:181], v[216:219], v[0:3]
	s_setprio 1
	s_barrier
	s_add_i32 s50, s50, 2
	s_add_u32 s44, s44, 0x100
	s_addc_u32 s45, s45, 0
	s_add_u32 s35, s35, 0x100
	s_addc_u32 s43, s43, 0
	s_cmp_gt_u32 s50, 13
	s_cbranch_scc0 .LBB0_760
	s_and_b64 vcc, exec, s[28:29]
	s_cbranch_vccz .LBB0_763
	s_barrier

; #define STAGE(bufoff, gbase) STAGE_(bufoff, gbase, voffA)
; #define STAGEB(bufoff, gbase) STAGE_(bufoff, gbase, voffB)
; #define LDA(dst, b, h) do { _Pragma("unroll") for (int m = 0; m < 4; ++m) _Pragma("unroll") for (int k = 0; k < 2; ++k) dst[m][k] = *LDSP(const bf16x8, lds + SA(b, h) + aoff + m * 2048 + k * 1024); } while (0)
; #define LDB(dst, b, h) do { _Pragma("unroll") for (int n = 0; n < 2; ++n) _Pragma("unroll") for (int k = 0; k < 2; ++k) dst[n][k] = *LDSP(const bf16x8, lds + SB(b, h) + boff + n * 2048 + k * 1024); } while (0)
; #define MMA(ai, bj, AT, BT) do { __builtin_amdgcn_s_setprio(1); \
;     _Pragma("unroll") for (int m = 0; m < 4; ++m) _Pragma("unroll") for (int n = 0; n < 2; ++n) _Pragma("unroll") for (int k = 0; k < 2; ++k) \
;       acc[ai][bj][m][n] = __builtin_amdgcn_mfma_f32_16x16x32_bf16(BT[n][k], AT[m][k], acc[ai][bj][m][n], 0, 0, 0); \
;     __builtin_amdgcn_s_setprio(0); } while (0)
; #define WAIT_V(n) asm volatile("s_waitcnt vmcnt(" #n ")" ::: "memory")
; #define WAIT_L(n) asm volatile("s_waitcnt lgkmcnt(" #n ")" ::: "memory")
; #define BAR __builtin_amdgcn_s_barrier()
; #define SCHED __builtin_amdgcn_sched_barrier(0)
; #define WAIT_V(n) asm volatile("s_waitcnt vmcnt(" #n ")" ::: "memory")
; #define BAR do { __builtin_amdgcn_sched_barrier(0); __builtin_amdgcn_s_barrier(); asm volatile("" ::: "memory"); __builtin_amdgcn_sched_barrier(0); } while (0)
; template <bool SP2, bool ALIGN_EPI, bool DUAL, class Epi> DI void gemm_phase2(const bf16_t* A, const bf16_t* Bt, const bf16_t* A2, const bf16_t* Bt2, int M, int N, int K, const Epi& E, lds_t* lds) {
;     ...
;     for (int t = 0; t < nt; t += 2) {
;       const bool last = (t == nt - 2);
;       const char* a1 = cA + (size_t)(t + 1) * kstep;
;       const char* a2 = last ? nA : cA + (size_t)(t + 2) * kstep; const char* b2 = last ? nB : cB + (size_t)(t + 2) * kstep;
;       const char* a3 = a2 + kstep; const char* b3 = b2 + kstep;
;       if constexpr (SP2) {
;         LDB(B0, 0, 0); LDB(B1, 0, 1); SCHED; LDA(At, 0, 0); STAGE(SA(1, 1), a1 + hstep);
;         WAIT_V(8); WAIT_L(0); BAR; MMA(0, 0, At, B0); MMA(0, 1, At, B1); BAR; SCHED;
;         LDA(At, 0, 1); STAGEB(SB(0, 0), b2); STAGEB(SB(0, 1), b2 + bstep); STAGE(SA(0, 0), a2);
;         WAIT_V(8); WAIT_L(0); BAR; MMA(1, 0, At, B0); MMA(1, 1, At, B1); BAR; SCHED;
.LBB0_824:
	ds_read_b128 v[152:155], v149
	ds_read_b128 v[156:159], v149 offset:1024
	ds_read_b128 v[160:163], v149 offset:2048
	ds_read_b128 v[164:167], v149 offset:3072
	ds_read_b128 v[168:171], v150
	ds_read_b128 v[172:175], v150 offset:1024
	ds_read_b128 v[176:179], v150 offset:2048
	ds_read_b128 v[180:183], v150 offset:3072
	s_add_u32 s45, s46, 0xfff00080
	s_addc_u32 s48, s47, -1
	s_cmp_eq_u32 s39, 60
	s_cselect_b32 s51, s0, s48
	s_cselect_b32 s50, s1, s45
	s_cselect_b32 s49, s7, s35
	s_cselect_b32 s48, s27, s34
	v_lshl_add_u64 v[140:141], s[46:47], 0, v[136:137]
	s_add_i32 m0, s3, 0xc000
	ds_read_b128 v[184:187], v151
	ds_read_b128 v[188:191], v151 offset:1024
	ds_read_b128 v[192:195], v151 offset:2048
	ds_read_b128 v[196:199], v151 offset:3072
	ds_read_b128 v[200:203], v151 offset:4096
	ds_read_b128 v[204:207], v151 offset:5120
	ds_read_b128 v[208:211], v151 offset:6144
	ds_read_b128 v[216:219], v151 offset:7168
	global_load_lds_dwordx4 v[140:141], off
	v_lshl_add_u64 v[140:141], s[46:47], 0, v[138:139]
	s_add_i32 m0, s3, 0xe000
	s_nop 0
	global_load_lds_dwordx4 v[140:141], off
	s_waitcnt vmcnt(8)
	s_waitcnt lgkmcnt(0)
	s_barrier
	s_setprio 0
	s_waitcnt lgkmcnt(0)
	v_mfma_f32_16x16x32_bf16 v[124:127], v[152:155], v[184:187], v[124:127]
	v_mfma_f32_16x16x32_bf16 v[120:123], v[160:163], v[184:187], v[120:123]
	v_mfma_f32_16x16x32_bf16 v[108:111], v[152:155], v[192:195], v[108:111]
	v_mfma_f32_16x16x32_bf16 v[104:107], v[160:163], v[192:195], v[104:107]
	v_mfma_f32_16x16x32_bf16 v[92:95], v[152:155], v[200:203], v[92:95]
	v_mfma_f32_16x16x32_bf16 v[88:91], v[160:163], v[200:203], v[88:91]
	v_mfma_f32_16x16x32_bf16 v[76:79], v[152:155], v[208:211], v[76:79]
	v_mfma_f32_16x16x32_bf16 v[72:75], v[160:163], v[208:211], v[72:75]
	v_mfma_f32_16x16x32_bf16 v[124:127], v[156:159], v[188:191], v[124:127]
	v_mfma_f32_16x16x32_bf16 v[120:123], v[164:167], v[188:191], v[120:123]
	v_mfma_f32_16x16x32_bf16 v[108:111], v[156:159], v[196:199], v[108:111]
	v_mfma_f32_16x16x32_bf16 v[104:107], v[164:167], v[196:199], v[104:107]
	v_mfma_f32_16x16x32_bf16 v[92:95], v[156:159], v[204:207], v[92:95]
	v_mfma_f32_16x16x32_bf16 v[88:91], v[164:167], v[204:207], v[88:91]
	v_mfma_f32_16x16x32_bf16 v[76:79], v[156:159], v[216:219], v[76:79]
	v_mfma_f32_16x16x32_bf16 v[72:75], v[164:167], v[216:219], v[72:75]
	s_setprio 1
	s_setprio 0
	v_mfma_f32_16x16x32_bf16 v[116:119], v[168:171], v[184:187], v[116:119]
	v_mfma_f32_16x16x32_bf16 v[112:115], v[176:179], v[184:187], v[112:115]
	v_mfma_f32_16x16x32_bf16 v[100:103], v[168:171], v[192:195], v[100:103]
	v_mfma_f32_16x16x32_bf16 v[96:99], v[176:179], v[192:195], v[96:99]
	v_mfma_f32_16x16x32_bf16 v[84:87], v[168:171], v[200:203], v[84:87]
	v_mfma_f32_16x16x32_bf16 v[80:83], v[176:179], v[200:203], v[80:83]
	v_mfma_f32_16x16x32_bf16 v[68:71], v[168:171], v[208:211], v[68:71]
	v_mfma_f32_16x16x32_bf16 v[64:67], v[176:179], v[208:211], v[64:67]
	v_mfma_f32_16x16x32_bf16 v[116:119], v[172:175], v[188:191], v[116:119]
	v_mfma_f32_16x16x32_bf16 v[112:115], v[180:183], v[188:191], v[112:115]
	v_mfma_f32_16x16x32_bf16 v[100:103], v[172:175], v[196:199], v[100:103]
	v_mfma_f32_16x16x32_bf16 v[96:99], v[180:183], v[196:199], v[96:99]
	v_mfma_f32_16x16x32_bf16 v[84:87], v[172:175], v[204:207], v[84:87]
	v_mfma_f32_16x16x32_bf16 v[80:83], v[180:183], v[204:207], v[80:83]
	v_mfma_f32_16x16x32_bf16 v[68:71], v[172:175], v[216:219], v[68:71]
	v_mfma_f32_16x16x32_bf16 v[64:67], v[180:183], v[216:219], v[64:67]
	s_setprio 1
	s_barrier
	s_add_i32 s45, s18, s2
	v_lshl_add_u64 v[140:141], s[48:49], 0, v[130:131]
	s_mov_b32 m0, s45
	ds_read_b128 v[184:187], v151 offset:16384
	ds_read_b128 v[188:191], v151 offset:17408
	ds_read_b128 v[192:195], v151 offset:18432
	ds_read_b128 v[196:199], v151 offset:19456
	ds_read_b128 v[200:203], v151 offset:20480
	ds_read_b128 v[204:207], v151 offset:21504
	ds_read_b128 v[208:211], v151 offset:22528
	ds_read_b128 v[216:219], v151 offset:23552
	global_load_lds_dwordx4 v[140:141], off
	s_add_i32 m0, s45, 0x2000
	s_add_u32 s52, s48, 0x40000
	v_lshl_add_u64 v[220:221], s[48:49], 0, v[134:135]
	s_addc_u32 s53, s49, 0
	s_add_i32 s45, s19, s2
	global_load_lds_dwordx4 v[220:221], off
	v_lshl_add_u64 v[222:223], s[52:53], 0, v[130:131]
	s_mov_b32 m0, s45
	v_lshl_add_u64 v[224:225], s[50:51], 0, v[132:133]
	global_load_lds_dwordx4 v[222:223], off
	v_lshl_add_u64 v[222:223], s[52:53], 0, v[134:135]
	s_add_i32 m0, s45, 0x2000
	s_nop 0
	global_load_lds_dwordx4 v[222:223], off
	v_lshl_add_u64 v[222:223], s[50:51], 0, v[128:129]
	s_mov_b32 m0, s3
	s_nop 0
	global_load_lds_dwordx4 v[222:223], off
	s_mov_b32 m0, s8
	s_nop 0
	global_load_lds_dwordx4 v[224:225], off
	s_waitcnt vmcnt(8)
	s_waitcnt lgkmcnt(0)
	s_barrier
; #define STAGE(bufoff, gbase) STAGE_(bufoff, gbase, voffA)
; #define LDA(dst, b, h) do { _Pragma("unroll") for (int m = 0; m < 4; ++m) _Pragma("unroll") for (int k = 0; k < 2; ++k) dst[m][k] = *LDSP(const bf16x8, lds + SA(b, h) + aoff + m * 2048 + k * 1024); } while (0)
; #define LDB(dst, b, h) do { _Pragma("unroll") for (int n = 0; n < 2; ++n) _Pragma("unroll") for (int k = 0; k < 2; ++k) dst[n][k] = *LDSP(const bf16x8, lds + SB(b, h) + boff + n * 2048 + k * 1024); } while (0)
; #define MMA(ai, bj, AT, BT) do { __builtin_amdgcn_s_setprio(1); \
;     _Pragma("unroll") for (int m = 0; m < 4; ++m) _Pragma("unroll") for (int n = 0; n < 2; ++n) _Pragma("unroll") for (int k = 0; k < 2; ++k) \
;       acc[ai][bj][m][n] = __builtin_amdgcn_mfma_f32_16x16x32_bf16(BT[n][k], AT[m][k], acc[ai][bj][m][n], 0, 0, 0); \
;     __builtin_amdgcn_s_setprio(0); } while (0)
; #define WAIT_V(n) asm volatile("s_waitcnt vmcnt(" #n ")" ::: "memory")
; #define WAIT_L(n) asm volatile("s_waitcnt lgkmcnt(" #n ")" ::: "memory")
; #define BAR __builtin_amdgcn_s_barrier()
; #define SCHED __builtin_amdgcn_sched_barrier(0)
; #define WAIT_V(n) asm volatile("s_waitcnt vmcnt(" #n ")" ::: "memory")
; #define BAR do { __builtin_amdgcn_sched_barrier(0); __builtin_amdgcn_s_barrier(); asm volatile("" ::: "memory"); __builtin_amdgcn_sched_barrier(0); } while (0)
; template <bool SP2, bool ALIGN_EPI, bool DUAL, class Epi> DI void gemm_phase2(const bf16_t* A, const bf16_t* Bt, const bf16_t* A2, const bf16_t* Bt2, int M, int N, int K, const Epi& E, lds_t* lds) {
;     ...
;         WAIT_V(8); WAIT_L(0); BAR; MMA(1, 0, At, B0); MMA(1, 1, At, B1); BAR; SCHED;
;         LDB(B0, 1, 0); LDB(B1, 1, 1); SCHED; LDA(At, 1, 0); STAGE(SA(0, 1), a2 + hstep);
;         WAIT_V(8); WAIT_L(0); BAR; MMA(0, 0, At, B0); MMA(0, 1, At, B1); BAR; SCHED;
	s_setprio 0
	s_waitcnt lgkmcnt(0)
	v_mfma_f32_16x16x32_bf16 v[60:63], v[152:155], v[184:187], v[60:63]
	v_mfma_f32_16x16x32_bf16 v[56:59], v[160:163], v[184:187], v[56:59]
	v_mfma_f32_16x16x32_bf16 v[44:47], v[152:155], v[192:195], v[44:47]
	v_mfma_f32_16x16x32_bf16 v[40:43], v[160:163], v[192:195], v[40:43]
	v_mfma_f32_16x16x32_bf16 v[28:31], v[152:155], v[200:203], v[28:31]
	v_mfma_f32_16x16x32_bf16 v[24:27], v[160:163], v[200:203], v[24:27]
	v_mfma_f32_16x16x32_bf16 v[12:15], v[152:155], v[208:211], v[12:15]
	v_mfma_f32_16x16x32_bf16 v[8:11], v[160:163], v[208:211], v[8:11]
	v_mfma_f32_16x16x32_bf16 v[60:63], v[156:159], v[188:191], v[60:63]
	v_mfma_f32_16x16x32_bf16 v[56:59], v[164:167], v[188:191], v[56:59]
	v_mfma_f32_16x16x32_bf16 v[44:47], v[156:159], v[196:199], v[44:47]
	v_mfma_f32_16x16x32_bf16 v[40:43], v[164:167], v[196:199], v[40:43]
	v_mfma_f32_16x16x32_bf16 v[28:31], v[156:159], v[204:207], v[28:31]
	v_mfma_f32_16x16x32_bf16 v[24:27], v[164:167], v[204:207], v[24:27]
	v_mfma_f32_16x16x32_bf16 v[12:15], v[156:159], v[216:219], v[12:15]
	v_mfma_f32_16x16x32_bf16 v[8:11], v[164:167], v[216:219], v[8:11]
	s_setprio 1
	s_setprio 0
	v_mfma_f32_16x16x32_bf16 v[52:55], v[168:171], v[184:187], v[52:55]
	v_mfma_f32_16x16x32_bf16 v[48:51], v[176:179], v[184:187], v[48:51]
	v_mfma_f32_16x16x32_bf16 v[36:39], v[168:171], v[192:195], v[36:39]
	v_mfma_f32_16x16x32_bf16 v[32:35], v[176:179], v[192:195], v[32:35]
	v_mfma_f32_16x16x32_bf16 v[20:23], v[168:171], v[200:203], v[20:23]
	v_mfma_f32_16x16x32_bf16 v[16:19], v[176:179], v[200:203], v[16:19]
	v_mfma_f32_16x16x32_bf16 v[4:7], v[168:171], v[208:211], v[4:7]
	v_mfma_f32_16x16x32_bf16 v[0:3], v[176:179], v[208:211], v[0:3]
	v_mfma_f32_16x16x32_bf16 v[52:55], v[172:175], v[188:191], v[52:55]
	v_mfma_f32_16x16x32_bf16 v[48:51], v[180:183], v[188:191], v[48:51]
	v_mfma_f32_16x16x32_bf16 v[36:39], v[172:175], v[196:199], v[36:39]
	v_mfma_f32_16x16x32_bf16 v[32:35], v[180:183], v[196:199], v[32:35]
	v_mfma_f32_16x16x32_bf16 v[20:23], v[172:175], v[204:207], v[20:23]
	v_mfma_f32_16x16x32_bf16 v[16:19], v[180:183], v[204:207], v[16:19]
	v_mfma_f32_16x16x32_bf16 v[4:7], v[172:175], v[216:219], v[4:7]
	v_mfma_f32_16x16x32_bf16 v[0:3], v[180:183], v[216:219], v[0:3]
	s_setprio 1
	s_barrier
	s_add_i32 s45, 0, 0x18000
	s_add_i32 s52, 0, 0x1c000
	v_add_u32_e32 v164, s45, v143
	v_add_u32_e32 v180, s52, v143
	ds_read_b128 v[152:155], v164
	ds_read_b128 v[156:159], v164 offset:1024
	ds_read_b128 v[160:163], v164 offset:2048
	ds_read_b128 v[164:167], v164 offset:3072
	ds_read_b128 v[168:171], v180
	ds_read_b128 v[172:175], v180 offset:1024
	ds_read_b128 v[176:179], v180 offset:2048
	ds_read_b128 v[180:183], v180 offset:3072
	s_add_u32 s50, s50, 0x100000
	s_addc_u32 s51, s51, 0
	s_mov_b32 m0, s9
	v_lshl_add_u64 v[226:227], s[50:51], 0, v[128:129]
	ds_read_b128 v[184:187], v151 offset:32768
	ds_read_b128 v[188:191], v151 offset:33792
	ds_read_b128 v[192:195], v151 offset:34816
	ds_read_b128 v[196:199], v151 offset:35840
	ds_read_b128 v[200:203], v151 offset:36864
	ds_read_b128 v[204:207], v151 offset:37888
	ds_read_b128 v[208:211], v151 offset:38912
	ds_read_b128 v[216:219], v151 offset:39936
	global_load_lds_dwordx4 v[226:227], off
	v_lshl_add_u64 v[226:227], s[50:51], 0, v[132:133]
	s_mov_b32 m0, s10
	s_nop 0
	global_load_lds_dwordx4 v[226:227], off
	s_waitcnt vmcnt(8)
	s_waitcnt lgkmcnt(0)
	s_barrier
	s_setprio 0
	s_waitcnt lgkmcnt(0)
	v_mfma_f32_16x16x32_bf16 v[124:127], v[152:155], v[184:187], v[124:127]
	v_mfma_f32_16x16x32_bf16 v[120:123], v[160:163], v[184:187], v[120:123]
	v_mfma_f32_16x16x32_bf16 v[108:111], v[152:155], v[192:195], v[108:111]
	v_mfma_f32_16x16x32_bf16 v[104:107], v[160:163], v[192:195], v[104:107]
	v_mfma_f32_16x16x32_bf16 v[92:95], v[152:155], v[200:203], v[92:95]
	v_mfma_f32_16x16x32_bf16 v[88:91], v[160:163], v[200:203], v[88:91]
	v_mfma_f32_16x16x32_bf16 v[76:79], v[152:155], v[208:211], v[76:79]
	v_mfma_f32_16x16x32_bf16 v[72:75], v[160:163], v[208:211], v[72:75]
	v_mfma_f32_16x16x32_bf16 v[124:127], v[156:159], v[188:191], v[124:127]
	v_mfma_f32_16x16x32_bf16 v[120:123], v[164:167], v[188:191], v[120:123]
	v_mfma_f32_16x16x32_bf16 v[108:111], v[156:159], v[196:199], v[108:111]
	v_mfma_f32_16x16x32_bf16 v[104:107], v[164:167], v[196:199], v[104:107]
	v_mfma_f32_16x16x32_bf16 v[92:95], v[156:159], v[204:207], v[92:95]
	v_mfma_f32_16x16x32_bf16 v[88:91], v[164:167], v[204:207], v[88:91]
	v_mfma_f32_16x16x32_bf16 v[76:79], v[156:159], v[216:219], v[76:79]
	v_mfma_f32_16x16x32_bf16 v[72:75], v[164:167], v[216:219], v[72:75]
	s_setprio 1
	s_setprio 0
	v_mfma_f32_16x16x32_bf16 v[116:119], v[168:171], v[184:187], v[116:119]
	v_mfma_f32_16x16x32_bf16 v[112:115], v[176:179], v[184:187], v[112:115]
	v_mfma_f32_16x16x32_bf16 v[100:103], v[168:171], v[192:195], v[100:103]
	v_mfma_f32_16x16x32_bf16 v[96:99], v[176:179], v[192:195], v[96:99]
	v_mfma_f32_16x16x32_bf16 v[84:87], v[168:171], v[200:203], v[84:87]
	v_mfma_f32_16x16x32_bf16 v[80:83], v[176:179], v[200:203], v[80:83]
	v_mfma_f32_16x16x32_bf16 v[68:71], v[168:171], v[208:211], v[68:71]
	v_mfma_f32_16x16x32_bf16 v[64:67], v[176:179], v[208:211], v[64:67]
	v_mfma_f32_16x16x32_bf16 v[116:119], v[172:175], v[188:191], v[116:119]
	v_mfma_f32_16x16x32_bf16 v[112:115], v[180:183], v[188:191], v[112:115]
	v_mfma_f32_16x16x32_bf16 v[100:103], v[172:175], v[196:199], v[100:103]
	v_mfma_f32_16x16x32_bf16 v[96:99], v[180:183], v[196:199], v[96:99]
	v_mfma_f32_16x16x32_bf16 v[84:87], v[172:175], v[204:207], v[84:87]
	v_mfma_f32_16x16x32_bf16 v[80:83], v[180:183], v[204:207], v[80:83]
	v_mfma_f32_16x16x32_bf16 v[68:71], v[172:175], v[216:219], v[68:71]
	v_mfma_f32_16x16x32_bf16 v[64:67], v[180:183], v[216:219], v[64:67]
	s_setprio 1
	s_barrier
; #define STAGE(bufoff, gbase) STAGE_(bufoff, gbase, voffA)
; #define STAGEB(bufoff, gbase) STAGE_(bufoff, gbase, voffB)
; #define LDA(dst, b, h) do { _Pragma("unroll") for (int m = 0; m < 4; ++m) _Pragma("unroll") for (int k = 0; k < 2; ++k) dst[m][k] = *LDSP(const bf16x8, lds + SA(b, h) + aoff + m * 2048 + k * 1024); } while (0)
; #define MMA(ai, bj, AT, BT) do { __builtin_amdgcn_s_setprio(1); \
;     _Pragma("unroll") for (int m = 0; m < 4; ++m) _Pragma("unroll") for (int n = 0; n < 2; ++n) _Pragma("unroll") for (int k = 0; k < 2; ++k) \
;       acc[ai][bj][m][n] = __builtin_amdgcn_mfma_f32_16x16x32_bf16(BT[n][k], AT[m][k], acc[ai][bj][m][n], 0, 0, 0); \
;     __builtin_amdgcn_s_setprio(0); } while (0)
; #define WAIT_V(n) asm volatile("s_waitcnt vmcnt(" #n ")" ::: "memory")
; #define WAIT_L(n) asm volatile("s_waitcnt lgkmcnt(" #n ")" ::: "memory")
; #define BAR __builtin_amdgcn_s_barrier()
; #define SCHED __builtin_amdgcn_sched_barrier(0)
; #define WAIT_V(n) asm volatile("s_waitcnt vmcnt(" #n ")" ::: "memory")
; #define BAR do { __builtin_amdgcn_sched_barrier(0); __builtin_amdgcn_s_barrier(); asm volatile("" ::: "memory"); __builtin_amdgcn_sched_barrier(0); } while (0)
; template <bool SP2, bool ALIGN_EPI, bool DUAL, class Epi> DI void gemm_phase2(const bf16_t* A, const bf16_t* Bt, const bf16_t* A2, const bf16_t* Bt2, int M, int N, int K, const Epi& E, lds_t* lds) {
;     ...
;     for (int t = 0; t < nt; t += 2) {
;       const bool last = (t == nt - 2);
;       const char* a1 = cA + (size_t)(t + 1) * kstep;
;       const char* a2 = last ? nA : cA + (size_t)(t + 2) * kstep; const char* b2 = last ? nB : cB + (size_t)(t + 2) * kstep;
;       const char* a3 = a2 + kstep; const char* b3 = b2 + kstep;
;     ...
;         LDA(At, 1, 1); STAGEB(SB(1, 0), b3); STAGEB(SB(1, 1), b3 + bstep); STAGE(SA(1, 0), a3);
;         WAIT_V(8); WAIT_L(0); BAR; MMA(1, 0, At, B0); MMA(1, 1, At, B1); BAR; SCHED;
	s_add_i32 s45, s45, s2
	v_lshl_add_u64 v[140:141], v[140:141], 0, s[22:23]
	s_mov_b32 m0, s45
	ds_read_b128 v[184:187], v151 offset:49152
	ds_read_b128 v[188:191], v151 offset:50176
	ds_read_b128 v[192:195], v151 offset:51200
	ds_read_b128 v[196:199], v151 offset:52224
	ds_read_b128 v[200:203], v151 offset:53248
	ds_read_b128 v[204:207], v151 offset:54272
	ds_read_b128 v[208:211], v151 offset:55296
	ds_read_b128 v[216:219], v151 offset:56320
	global_load_lds_dwordx4 v[140:141], off
	s_add_i32 m0, s45, 0x2000
	s_add_u32 s48, s48, 0x40080
	v_lshl_add_u64 v[140:141], v[220:221], 0, s[22:23]
	s_addc_u32 s49, s49, 0
	s_add_i32 s45, s52, s2
	global_load_lds_dwordx4 v[140:141], off
	v_lshl_add_u64 v[140:141], s[48:49], 0, v[130:131]
	s_mov_b32 m0, s45
	s_nop 0
	global_load_lds_dwordx4 v[140:141], off
	v_lshl_add_u64 v[140:141], s[48:49], 0, v[134:135]
	s_add_i32 m0, s45, 0x2000
	s_nop 0
	global_load_lds_dwordx4 v[140:141], off
	v_lshl_add_u64 v[140:141], v[222:223], 0, s[22:23]
	s_mov_b32 m0, s14
	s_nop 0
	global_load_lds_dwordx4 v[140:141], off
	v_lshl_add_u64 v[140:141], v[224:225], 0, s[22:23]
	s_mov_b32 m0, s15
	s_nop 0
	global_load_lds_dwordx4 v[140:141], off
	s_waitcnt vmcnt(8)
	s_waitcnt lgkmcnt(0)
	s_barrier
	s_setprio 0
	s_waitcnt lgkmcnt(0)
	v_mfma_f32_16x16x32_bf16 v[60:63], v[152:155], v[184:187], v[60:63]
	v_mfma_f32_16x16x32_bf16 v[56:59], v[160:163], v[184:187], v[56:59]
	v_mfma_f32_16x16x32_bf16 v[44:47], v[152:155], v[192:195], v[44:47]
	v_mfma_f32_16x16x32_bf16 v[40:43], v[160:163], v[192:195], v[40:43]
	v_mfma_f32_16x16x32_bf16 v[28:31], v[152:155], v[200:203], v[28:31]
	v_mfma_f32_16x16x32_bf16 v[24:27], v[160:163], v[200:203], v[24:27]
	v_mfma_f32_16x16x32_bf16 v[12:15], v[152:155], v[208:211], v[12:15]
	v_mfma_f32_16x16x32_bf16 v[8:11], v[160:163], v[208:211], v[8:11]
	v_mfma_f32_16x16x32_bf16 v[60:63], v[156:159], v[188:191], v[60:63]
	v_mfma_f32_16x16x32_bf16 v[56:59], v[164:167], v[188:191], v[56:59]
	v_mfma_f32_16x16x32_bf16 v[44:47], v[156:159], v[196:199], v[44:47]
	v_mfma_f32_16x16x32_bf16 v[40:43], v[164:167], v[196:199], v[40:43]
	v_mfma_f32_16x16x32_bf16 v[28:31], v[156:159], v[204:207], v[28:31]
	v_mfma_f32_16x16x32_bf16 v[24:27], v[164:167], v[204:207], v[24:27]
	v_mfma_f32_16x16x32_bf16 v[12:15], v[156:159], v[216:219], v[12:15]
	v_mfma_f32_16x16x32_bf16 v[8:11], v[164:167], v[216:219], v[8:11]
	s_setprio 1
	s_setprio 0
	v_mfma_f32_16x16x32_bf16 v[52:55], v[168:171], v[184:187], v[52:55]
	v_mfma_f32_16x16x32_bf16 v[48:51], v[176:179], v[184:187], v[48:51]
	v_mfma_f32_16x16x32_bf16 v[36:39], v[168:171], v[192:195], v[36:39]
	v_mfma_f32_16x16x32_bf16 v[32:35], v[176:179], v[192:195], v[32:35]
	v_mfma_f32_16x16x32_bf16 v[20:23], v[168:171], v[200:203], v[20:23]
	v_mfma_f32_16x16x32_bf16 v[16:19], v[176:179], v[200:203], v[16:19]
	v_mfma_f32_16x16x32_bf16 v[4:7], v[168:171], v[208:211], v[4:7]
	v_mfma_f32_16x16x32_bf16 v[0:3], v[176:179], v[208:211], v[0:3]
	v_mfma_f32_16x16x32_bf16 v[52:55], v[172:175], v[188:191], v[52:55]
	v_mfma_f32_16x16x32_bf16 v[48:51], v[180:183], v[188:191], v[48:51]
	v_mfma_f32_16x16x32_bf16 v[36:39], v[172:175], v[196:199], v[36:39]
	v_mfma_f32_16x16x32_bf16 v[32:35], v[180:183], v[196:199], v[32:35]
	v_mfma_f32_16x16x32_bf16 v[20:23], v[172:175], v[204:207], v[20:23]
	v_mfma_f32_16x16x32_bf16 v[16:19], v[180:183], v[204:207], v[16:19]
	v_mfma_f32_16x16x32_bf16 v[4:7], v[172:175], v[216:219], v[4:7]
	v_mfma_f32_16x16x32_bf16 v[0:3], v[180:183], v[216:219], v[0:3]
	s_setprio 1
	s_barrier
	s_add_i32 s39, s39, 2
	s_add_u32 s46, s46, 0x100
	s_addc_u32 s47, s47, 0
	s_add_u32 s34, s34, 0x100
	s_addc_u32 s35, s35, 0
	s_cmp_gt_u32 s39, 61
	s_cbranch_scc0 .LBB0_824
	s_and_b64 vcc, exec, s[28:29]
	s_cbranch_vccz .LBB0_827
	s_barrier

; #define STAGE(bufoff, gbase) STAGE_(bufoff, gbase, voffA)
; #define STAGEB(bufoff, gbase) STAGE_(bufoff, gbase, voffB)
; #define LDA(dst, b, h) do { _Pragma("unroll") for (int m = 0; m < 4; ++m) _Pragma("unroll") for (int k = 0; k < 2; ++k) dst[m][k] = *LDSP(const bf16x8, lds + SA(b, h) + aoff + m * 2048 + k * 1024); } while (0)
; #define LDB(dst, b, h) do { _Pragma("unroll") for (int n = 0; n < 2; ++n) _Pragma("unroll") for (int k = 0; k < 2; ++k) dst[n][k] = *LDSP(const bf16x8, lds + SB(b, h) + boff + n * 2048 + k * 1024); } while (0)
; #define MMA(ai, bj, AT, BT) do { __builtin_amdgcn_s_setprio(1); \
;     _Pragma("unroll") for (int m = 0; m < 4; ++m) _Pragma("unroll") for (int n = 0; n < 2; ++n) _Pragma("unroll") for (int k = 0; k < 2; ++k) \
;       acc[ai][bj][m][n] = __builtin_amdgcn_mfma_f32_16x16x32_bf16(BT[n][k], AT[m][k], acc[ai][bj][m][n], 0, 0, 0); \
;     __builtin_amdgcn_s_setprio(0); } while (0)
; #define WAIT_V(n) asm volatile("s_waitcnt vmcnt(" #n ")" ::: "memory")
; #define WAIT_L(n) asm volatile("s_waitcnt lgkmcnt(" #n ")" ::: "memory")
; #define BAR __builtin_amdgcn_s_barrier()
; #define SCHED __builtin_amdgcn_sched_barrier(0)
; #define WAIT_V(n) asm volatile("s_waitcnt vmcnt(" #n ")" ::: "memory")
; #define BAR do { __builtin_amdgcn_sched_barrier(0); __builtin_amdgcn_s_barrier(); asm volatile("" ::: "memory"); __builtin_amdgcn_sched_barrier(0); } while (0)
; template <bool SP2, bool ALIGN_EPI, bool DUAL, class Epi> DI void gemm_phase2(const bf16_t* A, const bf16_t* Bt, const bf16_t* A2, const bf16_t* Bt2, int M, int N, int K, const Epi& E, lds_t* lds) {
;     ...
;     for (int t = 0; t < nt; t += 2) {
;       const bool last = (t == nt - 2);
;       const char* a1 = cA + (size_t)(t + 1) * kstep;
;       const char* a2 = last ? nA : cA + (size_t)(t + 2) * kstep; const char* b2 = last ? nB : cB + (size_t)(t + 2) * kstep;
;       const char* a3 = a2 + kstep; const char* b3 = b2 + kstep;
;       if constexpr (SP2) {
;         LDB(B0, 0, 0); LDB(B1, 0, 1); SCHED; LDA(At, 0, 0); STAGE(SA(1, 1), a1 + hstep);
;         WAIT_V(8); WAIT_L(0); BAR; MMA(0, 0, At, B0); MMA(0, 1, At, B1); BAR; SCHED;
;         LDA(At, 0, 1); STAGEB(SB(0, 0), b2); STAGEB(SB(0, 1), b2 + bstep); STAGE(SA(0, 0), a2);
;         WAIT_V(8); WAIT_L(0); BAR; MMA(1, 0, At, B0); MMA(1, 1, At, B1); BAR; SCHED;
.LBB0_900:
	ds_read_b128 v[140:143], v160
	ds_read_b128 v[144:147], v160 offset:1024
	ds_read_b128 v[148:151], v160 offset:2048
	ds_read_b128 v[152:155], v160 offset:3072
	ds_read_b128 v[164:167], v161
	ds_read_b128 v[168:171], v161 offset:1024
	ds_read_b128 v[172:175], v161 offset:2048
	ds_read_b128 v[176:179], v161 offset:3072
	s_add_u32 s27, s42, 0xfff00080
	s_addc_u32 s41, s43, -1
	s_cmp_eq_u32 s21, 60
	s_cselect_b32 s47, s0, s41
	s_cselect_b32 s46, s1, s27
	s_cselect_b32 s45, s2, s15
	s_cselect_b32 s44, s3, s14
	v_lshl_add_u64 v[216:217], s[42:43], 0, v[136:137]
	s_add_i32 m0, s11, 0xc000
	ds_read_b128 v[180:183], v162
	ds_read_b128 v[184:187], v162 offset:1024
	ds_read_b128 v[188:191], v162 offset:2048
	ds_read_b128 v[192:195], v162 offset:3072
	ds_read_b128 v[196:199], v162 offset:4096
	ds_read_b128 v[200:203], v162 offset:5120
	ds_read_b128 v[204:207], v162 offset:6144
	ds_read_b128 v[208:211], v162 offset:7168
	global_load_lds_dwordx4 v[216:217], off
	v_lshl_add_u64 v[216:217], s[42:43], 0, v[138:139]
	s_add_i32 m0, s11, 0xe000
	s_nop 0
	global_load_lds_dwordx4 v[216:217], off
	s_waitcnt vmcnt(8)
	s_waitcnt lgkmcnt(0)
	s_barrier
	s_setprio 0
	s_waitcnt lgkmcnt(0)
	v_mfma_f32_16x16x32_bf16 v[124:127], v[140:143], v[180:183], v[124:127]
	v_mfma_f32_16x16x32_bf16 v[120:123], v[148:151], v[180:183], v[120:123]
	v_mfma_f32_16x16x32_bf16 v[108:111], v[140:143], v[188:191], v[108:111]
	v_mfma_f32_16x16x32_bf16 v[104:107], v[148:151], v[188:191], v[104:107]
	v_mfma_f32_16x16x32_bf16 v[92:95], v[140:143], v[196:199], v[92:95]
	v_mfma_f32_16x16x32_bf16 v[88:91], v[148:151], v[196:199], v[88:91]
	v_mfma_f32_16x16x32_bf16 v[76:79], v[140:143], v[204:207], v[76:79]
	v_mfma_f32_16x16x32_bf16 v[72:75], v[148:151], v[204:207], v[72:75]
	v_mfma_f32_16x16x32_bf16 v[124:127], v[144:147], v[184:187], v[124:127]
	v_mfma_f32_16x16x32_bf16 v[120:123], v[152:155], v[184:187], v[120:123]
	v_mfma_f32_16x16x32_bf16 v[108:111], v[144:147], v[192:195], v[108:111]
	v_mfma_f32_16x16x32_bf16 v[104:107], v[152:155], v[192:195], v[104:107]
	v_mfma_f32_16x16x32_bf16 v[92:95], v[144:147], v[200:203], v[92:95]
	v_mfma_f32_16x16x32_bf16 v[88:91], v[152:155], v[200:203], v[88:91]
	v_mfma_f32_16x16x32_bf16 v[76:79], v[144:147], v[208:211], v[76:79]
	v_mfma_f32_16x16x32_bf16 v[72:75], v[152:155], v[208:211], v[72:75]
	s_setprio 1
	s_setprio 0
	v_mfma_f32_16x16x32_bf16 v[116:119], v[164:167], v[180:183], v[116:119]
	v_mfma_f32_16x16x32_bf16 v[112:115], v[172:175], v[180:183], v[112:115]
	v_mfma_f32_16x16x32_bf16 v[100:103], v[164:167], v[188:191], v[100:103]
	v_mfma_f32_16x16x32_bf16 v[96:99], v[172:175], v[188:191], v[96:99]
	v_mfma_f32_16x16x32_bf16 v[84:87], v[164:167], v[196:199], v[84:87]
	v_mfma_f32_16x16x32_bf16 v[80:83], v[172:175], v[196:199], v[80:83]
	v_mfma_f32_16x16x32_bf16 v[68:71], v[164:167], v[204:207], v[68:71]
	v_mfma_f32_16x16x32_bf16 v[64:67], v[172:175], v[204:207], v[64:67]
	v_mfma_f32_16x16x32_bf16 v[116:119], v[168:171], v[184:187], v[116:119]
	v_mfma_f32_16x16x32_bf16 v[112:115], v[176:179], v[184:187], v[112:115]
	v_mfma_f32_16x16x32_bf16 v[100:103], v[168:171], v[192:195], v[100:103]
	v_mfma_f32_16x16x32_bf16 v[96:99], v[176:179], v[192:195], v[96:99]
	v_mfma_f32_16x16x32_bf16 v[84:87], v[168:171], v[200:203], v[84:87]
	v_mfma_f32_16x16x32_bf16 v[80:83], v[176:179], v[200:203], v[80:83]
	v_mfma_f32_16x16x32_bf16 v[68:71], v[168:171], v[208:211], v[68:71]
	v_mfma_f32_16x16x32_bf16 v[64:67], v[176:179], v[208:211], v[64:67]
	s_setprio 1
	s_barrier
	s_add_i32 s27, s49, s10
	v_lshl_add_u64 v[216:217], s[44:45], 0, v[130:131]
	s_mov_b32 m0, s27
	ds_read_b128 v[180:183], v162 offset:16384
	ds_read_b128 v[184:187], v162 offset:17408
	ds_read_b128 v[188:191], v162 offset:18432
	ds_read_b128 v[192:195], v162 offset:19456
	ds_read_b128 v[196:199], v162 offset:20480
	ds_read_b128 v[200:203], v162 offset:21504
	ds_read_b128 v[204:207], v162 offset:22528
	ds_read_b128 v[208:211], v162 offset:23552
	global_load_lds_dwordx4 v[216:217], off
	s_add_i32 m0, s27, 0x2000
	s_add_u32 s54, s44, 0x40000
	v_lshl_add_u64 v[218:219], s[44:45], 0, v[134:135]
	s_addc_u32 s55, s45, 0
	s_add_i32 s27, s50, s10
	global_load_lds_dwordx4 v[218:219], off
	v_lshl_add_u64 v[220:221], s[54:55], 0, v[130:131]
	s_mov_b32 m0, s27
	v_lshl_add_u64 v[222:223], s[46:47], 0, v[132:133]
	global_load_lds_dwordx4 v[220:221], off
	v_lshl_add_u64 v[220:221], s[54:55], 0, v[134:135]
	s_add_i32 m0, s27, 0x2000
	s_nop 0
	global_load_lds_dwordx4 v[220:221], off
	v_lshl_add_u64 v[220:221], s[46:47], 0, v[128:129]
	s_mov_b32 m0, s11
	s_nop 0
	global_load_lds_dwordx4 v[220:221], off
	s_mov_b32 m0, s18
	s_nop 0
	global_load_lds_dwordx4 v[222:223], off
	s_waitcnt vmcnt(8)
	s_waitcnt lgkmcnt(0)
	s_barrier
; #define STAGE(bufoff, gbase) STAGE_(bufoff, gbase, voffA)
; #define LDA(dst, b, h) do { _Pragma("unroll") for (int m = 0; m < 4; ++m) _Pragma("unroll") for (int k = 0; k < 2; ++k) dst[m][k] = *LDSP(const bf16x8, lds + SA(b, h) + aoff + m * 2048 + k * 1024); } while (0)
; #define LDB(dst, b, h) do { _Pragma("unroll") for (int n = 0; n < 2; ++n) _Pragma("unroll") for (int k = 0; k < 2; ++k) dst[n][k] = *LDSP(const bf16x8, lds + SB(b, h) + boff + n * 2048 + k * 1024); } while (0)
; #define MMA(ai, bj, AT, BT) do { __builtin_amdgcn_s_setprio(1); \
;     _Pragma("unroll") for (int m = 0; m < 4; ++m) _Pragma("unroll") for (int n = 0; n < 2; ++n) _Pragma("unroll") for (int k = 0; k < 2; ++k) \
;       acc[ai][bj][m][n] = __builtin_amdgcn_mfma_f32_16x16x32_bf16(BT[n][k], AT[m][k], acc[ai][bj][m][n], 0, 0, 0); \
;     __builtin_amdgcn_s_setprio(0); } while (0)
; #define WAIT_V(n) asm volatile("s_waitcnt vmcnt(" #n ")" ::: "memory")
; #define WAIT_L(n) asm volatile("s_waitcnt lgkmcnt(" #n ")" ::: "memory")
; #define BAR __builtin_amdgcn_s_barrier()
; #define SCHED __builtin_amdgcn_sched_barrier(0)
; #define WAIT_V(n) asm volatile("s_waitcnt vmcnt(" #n ")" ::: "memory")
; #define BAR do { __builtin_amdgcn_sched_barrier(0); __builtin_amdgcn_s_barrier(); asm volatile("" ::: "memory"); __builtin_amdgcn_sched_barrier(0); } while (0)
; template <bool SP2, bool ALIGN_EPI, bool DUAL, class Epi> DI void gemm_phase2(const bf16_t* A, const bf16_t* Bt, const bf16_t* A2, const bf16_t* Bt2, int M, int N, int K, const Epi& E, lds_t* lds) {
;     ...
;         WAIT_V(8); WAIT_L(0); BAR; MMA(1, 0, At, B0); MMA(1, 1, At, B1); BAR; SCHED;
;         LDB(B0, 1, 0); LDB(B1, 1, 1); SCHED; LDA(At, 1, 0); STAGE(SA(0, 1), a2 + hstep);
;         WAIT_V(8); WAIT_L(0); BAR; MMA(0, 0, At, B0); MMA(0, 1, At, B1); BAR; SCHED;
	s_setprio 0
	s_waitcnt lgkmcnt(0)
	v_mfma_f32_16x16x32_bf16 v[60:63], v[140:143], v[180:183], v[60:63]
	v_mfma_f32_16x16x32_bf16 v[56:59], v[148:151], v[180:183], v[56:59]
	v_mfma_f32_16x16x32_bf16 v[44:47], v[140:143], v[188:191], v[44:47]
	v_mfma_f32_16x16x32_bf16 v[40:43], v[148:151], v[188:191], v[40:43]
	v_mfma_f32_16x16x32_bf16 v[28:31], v[140:143], v[196:199], v[28:31]
	v_mfma_f32_16x16x32_bf16 v[24:27], v[148:151], v[196:199], v[24:27]
	v_mfma_f32_16x16x32_bf16 v[12:15], v[140:143], v[204:207], v[12:15]
	v_mfma_f32_16x16x32_bf16 v[8:11], v[148:151], v[204:207], v[8:11]
	v_mfma_f32_16x16x32_bf16 v[60:63], v[144:147], v[184:187], v[60:63]
	v_mfma_f32_16x16x32_bf16 v[56:59], v[152:155], v[184:187], v[56:59]
	v_mfma_f32_16x16x32_bf16 v[44:47], v[144:147], v[192:195], v[44:47]
	v_mfma_f32_16x16x32_bf16 v[40:43], v[152:155], v[192:195], v[40:43]
	v_mfma_f32_16x16x32_bf16 v[28:31], v[144:147], v[200:203], v[28:31]
	v_mfma_f32_16x16x32_bf16 v[24:27], v[152:155], v[200:203], v[24:27]
	v_mfma_f32_16x16x32_bf16 v[12:15], v[144:147], v[208:211], v[12:15]
	v_mfma_f32_16x16x32_bf16 v[8:11], v[152:155], v[208:211], v[8:11]
	s_setprio 1
	s_setprio 0
	v_mfma_f32_16x16x32_bf16 v[52:55], v[164:167], v[180:183], v[52:55]
	v_mfma_f32_16x16x32_bf16 v[48:51], v[172:175], v[180:183], v[48:51]
	v_mfma_f32_16x16x32_bf16 v[36:39], v[164:167], v[188:191], v[36:39]
	v_mfma_f32_16x16x32_bf16 v[32:35], v[172:175], v[188:191], v[32:35]
	v_mfma_f32_16x16x32_bf16 v[20:23], v[164:167], v[196:199], v[20:23]
	v_mfma_f32_16x16x32_bf16 v[16:19], v[172:175], v[196:199], v[16:19]
	v_mfma_f32_16x16x32_bf16 v[4:7], v[164:167], v[204:207], v[4:7]
	v_mfma_f32_16x16x32_bf16 v[0:3], v[172:175], v[204:207], v[0:3]
	v_mfma_f32_16x16x32_bf16 v[52:55], v[168:171], v[184:187], v[52:55]
	v_mfma_f32_16x16x32_bf16 v[48:51], v[176:179], v[184:187], v[48:51]
	v_mfma_f32_16x16x32_bf16 v[36:39], v[168:171], v[192:195], v[36:39]
	v_mfma_f32_16x16x32_bf16 v[32:35], v[176:179], v[192:195], v[32:35]
	v_mfma_f32_16x16x32_bf16 v[20:23], v[168:171], v[200:203], v[20:23]
	v_mfma_f32_16x16x32_bf16 v[16:19], v[176:179], v[200:203], v[16:19]
	v_mfma_f32_16x16x32_bf16 v[4:7], v[168:171], v[208:211], v[4:7]
	v_mfma_f32_16x16x32_bf16 v[0:3], v[176:179], v[208:211], v[0:3]
	s_setprio 1
	s_barrier
	s_add_i32 s27, 0, 0x18000
	s_add_i32 s41, 0, 0x1c000
	v_add_u32_e32 v152, s27, v157
	v_add_u32_e32 v176, s41, v157
	ds_read_b128 v[140:143], v152
	ds_read_b128 v[144:147], v152 offset:1024
	ds_read_b128 v[148:151], v152 offset:2048
	ds_read_b128 v[152:155], v152 offset:3072
	ds_read_b128 v[164:167], v176
	ds_read_b128 v[168:171], v176 offset:1024
	ds_read_b128 v[172:175], v176 offset:2048
	ds_read_b128 v[176:179], v176 offset:3072
	s_add_u32 s46, s46, 0x100000
	s_addc_u32 s47, s47, 0
	s_mov_b32 m0, s19
	v_lshl_add_u64 v[224:225], s[46:47], 0, v[128:129]
	ds_read_b128 v[180:183], v162 offset:32768
	ds_read_b128 v[184:187], v162 offset:33792
	ds_read_b128 v[188:191], v162 offset:34816
	ds_read_b128 v[192:195], v162 offset:35840
	ds_read_b128 v[196:199], v162 offset:36864
	ds_read_b128 v[200:203], v162 offset:37888
	ds_read_b128 v[204:207], v162 offset:38912
	ds_read_b128 v[208:211], v162 offset:39936
	global_load_lds_dwordx4 v[224:225], off
	v_lshl_add_u64 v[224:225], s[46:47], 0, v[132:133]
	s_mov_b32 m0, s33
	s_nop 0
	global_load_lds_dwordx4 v[224:225], off
	s_waitcnt vmcnt(8)
	s_waitcnt lgkmcnt(0)
	s_barrier
	s_setprio 0
	s_waitcnt lgkmcnt(0)
	v_mfma_f32_16x16x32_bf16 v[124:127], v[140:143], v[180:183], v[124:127]
	v_mfma_f32_16x16x32_bf16 v[120:123], v[148:151], v[180:183], v[120:123]
	v_mfma_f32_16x16x32_bf16 v[108:111], v[140:143], v[188:191], v[108:111]
	v_mfma_f32_16x16x32_bf16 v[104:107], v[148:151], v[188:191], v[104:107]
	v_mfma_f32_16x16x32_bf16 v[92:95], v[140:143], v[196:199], v[92:95]
	v_mfma_f32_16x16x32_bf16 v[88:91], v[148:151], v[196:199], v[88:91]
	v_mfma_f32_16x16x32_bf16 v[76:79], v[140:143], v[204:207], v[76:79]
	v_mfma_f32_16x16x32_bf16 v[72:75], v[148:151], v[204:207], v[72:75]
	v_mfma_f32_16x16x32_bf16 v[124:127], v[144:147], v[184:187], v[124:127]
	v_mfma_f32_16x16x32_bf16 v[120:123], v[152:155], v[184:187], v[120:123]
	v_mfma_f32_16x16x32_bf16 v[108:111], v[144:147], v[192:195], v[108:111]
	v_mfma_f32_16x16x32_bf16 v[104:107], v[152:155], v[192:195], v[104:107]
	v_mfma_f32_16x16x32_bf16 v[92:95], v[144:147], v[200:203], v[92:95]
	v_mfma_f32_16x16x32_bf16 v[88:91], v[152:155], v[200:203], v[88:91]
	v_mfma_f32_16x16x32_bf16 v[76:79], v[144:147], v[208:211], v[76:79]
	v_mfma_f32_16x16x32_bf16 v[72:75], v[152:155], v[208:211], v[72:75]
	s_setprio 1
	s_setprio 0
	v_mfma_f32_16x16x32_bf16 v[116:119], v[164:167], v[180:183], v[116:119]
	v_mfma_f32_16x16x32_bf16 v[112:115], v[172:175], v[180:183], v[112:115]
	v_mfma_f32_16x16x32_bf16 v[100:103], v[164:167], v[188:191], v[100:103]
	v_mfma_f32_16x16x32_bf16 v[96:99], v[172:175], v[188:191], v[96:99]
	v_mfma_f32_16x16x32_bf16 v[84:87], v[164:167], v[196:199], v[84:87]
	v_mfma_f32_16x16x32_bf16 v[80:83], v[172:175], v[196:199], v[80:83]
	v_mfma_f32_16x16x32_bf16 v[68:71], v[164:167], v[204:207], v[68:71]
	v_mfma_f32_16x16x32_bf16 v[64:67], v[172:175], v[204:207], v[64:67]
	v_mfma_f32_16x16x32_bf16 v[116:119], v[168:171], v[184:187], v[116:119]
	v_mfma_f32_16x16x32_bf16 v[112:115], v[176:179], v[184:187], v[112:115]
	v_mfma_f32_16x16x32_bf16 v[100:103], v[168:171], v[192:195], v[100:103]
	v_mfma_f32_16x16x32_bf16 v[96:99], v[176:179], v[192:195], v[96:99]
	v_mfma_f32_16x16x32_bf16 v[84:87], v[168:171], v[200:203], v[84:87]
	v_mfma_f32_16x16x32_bf16 v[80:83], v[176:179], v[200:203], v[80:83]
	v_mfma_f32_16x16x32_bf16 v[68:71], v[168:171], v[208:211], v[68:71]
	v_mfma_f32_16x16x32_bf16 v[64:67], v[176:179], v[208:211], v[64:67]
	s_setprio 1
	s_barrier
; #define STAGE(bufoff, gbase) STAGE_(bufoff, gbase, voffA)
; #define STAGEB(bufoff, gbase) STAGE_(bufoff, gbase, voffB)
; #define LDA(dst, b, h) do { _Pragma("unroll") for (int m = 0; m < 4; ++m) _Pragma("unroll") for (int k = 0; k < 2; ++k) dst[m][k] = *LDSP(const bf16x8, lds + SA(b, h) + aoff + m * 2048 + k * 1024); } while (0)
; #define MMA(ai, bj, AT, BT) do { __builtin_amdgcn_s_setprio(1); \
;     _Pragma("unroll") for (int m = 0; m < 4; ++m) _Pragma("unroll") for (int n = 0; n < 2; ++n) _Pragma("unroll") for (int k = 0; k < 2; ++k) \
;       acc[ai][bj][m][n] = __builtin_amdgcn_mfma_f32_16x16x32_bf16(BT[n][k], AT[m][k], acc[ai][bj][m][n], 0, 0, 0); \
;     __builtin_amdgcn_s_setprio(0); } while (0)
; #define WAIT_V(n) asm volatile("s_waitcnt vmcnt(" #n ")" ::: "memory")
; #define WAIT_L(n) asm volatile("s_waitcnt lgkmcnt(" #n ")" ::: "memory")
; #define BAR __builtin_amdgcn_s_barrier()
; #define SCHED __builtin_amdgcn_sched_barrier(0)
; #define WAIT_V(n) asm volatile("s_waitcnt vmcnt(" #n ")" ::: "memory")
; #define BAR do { __builtin_amdgcn_sched_barrier(0); __builtin_amdgcn_s_barrier(); asm volatile("" ::: "memory"); __builtin_amdgcn_sched_barrier(0); } while (0)
; template <bool SP2, bool ALIGN_EPI, bool DUAL, class Epi> DI void gemm_phase2(const bf16_t* A, const bf16_t* Bt, const bf16_t* A2, const bf16_t* Bt2, int M, int N, int K, const Epi& E, lds_t* lds) {
;     ...
;     for (int t = 0; t < nt; t += 2) {
;       const bool last = (t == nt - 2);
;       const char* a1 = cA + (size_t)(t + 1) * kstep;
;       const char* a2 = last ? nA : cA + (size_t)(t + 2) * kstep; const char* b2 = last ? nB : cB + (size_t)(t + 2) * kstep;
;       const char* a3 = a2 + kstep; const char* b3 = b2 + kstep;
;     ...
;         LDA(At, 1, 1); STAGEB(SB(1, 0), b3); STAGEB(SB(1, 1), b3 + bstep); STAGE(SA(1, 0), a3);
;         WAIT_V(8); WAIT_L(0); BAR; MMA(1, 0, At, B0); MMA(1, 1, At, B1); BAR; SCHED;
	s_add_i32 s27, s27, s10
	v_lshl_add_u64 v[216:217], v[216:217], 0, s[8:9]
	s_mov_b32 m0, s27
	ds_read_b128 v[180:183], v162 offset:49152
	ds_read_b128 v[184:187], v162 offset:50176
	ds_read_b128 v[188:191], v162 offset:51200
	ds_read_b128 v[192:195], v162 offset:52224
	ds_read_b128 v[196:199], v162 offset:53248
	ds_read_b128 v[200:203], v162 offset:54272
	ds_read_b128 v[204:207], v162 offset:55296
	ds_read_b128 v[208:211], v162 offset:56320
	global_load_lds_dwordx4 v[216:217], off
	s_add_i32 m0, s27, 0x2000
	s_add_u32 s44, s44, 0x40080
	v_lshl_add_u64 v[216:217], v[218:219], 0, s[8:9]
	s_addc_u32 s45, s45, 0
	s_add_i32 s27, s41, s10
	global_load_lds_dwordx4 v[216:217], off
	v_lshl_add_u64 v[216:217], s[44:45], 0, v[130:131]
	s_mov_b32 m0, s27
	s_nop 0
	global_load_lds_dwordx4 v[216:217], off
	v_lshl_add_u64 v[216:217], s[44:45], 0, v[134:135]
	s_add_i32 m0, s27, 0x2000
	s_nop 0
	global_load_lds_dwordx4 v[216:217], off
	v_lshl_add_u64 v[216:217], v[220:221], 0, s[8:9]
	s_mov_b32 m0, s39
	s_nop 0
	global_load_lds_dwordx4 v[216:217], off
	v_lshl_add_u64 v[216:217], v[222:223], 0, s[8:9]
	s_mov_b32 m0, s48
	s_nop 0
	global_load_lds_dwordx4 v[216:217], off
	s_waitcnt vmcnt(8)
	s_waitcnt lgkmcnt(0)
	s_barrier
	s_setprio 0
	s_waitcnt lgkmcnt(0)
	v_mfma_f32_16x16x32_bf16 v[60:63], v[140:143], v[180:183], v[60:63]
	v_mfma_f32_16x16x32_bf16 v[56:59], v[148:151], v[180:183], v[56:59]
	v_mfma_f32_16x16x32_bf16 v[44:47], v[140:143], v[188:191], v[44:47]
	v_mfma_f32_16x16x32_bf16 v[40:43], v[148:151], v[188:191], v[40:43]
	v_mfma_f32_16x16x32_bf16 v[28:31], v[140:143], v[196:199], v[28:31]
	v_mfma_f32_16x16x32_bf16 v[24:27], v[148:151], v[196:199], v[24:27]
	v_mfma_f32_16x16x32_bf16 v[12:15], v[140:143], v[204:207], v[12:15]
	v_mfma_f32_16x16x32_bf16 v[8:11], v[148:151], v[204:207], v[8:11]
	v_mfma_f32_16x16x32_bf16 v[60:63], v[144:147], v[184:187], v[60:63]
	v_mfma_f32_16x16x32_bf16 v[56:59], v[152:155], v[184:187], v[56:59]
	v_mfma_f32_16x16x32_bf16 v[44:47], v[144:147], v[192:195], v[44:47]
	v_mfma_f32_16x16x32_bf16 v[40:43], v[152:155], v[192:195], v[40:43]
	v_mfma_f32_16x16x32_bf16 v[28:31], v[144:147], v[200:203], v[28:31]
	v_mfma_f32_16x16x32_bf16 v[24:27], v[152:155], v[200:203], v[24:27]
	v_mfma_f32_16x16x32_bf16 v[12:15], v[144:147], v[208:211], v[12:15]
	v_mfma_f32_16x16x32_bf16 v[8:11], v[152:155], v[208:211], v[8:11]
	s_setprio 1
	s_setprio 0
	v_mfma_f32_16x16x32_bf16 v[52:55], v[164:167], v[180:183], v[52:55]
	v_mfma_f32_16x16x32_bf16 v[48:51], v[172:175], v[180:183], v[48:51]
	v_mfma_f32_16x16x32_bf16 v[36:39], v[164:167], v[188:191], v[36:39]
	v_mfma_f32_16x16x32_bf16 v[32:35], v[172:175], v[188:191], v[32:35]
	v_mfma_f32_16x16x32_bf16 v[20:23], v[164:167], v[196:199], v[20:23]
	v_mfma_f32_16x16x32_bf16 v[16:19], v[172:175], v[196:199], v[16:19]
	v_mfma_f32_16x16x32_bf16 v[4:7], v[164:167], v[204:207], v[4:7]
	v_mfma_f32_16x16x32_bf16 v[0:3], v[172:175], v[204:207], v[0:3]
	v_mfma_f32_16x16x32_bf16 v[52:55], v[168:171], v[184:187], v[52:55]
	v_mfma_f32_16x16x32_bf16 v[48:51], v[176:179], v[184:187], v[48:51]
	v_mfma_f32_16x16x32_bf16 v[36:39], v[168:171], v[192:195], v[36:39]
	v_mfma_f32_16x16x32_bf16 v[32:35], v[176:179], v[192:195], v[32:35]
	v_mfma_f32_16x16x32_bf16 v[20:23], v[168:171], v[200:203], v[20:23]
	v_mfma_f32_16x16x32_bf16 v[16:19], v[176:179], v[200:203], v[16:19]
	v_mfma_f32_16x16x32_bf16 v[4:7], v[168:171], v[208:211], v[4:7]
	v_mfma_f32_16x16x32_bf16 v[0:3], v[176:179], v[208:211], v[0:3]
	s_setprio 1
	s_barrier
	s_add_i32 s21, s21, 2
	s_add_u32 s42, s42, 0x100
	s_addc_u32 s43, s43, 0
	s_add_u32 s14, s14, 0x100
	s_addc_u32 s15, s15, 0
	s_cmp_gt_u32 s21, 61
	s_cbranch_scc0 .LBB0_900
	s_and_b64 vcc, exec, s[22:23]
	s_cbranch_vccz .LBB0_903
	s_barrier
